# lever 1: duplicated (already satisfied) lgkmcnt(0) waits in front of the K-loop MFMA blocks removed
# baseline (speedup 1.0000x reference)
; #define PG8_STAGE(bufoff, gbase, voff) do { _Pragma("unroll") for (int _i = 0; _i < 2; ++_i) \
;     __builtin_amdgcn_global_load_lds((const unsigned*)((const char*)(gbase) + (voff)[_i]), (PG8_LAS unsigned*)(lds + (bufoff) + ldsw + _i * 8192), 16, 0, 0); } while (0)
; #define PG8_LDA(dst, b, h) do { _Pragma("unroll") for (int m = 0; m < 4; ++m) _Pragma("unroll") for (int k = 0; k < 2; ++k) dst[m][k] = *(const PG8_LAS bf16x8*)(lds + PG8_SA(b, h) + aoff + m * 2048 + k * 1024); } while (0)
; #define PG8_LDB(dst, b, h) do { _Pragma("unroll") for (int n = 0; n < 2; ++n) _Pragma("unroll") for (int k = 0; k < 2; ++k) dst[n][k] = *(const PG8_LAS bf16x8*)(lds + PG8_SB(b, h) + boff + n * 2048 + k * 1024); } while (0)
; #define PG8_MMA(ai, bj, At, Bt) do { __builtin_amdgcn_s_setprio(1); _Pragma("unroll") for (int m = 0; m < 4; ++m) _Pragma("unroll") for (int n = 0; n < 2; ++n) _Pragma("unroll") for (int k = 0; k < 2; ++k) \
;     acc[ai][bj][m][n] = __builtin_amdgcn_mfma_f32_16x16x32_bf16(Bt[n][k], At[m][k], acc[ai][bj][m][n], 0, 0, 0); __builtin_amdgcn_s_setprio(0); } while (0)
; #define PG8_WAIT_L(n) asm volatile("s_waitcnt lgkmcnt(" #n ")" ::: "memory")
; #define PG8_BAR __builtin_amdgcn_s_barrier()
; #define PG8_SCHED __builtin_amdgcn_sched_barrier(0)
; template <class Epi>
; DI void gemm_phase(PG8_LAS unsigned char* lds, const Gemm g, const StaticOrder& S, const Epi& E) {
;     ...
;     const bool has_next = S.next(ui + 1, nxt);
;     const char* nA = has_next ? (const char*)g.A + (size_t)nxt.pm * tstepA : cA; const char* nB = has_next ? (const char*)g.Bt + (size_t)nxt.pn * tstepB : cB;
;     for (int t = 0; t < nt; t += 2) {
;       const bool last = (t == nt - 2);
;       const char* a1 = cA + (size_t)(t + 1) * kstep;
;       const char* a2 = last ? nA : cA + (size_t)(t + 2) * kstep; const char* b2 = last ? nB : cB + (size_t)(t + 2) * kstep;
;       const char* a3 = a2 + kstep; const char* b3 = b2 + kstep;
;       PG8_LDB(B0, 0, 0); PG8_SCHED; PG8_LDA(At, 0, 0); PG8_STAGE(PG8_SA(1, 1), a1 + hstepA, voffA);
;       PG8_WAIT_L(8); PG8_BAR; PG8_WAIT_L(0); PG8_MMA(0, 0, At, B0); PG8_BAR; PG8_SCHED;
;       PG8_LDB(B1, 0, 1); PG8_STAGE(PG8_SB(0, 0), b2, voffB);
;       PG8_BAR; PG8_WAIT_L(0); PG8_MMA(0, 1, At, B1); PG8_BAR;
;       PG8_LDA(At, 0, 1); PG8_STAGE(PG8_SA(0, 0), a2, voffA);
;       PG8_BAR; PG8_WAIT_L(0); PG8_MMA(1, 0, At, B0); PG8_BAR; PG8_SCHED;
.LBB0_51:
	v_mov_b64_e32 v[2:3], 0x580
	s_ashr_i32 s51, s50, 31
	v_cmp_lt_i64_e32 vcc, s[52:53], v[2:3]
	s_lshl_b64 s[52:53], s[50:51], 19
	s_add_u32 s52, s22, s52
	s_addc_u32 s53, s23, s53
	s_and_b64 s[54:55], vcc, exec
	s_cselect_b32 s51, s53, s57
	s_cselect_b32 s72, s52, s56
	s_ashr_i32 s31, s30, 31
	s_lshl_b64 s[54:55], s[30:31], 19
	v_readlane_b32 s60, v252, 11
	v_readlane_b32 s61, v252, 12
	s_add_u32 s54, s60, s54
	s_addc_u32 s55, s61, s55
	s_and_b64 s[60:61], vcc, exec
	s_cselect_b32 s31, s55, s59
	s_cselect_b32 s73, s54, s58
	s_add_u32 s56, s56, 0x40080
	s_addc_u32 s57, s57, 0
	s_add_u32 s74, s58, 0x100
	v_mov_b32_e32 v2, 0
	s_addc_u32 s75, s59, 0
	s_mov_b32 s76, -2
	s_add_u32 s58, s56, 0xfffc0080
	s_addc_u32 s59, s57, -1
	s_add_i32 s77, 0, 0x10000
	v_add_u32_e32 v153, s77, v149
	ds_read_b128 v[144:147], v153
	ds_read_b128 v[154:157], v153 offset:1024
	ds_read_b128 v[158:161], v153 offset:2048
	ds_read_b128 v[162:165], v153 offset:3072
	s_cmp_eq_u32 s76, 12
	s_cselect_b32 s61, s51, s59
	s_cselect_b32 s60, s72, s58
	s_cselect_b32 s59, s31, s75
	s_cselect_b32 s58, s73, s74
	v_lshl_add_u64 v[198:199], s[56:57], 0, v[132:133]
	s_add_i32 m0, s37, 0xc000
	ds_read_b128 v[166:169], v152
	ds_read_b128 v[170:173], v152 offset:1024
	ds_read_b128 v[174:177], v152 offset:2048
	ds_read_b128 v[178:181], v152 offset:3072
	ds_read_b128 v[182:185], v152 offset:4096
	ds_read_b128 v[186:189], v152 offset:5120
	ds_read_b128 v[190:193], v152 offset:6144
	ds_read_b128 v[194:197], v152 offset:7168
	global_load_lds_dwordx4 v[198:199], off
	v_lshl_add_u64 v[198:199], s[56:57], 0, v[142:143]
	s_add_i32 m0, s37, 0xe000
	s_nop 0
	global_load_lds_dwordx4 v[198:199], off
	s_waitcnt lgkmcnt(8)
	s_barrier
	s_waitcnt lgkmcnt(0)
	v_mfma_f32_16x16x32_bf16 v[126:129], v[144:147], v[166:169], 0
	v_mfma_f32_16x16x32_bf16 v[122:125], v[158:161], v[166:169], 0
	v_mfma_f32_16x16x32_bf16 v[110:113], v[144:147], v[174:177], 0
	v_mfma_f32_16x16x32_bf16 v[106:109], v[158:161], v[174:177], 0
	v_mfma_f32_16x16x32_bf16 v[94:97], v[144:147], v[182:185], 0
	v_mfma_f32_16x16x32_bf16 v[90:93], v[158:161], v[182:185], 0
	v_mfma_f32_16x16x32_bf16 v[78:81], v[144:147], v[190:193], 0
	v_mfma_f32_16x16x32_bf16 v[74:77], v[158:161], v[190:193], 0
	v_mfma_f32_16x16x32_bf16 v[126:129], v[154:157], v[170:173], v[126:129]
	v_mfma_f32_16x16x32_bf16 v[122:125], v[162:165], v[170:173], v[122:125]
	v_mfma_f32_16x16x32_bf16 v[110:113], v[154:157], v[178:181], v[110:113]
	v_mfma_f32_16x16x32_bf16 v[106:109], v[162:165], v[178:181], v[106:109]
	v_mfma_f32_16x16x32_bf16 v[94:97], v[154:157], v[186:189], v[94:97]
	v_mfma_f32_16x16x32_bf16 v[90:93], v[162:165], v[186:189], v[90:93]
	v_mfma_f32_16x16x32_bf16 v[78:81], v[154:157], v[194:197], v[78:81]
	v_mfma_f32_16x16x32_bf16 v[74:77], v[162:165], v[194:197], v[74:77]
	s_barrier
	s_add_i32 s80, 0, 0x14000
	s_add_i32 s77, s77, s34
	v_add_u32_e32 v153, s80, v149
	v_lshl_add_u64 v[198:199], s[58:59], 0, v[0:1]
	s_mov_b32 m0, s77
	ds_read_b128 v[222:225], v153
	ds_read_b128 v[226:229], v153 offset:1024
	ds_read_b128 v[230:233], v153 offset:2048
	ds_read_b128 v[234:237], v153 offset:3072
	global_load_lds_dwordx4 v[198:199], off
	v_lshl_add_u64 v[238:239], s[58:59], 0, v[130:131]
	s_add_i32 m0, s77, 0x2000
	s_nop 0
	global_load_lds_dwordx4 v[238:239], off
	s_barrier
	s_waitcnt lgkmcnt(0)
	v_mfma_f32_16x16x32_bf16 v[118:121], v[222:225], v[166:169], 0
	v_mfma_f32_16x16x32_bf16 v[114:117], v[230:233], v[166:169], 0
	v_mfma_f32_16x16x32_bf16 v[102:105], v[222:225], v[174:177], 0
	v_mfma_f32_16x16x32_bf16 v[98:101], v[230:233], v[174:177], 0
	v_mfma_f32_16x16x32_bf16 v[86:89], v[222:225], v[182:185], 0
	v_mfma_f32_16x16x32_bf16 v[82:85], v[230:233], v[182:185], 0
	v_mfma_f32_16x16x32_bf16 v[70:73], v[222:225], v[190:193], 0
	v_mfma_f32_16x16x32_bf16 v[66:69], v[230:233], v[190:193], 0
	v_mfma_f32_16x16x32_bf16 v[118:121], v[226:229], v[170:173], v[118:121]
	v_mfma_f32_16x16x32_bf16 v[114:117], v[234:237], v[170:173], v[114:117]
	v_mfma_f32_16x16x32_bf16 v[102:105], v[226:229], v[178:181], v[102:105]
	v_mfma_f32_16x16x32_bf16 v[98:101], v[234:237], v[178:181], v[98:101]
	v_mfma_f32_16x16x32_bf16 v[86:89], v[226:229], v[186:189], v[86:89]
	v_mfma_f32_16x16x32_bf16 v[82:85], v[234:237], v[186:189], v[82:85]
	v_mfma_f32_16x16x32_bf16 v[70:73], v[226:229], v[194:197], v[70:73]
	v_mfma_f32_16x16x32_bf16 v[66:69], v[234:237], v[194:197], v[66:69]
	s_mov_b32 m0, s37
	v_lshl_add_u64 v[240:241], s[60:61], 0, v[0:1]
	s_barrier
	ds_read_b128 v[166:169], v152 offset:16384
	ds_read_b128 v[170:173], v152 offset:17408
	ds_read_b128 v[174:177], v152 offset:18432
	ds_read_b128 v[178:181], v152 offset:19456
	ds_read_b128 v[182:185], v152 offset:20480
	ds_read_b128 v[186:189], v152 offset:21504
	ds_read_b128 v[190:193], v152 offset:22528
	ds_read_b128 v[194:197], v152 offset:23552
	global_load_lds_dwordx4 v[240:241], off
	v_lshl_add_u64 v[242:243], s[60:61], 0, v[130:131]
	s_mov_b32 m0, s62
	s_nop 0
	global_load_lds_dwordx4 v[242:243], off
	s_barrier
	s_waitcnt lgkmcnt(0)
	v_mfma_f32_16x16x32_bf16 v[62:65], v[144:147], v[166:169], 0
	v_mfma_f32_16x16x32_bf16 v[58:61], v[158:161], v[166:169], 0
	v_mfma_f32_16x16x32_bf16 v[46:49], v[144:147], v[174:177], 0
	v_mfma_f32_16x16x32_bf16 v[42:45], v[158:161], v[174:177], 0
	v_mfma_f32_16x16x32_bf16 v[30:33], v[144:147], v[182:185], 0
	v_mfma_f32_16x16x32_bf16 v[26:29], v[158:161], v[182:185], 0
	v_mfma_f32_16x16x32_bf16 v[14:17], v[144:147], v[190:193], 0
	v_mfma_f32_16x16x32_bf16 v[10:13], v[158:161], v[190:193], 0
	v_mfma_f32_16x16x32_bf16 v[62:65], v[154:157], v[170:173], v[62:65]
	v_mfma_f32_16x16x32_bf16 v[58:61], v[162:165], v[170:173], v[58:61]
	v_mfma_f32_16x16x32_bf16 v[46:49], v[154:157], v[178:181], v[46:49]
	v_mfma_f32_16x16x32_bf16 v[42:45], v[162:165], v[178:181], v[42:45]
	v_mfma_f32_16x16x32_bf16 v[30:33], v[154:157], v[186:189], v[30:33]
	v_mfma_f32_16x16x32_bf16 v[26:29], v[162:165], v[186:189], v[26:29]
	v_mfma_f32_16x16x32_bf16 v[14:17], v[154:157], v[194:197], v[14:17]
	v_mfma_f32_16x16x32_bf16 v[10:13], v[162:165], v[194:197], v[10:13]
	s_barrier
; #define PG8_STAGE(bufoff, gbase, voff) do { _Pragma("unroll") for (int _i = 0; _i < 2; ++_i) \
;     __builtin_amdgcn_global_load_lds((const unsigned*)((const char*)(gbase) + (voff)[_i]), (PG8_LAS unsigned*)(lds + (bufoff) + ldsw + _i * 8192), 16, 0, 0); } while (0)
; #define PG8_LDA(dst, b, h) do { _Pragma("unroll") for (int m = 0; m < 4; ++m) _Pragma("unroll") for (int k = 0; k < 2; ++k) dst[m][k] = *(const PG8_LAS bf16x8*)(lds + PG8_SA(b, h) + aoff + m * 2048 + k * 1024); } while (0)
; #define PG8_LDB(dst, b, h) do { _Pragma("unroll") for (int n = 0; n < 2; ++n) _Pragma("unroll") for (int k = 0; k < 2; ++k) dst[n][k] = *(const PG8_LAS bf16x8*)(lds + PG8_SB(b, h) + boff + n * 2048 + k * 1024); } while (0)
; #define PG8_MMA(ai, bj, At, Bt) do { __builtin_amdgcn_s_setprio(1); _Pragma("unroll") for (int m = 0; m < 4; ++m) _Pragma("unroll") for (int n = 0; n < 2; ++n) _Pragma("unroll") for (int k = 0; k < 2; ++k) \
;     acc[ai][bj][m][n] = __builtin_amdgcn_mfma_f32_16x16x32_bf16(Bt[n][k], At[m][k], acc[ai][bj][m][n], 0, 0, 0); __builtin_amdgcn_s_setprio(0); } while (0)
; #define PG8_WAIT_V(n) asm volatile("s_waitcnt vmcnt(" #n ")" ::: "memory")
; #define PG8_WAIT_L(n) asm volatile("s_waitcnt lgkmcnt(" #n ")" ::: "memory")
; #define PG8_BAR __builtin_amdgcn_s_barrier()
; #define PG8_SCHED __builtin_amdgcn_sched_barrier(0)
; template <class Epi>
; DI void gemm_phase(PG8_LAS unsigned char* lds, const Gemm g, const StaticOrder& S, const Epi& E) {
;     ...
;       PG8_STAGE(PG8_SB(0, 1), b2 + hstepB, voffB);
;       PG8_WAIT_V(6); PG8_BAR; PG8_MMA(1, 1, At, B1); PG8_BAR;
;       PG8_LDB(B0, 1, 0); PG8_SCHED; PG8_LDA(At, 1, 0); PG8_STAGE(PG8_SA(0, 1), a2 + hstepA, voffA);
;       PG8_WAIT_L(8); PG8_BAR; PG8_WAIT_L(0); PG8_MMA(0, 0, At, B0); PG8_BAR; PG8_SCHED;
;       PG8_LDB(B1, 1, 1); PG8_STAGE(PG8_SB(1, 0), b3, voffB);
;       PG8_BAR; PG8_WAIT_L(0); PG8_MMA(0, 1, At, B1); PG8_BAR;
;       PG8_LDA(At, 1, 1); PG8_STAGE(PG8_SA(1, 0), a3, voffA);
	s_add_u32 s78, s58, 0x40000
	s_addc_u32 s79, s59, 0
	s_add_i32 s77, s80, s34
	v_lshl_add_u64 v[144:145], s[78:79], 0, v[0:1]
	s_mov_b32 m0, s77
	s_nop 0
	global_load_lds_dwordx4 v[144:145], off
	v_lshl_add_u64 v[144:145], s[78:79], 0, v[130:131]
	s_add_i32 m0, s77, 0x2000
	s_nop 0
	global_load_lds_dwordx4 v[144:145], off
	s_waitcnt vmcnt(6)
	s_barrier
	v_mfma_f32_16x16x32_bf16 v[54:57], v[222:225], v[166:169], 0
	v_mfma_f32_16x16x32_bf16 v[50:53], v[230:233], v[166:169], 0
	v_mfma_f32_16x16x32_bf16 v[38:41], v[222:225], v[174:177], 0
	v_mfma_f32_16x16x32_bf16 v[34:37], v[230:233], v[174:177], 0
	v_mfma_f32_16x16x32_bf16 v[22:25], v[222:225], v[182:185], 0
	v_mfma_f32_16x16x32_bf16 v[18:21], v[230:233], v[182:185], 0
	v_mfma_f32_16x16x32_bf16 v[6:9], v[222:225], v[190:193], 0
	v_mfma_f32_16x16x32_bf16 v[2:5], v[230:233], v[190:193], 0
	v_mfma_f32_16x16x32_bf16 v[54:57], v[226:229], v[170:173], v[54:57]
	v_mfma_f32_16x16x32_bf16 v[50:53], v[234:237], v[170:173], v[50:53]
	v_mfma_f32_16x16x32_bf16 v[38:41], v[226:229], v[178:181], v[38:41]
	v_mfma_f32_16x16x32_bf16 v[34:37], v[234:237], v[178:181], v[34:37]
	v_mfma_f32_16x16x32_bf16 v[22:25], v[226:229], v[186:189], v[22:25]
	v_mfma_f32_16x16x32_bf16 v[18:21], v[234:237], v[186:189], v[18:21]
	v_mfma_f32_16x16x32_bf16 v[6:9], v[226:229], v[194:197], v[6:9]
	v_mfma_f32_16x16x32_bf16 v[2:5], v[234:237], v[194:197], v[2:5]
	s_add_i32 s77, 0, 0x18000
	v_add_u32_e32 v153, s77, v149
	s_barrier
	ds_read_b128 v[144:147], v153
	ds_read_b128 v[154:157], v153 offset:1024
	ds_read_b128 v[158:161], v153 offset:2048
	ds_read_b128 v[162:165], v153 offset:3072
	s_add_u32 s60, s60, 0x40000
	s_addc_u32 s61, s61, 0
	s_mov_b32 m0, s63
	v_lshl_add_u64 v[222:223], s[60:61], 0, v[0:1]
	ds_read_b128 v[166:169], v152 offset:32768
	ds_read_b128 v[170:173], v152 offset:33792
	ds_read_b128 v[174:177], v152 offset:34816
	ds_read_b128 v[178:181], v152 offset:35840
	ds_read_b128 v[182:185], v152 offset:36864
	ds_read_b128 v[186:189], v152 offset:37888
	ds_read_b128 v[190:193], v152 offset:38912
	ds_read_b128 v[194:197], v152 offset:39936
	global_load_lds_dwordx4 v[222:223], off
	v_lshl_add_u64 v[222:223], s[60:61], 0, v[130:131]
	s_mov_b32 m0, s64
	s_nop 0
	global_load_lds_dwordx4 v[222:223], off
	s_waitcnt lgkmcnt(8)
	s_barrier
	s_waitcnt lgkmcnt(0)
	v_mfma_f32_16x16x32_bf16 v[126:129], v[144:147], v[166:169], v[126:129]
	v_mfma_f32_16x16x32_bf16 v[122:125], v[158:161], v[166:169], v[122:125]
	v_mfma_f32_16x16x32_bf16 v[110:113], v[144:147], v[174:177], v[110:113]
	v_mfma_f32_16x16x32_bf16 v[106:109], v[158:161], v[174:177], v[106:109]
	v_mfma_f32_16x16x32_bf16 v[94:97], v[144:147], v[182:185], v[94:97]
	v_mfma_f32_16x16x32_bf16 v[90:93], v[158:161], v[182:185], v[90:93]
	v_mfma_f32_16x16x32_bf16 v[78:81], v[144:147], v[190:193], v[78:81]
	v_mfma_f32_16x16x32_bf16 v[74:77], v[158:161], v[190:193], v[74:77]
	v_mfma_f32_16x16x32_bf16 v[126:129], v[154:157], v[170:173], v[126:129]
	v_mfma_f32_16x16x32_bf16 v[122:125], v[162:165], v[170:173], v[122:125]
	v_mfma_f32_16x16x32_bf16 v[110:113], v[154:157], v[178:181], v[110:113]
	v_mfma_f32_16x16x32_bf16 v[106:109], v[162:165], v[178:181], v[106:109]
	v_mfma_f32_16x16x32_bf16 v[94:97], v[154:157], v[186:189], v[94:97]
	v_mfma_f32_16x16x32_bf16 v[90:93], v[162:165], v[186:189], v[90:93]
	v_mfma_f32_16x16x32_bf16 v[78:81], v[154:157], v[194:197], v[78:81]
	v_mfma_f32_16x16x32_bf16 v[74:77], v[162:165], v[194:197], v[74:77]
	s_barrier
	s_add_i32 s60, 0, 0x1c000
	s_add_i32 s61, s77, s34
	v_add_u32_e32 v153, s60, v149
	v_lshl_add_u64 v[198:199], v[198:199], 0, s[86:87]
	s_mov_b32 m0, s61
	ds_read_b128 v[222:225], v153
	ds_read_b128 v[226:229], v153 offset:1024
	ds_read_b128 v[230:233], v153 offset:2048
	ds_read_b128 v[234:237], v153 offset:3072
	global_load_lds_dwordx4 v[198:199], off
	v_lshl_add_u64 v[198:199], v[238:239], 0, s[86:87]
	s_add_i32 m0, s61, 0x2000
	s_nop 0
	global_load_lds_dwordx4 v[198:199], off
	s_barrier
	s_waitcnt lgkmcnt(0)
	v_mfma_f32_16x16x32_bf16 v[118:121], v[222:225], v[166:169], v[118:121]
	v_mfma_f32_16x16x32_bf16 v[114:117], v[230:233], v[166:169], v[114:117]
	v_mfma_f32_16x16x32_bf16 v[102:105], v[222:225], v[174:177], v[102:105]
	v_mfma_f32_16x16x32_bf16 v[98:101], v[230:233], v[174:177], v[98:101]
	v_mfma_f32_16x16x32_bf16 v[86:89], v[222:225], v[182:185], v[86:89]
	v_mfma_f32_16x16x32_bf16 v[82:85], v[230:233], v[182:185], v[82:85]
	v_mfma_f32_16x16x32_bf16 v[70:73], v[222:225], v[190:193], v[70:73]
	v_mfma_f32_16x16x32_bf16 v[66:69], v[230:233], v[190:193], v[66:69]
	v_mfma_f32_16x16x32_bf16 v[118:121], v[226:229], v[170:173], v[118:121]
	v_mfma_f32_16x16x32_bf16 v[114:117], v[234:237], v[170:173], v[114:117]
	v_mfma_f32_16x16x32_bf16 v[102:105], v[226:229], v[178:181], v[102:105]
	v_mfma_f32_16x16x32_bf16 v[98:101], v[234:237], v[178:181], v[98:101]
	v_mfma_f32_16x16x32_bf16 v[86:89], v[226:229], v[186:189], v[86:89]
	v_mfma_f32_16x16x32_bf16 v[82:85], v[234:237], v[186:189], v[82:85]
	v_mfma_f32_16x16x32_bf16 v[70:73], v[226:229], v[194:197], v[70:73]
	v_mfma_f32_16x16x32_bf16 v[66:69], v[234:237], v[194:197], v[66:69]
	s_mov_b32 m0, s65
	v_lshl_add_u64 v[198:199], v[240:241], 0, s[86:87]
	s_barrier
	ds_read_b128 v[166:169], v152 offset:49152
	ds_read_b128 v[170:173], v152 offset:50176
	ds_read_b128 v[174:177], v152 offset:51200
	ds_read_b128 v[178:181], v152 offset:52224
	ds_read_b128 v[182:185], v152 offset:53248
	ds_read_b128 v[186:189], v152 offset:54272
	ds_read_b128 v[190:193], v152 offset:55296
	ds_read_b128 v[194:197], v152 offset:56320
	global_load_lds_dwordx4 v[198:199], off
	v_lshl_add_u64 v[198:199], v[242:243], 0, s[86:87]
	s_mov_b32 m0, s66
	s_nop 0
	global_load_lds_dwordx4 v[198:199], off
	s_barrier
; #define PG8_STAGE(bufoff, gbase, voff) do { _Pragma("unroll") for (int _i = 0; _i < 2; ++_i) \
;     __builtin_amdgcn_global_load_lds((const unsigned*)((const char*)(gbase) + (voff)[_i]), (PG8_LAS unsigned*)(lds + (bufoff) + ldsw + _i * 8192), 16, 0, 0); } while (0)
; #define PG8_LDA(dst, b, h) do { _Pragma("unroll") for (int m = 0; m < 4; ++m) _Pragma("unroll") for (int k = 0; k < 2; ++k) dst[m][k] = *(const PG8_LAS bf16x8*)(lds + PG8_SA(b, h) + aoff + m * 2048 + k * 1024); } while (0)
; #define PG8_LDB(dst, b, h) do { _Pragma("unroll") for (int n = 0; n < 2; ++n) _Pragma("unroll") for (int k = 0; k < 2; ++k) dst[n][k] = *(const PG8_LAS bf16x8*)(lds + PG8_SB(b, h) + boff + n * 2048 + k * 1024); } while (0)
; #define PG8_MMA(ai, bj, At, Bt) do { __builtin_amdgcn_s_setprio(1); _Pragma("unroll") for (int m = 0; m < 4; ++m) _Pragma("unroll") for (int n = 0; n < 2; ++n) _Pragma("unroll") for (int k = 0; k < 2; ++k) \
;     acc[ai][bj][m][n] = __builtin_amdgcn_mfma_f32_16x16x32_bf16(Bt[n][k], At[m][k], acc[ai][bj][m][n], 0, 0, 0); __builtin_amdgcn_s_setprio(0); } while (0)
; #define PG8_WAIT_V(n) asm volatile("s_waitcnt vmcnt(" #n ")" ::: "memory")
; #define PG8_WAIT_L(n) asm volatile("s_waitcnt lgkmcnt(" #n ")" ::: "memory")
; #define PG8_BAR __builtin_amdgcn_s_barrier()
; #define PG8_SCHED __builtin_amdgcn_sched_barrier(0)
; template <class Epi>
; DI void gemm_phase(PG8_LAS unsigned char* lds, const Gemm g, const StaticOrder& S, const Epi& E) {
;     ...
;     for (int t = 0; t < nt; t += 2) {
;       const bool last = (t == nt - 2);
;       const char* a1 = cA + (size_t)(t + 1) * kstep;
;       const char* a2 = last ? nA : cA + (size_t)(t + 2) * kstep; const char* b2 = last ? nB : cB + (size_t)(t + 2) * kstep;
;       const char* a3 = a2 + kstep; const char* b3 = b2 + kstep;
;       PG8_LDB(B0, 0, 0); PG8_SCHED; PG8_LDA(At, 0, 0); PG8_STAGE(PG8_SA(1, 1), a1 + hstepA, voffA);
;       PG8_WAIT_L(8); PG8_BAR; PG8_WAIT_L(0); PG8_MMA(0, 0, At, B0); PG8_BAR; PG8_SCHED;
;       PG8_LDB(B1, 0, 1); PG8_STAGE(PG8_SB(0, 0), b2, voffB);
;     ...
;       PG8_BAR; PG8_WAIT_L(0); PG8_MMA(1, 0, At, B0); PG8_BAR; PG8_SCHED;
;       PG8_STAGE(PG8_SB(1, 1), b3 + hstepB, voffB);
;       PG8_WAIT_V(6); PG8_BAR; PG8_MMA(1, 1, At, B1); PG8_BAR;
	s_waitcnt lgkmcnt(0)
	v_mfma_f32_16x16x32_bf16 v[62:65], v[144:147], v[166:169], v[62:65]
	v_mfma_f32_16x16x32_bf16 v[58:61], v[158:161], v[166:169], v[58:61]
	v_mfma_f32_16x16x32_bf16 v[46:49], v[144:147], v[174:177], v[46:49]
	v_mfma_f32_16x16x32_bf16 v[42:45], v[158:161], v[174:177], v[42:45]
	v_mfma_f32_16x16x32_bf16 v[30:33], v[144:147], v[182:185], v[30:33]
	v_mfma_f32_16x16x32_bf16 v[26:29], v[158:161], v[182:185], v[26:29]
	v_mfma_f32_16x16x32_bf16 v[14:17], v[144:147], v[190:193], v[14:17]
	v_mfma_f32_16x16x32_bf16 v[10:13], v[158:161], v[190:193], v[10:13]
	v_mfma_f32_16x16x32_bf16 v[62:65], v[154:157], v[170:173], v[62:65]
	v_mfma_f32_16x16x32_bf16 v[58:61], v[162:165], v[170:173], v[58:61]
	v_mfma_f32_16x16x32_bf16 v[46:49], v[154:157], v[178:181], v[46:49]
	v_mfma_f32_16x16x32_bf16 v[42:45], v[162:165], v[178:181], v[42:45]
	v_mfma_f32_16x16x32_bf16 v[30:33], v[154:157], v[186:189], v[30:33]
	v_mfma_f32_16x16x32_bf16 v[26:29], v[162:165], v[186:189], v[26:29]
	v_mfma_f32_16x16x32_bf16 v[14:17], v[154:157], v[194:197], v[14:17]
	v_mfma_f32_16x16x32_bf16 v[10:13], v[162:165], v[194:197], v[10:13]
	s_barrier
	s_add_u32 s58, s58, 0x40080
	s_addc_u32 s59, s59, 0
	s_add_i32 s60, s60, s34
	v_lshl_add_u64 v[144:145], s[58:59], 0, v[0:1]
	s_mov_b32 m0, s60
	s_nop 0
	global_load_lds_dwordx4 v[144:145], off
	v_lshl_add_u64 v[144:145], s[58:59], 0, v[130:131]
	s_add_i32 m0, s60, 0x2000
	s_nop 0
	global_load_lds_dwordx4 v[144:145], off
	s_waitcnt vmcnt(6)
	s_barrier
	v_mfma_f32_16x16x32_bf16 v[54:57], v[222:225], v[166:169], v[54:57]
	v_mfma_f32_16x16x32_bf16 v[50:53], v[230:233], v[166:169], v[50:53]
	v_mfma_f32_16x16x32_bf16 v[38:41], v[222:225], v[174:177], v[38:41]
	v_mfma_f32_16x16x32_bf16 v[34:37], v[230:233], v[174:177], v[34:37]
	v_mfma_f32_16x16x32_bf16 v[22:25], v[222:225], v[182:185], v[22:25]
	v_mfma_f32_16x16x32_bf16 v[18:21], v[230:233], v[182:185], v[18:21]
	v_mfma_f32_16x16x32_bf16 v[6:9], v[222:225], v[190:193], v[6:9]
	v_mfma_f32_16x16x32_bf16 v[2:5], v[230:233], v[190:193], v[2:5]
	v_mfma_f32_16x16x32_bf16 v[54:57], v[226:229], v[170:173], v[54:57]
	v_mfma_f32_16x16x32_bf16 v[50:53], v[234:237], v[170:173], v[50:53]
	v_mfma_f32_16x16x32_bf16 v[38:41], v[226:229], v[178:181], v[38:41]
	v_mfma_f32_16x16x32_bf16 v[34:37], v[234:237], v[178:181], v[34:37]
	v_mfma_f32_16x16x32_bf16 v[22:25], v[226:229], v[186:189], v[22:25]
	v_mfma_f32_16x16x32_bf16 v[18:21], v[234:237], v[186:189], v[18:21]
	v_mfma_f32_16x16x32_bf16 v[6:9], v[226:229], v[194:197], v[6:9]
	v_mfma_f32_16x16x32_bf16 v[2:5], v[234:237], v[194:197], v[2:5]
	s_add_i32 s76, s76, 2
	s_add_u32 s56, s56, 0x100
	s_addc_u32 s57, s57, 0
	s_add_u32 s74, s74, 0x100
	s_addc_u32 s75, s75, 0
	s_cmp_gt_u32 s76, 13
	s_barrier
	s_cbranch_scc1 .Lpeel_exit_0
.LBB0_52:
	s_add_u32 s58, s56, 0xfffc0080
	s_addc_u32 s59, s57, -1
	s_add_i32 s77, 0, 0x10000
	v_add_u32_e32 v153, s77, v149
	ds_read_b128 v[144:147], v153
	ds_read_b128 v[154:157], v153 offset:1024
	ds_read_b128 v[158:161], v153 offset:2048
	ds_read_b128 v[162:165], v153 offset:3072
	s_cmp_eq_u32 s76, 12
	s_cselect_b32 s61, s51, s59
	s_cselect_b32 s60, s72, s58
	s_cselect_b32 s59, s31, s75
	s_cselect_b32 s58, s73, s74
	v_lshl_add_u64 v[198:199], s[56:57], 0, v[132:133]
	s_add_i32 m0, s37, 0xc000
	ds_read_b128 v[166:169], v152
	ds_read_b128 v[170:173], v152 offset:1024
	ds_read_b128 v[174:177], v152 offset:2048
	ds_read_b128 v[178:181], v152 offset:3072
	ds_read_b128 v[182:185], v152 offset:4096
	ds_read_b128 v[186:189], v152 offset:5120
	ds_read_b128 v[190:193], v152 offset:6144
	ds_read_b128 v[194:197], v152 offset:7168
	global_load_lds_dwordx4 v[198:199], off
	v_lshl_add_u64 v[198:199], s[56:57], 0, v[142:143]
	s_add_i32 m0, s37, 0xe000
	s_nop 0
	global_load_lds_dwordx4 v[198:199], off
	s_waitcnt lgkmcnt(8)
	s_barrier
	s_waitcnt lgkmcnt(0)
	v_mfma_f32_16x16x32_bf16 v[126:129], v[144:147], v[166:169], v[126:129]
	v_mfma_f32_16x16x32_bf16 v[122:125], v[158:161], v[166:169], v[122:125]
	v_mfma_f32_16x16x32_bf16 v[110:113], v[144:147], v[174:177], v[110:113]
	v_mfma_f32_16x16x32_bf16 v[106:109], v[158:161], v[174:177], v[106:109]
	v_mfma_f32_16x16x32_bf16 v[94:97], v[144:147], v[182:185], v[94:97]
	v_mfma_f32_16x16x32_bf16 v[90:93], v[158:161], v[182:185], v[90:93]
	v_mfma_f32_16x16x32_bf16 v[78:81], v[144:147], v[190:193], v[78:81]
	v_mfma_f32_16x16x32_bf16 v[74:77], v[158:161], v[190:193], v[74:77]
	v_mfma_f32_16x16x32_bf16 v[126:129], v[154:157], v[170:173], v[126:129]
	v_mfma_f32_16x16x32_bf16 v[122:125], v[162:165], v[170:173], v[122:125]
	v_mfma_f32_16x16x32_bf16 v[110:113], v[154:157], v[178:181], v[110:113]
	v_mfma_f32_16x16x32_bf16 v[106:109], v[162:165], v[178:181], v[106:109]
	v_mfma_f32_16x16x32_bf16 v[94:97], v[154:157], v[186:189], v[94:97]
	v_mfma_f32_16x16x32_bf16 v[90:93], v[162:165], v[186:189], v[90:93]
	v_mfma_f32_16x16x32_bf16 v[78:81], v[154:157], v[194:197], v[78:81]
	v_mfma_f32_16x16x32_bf16 v[74:77], v[162:165], v[194:197], v[74:77]
	s_barrier
	s_add_i32 s80, 0, 0x14000
	s_add_i32 s77, s77, s34
	v_add_u32_e32 v153, s80, v149
	v_lshl_add_u64 v[198:199], s[58:59], 0, v[0:1]
	s_mov_b32 m0, s77
	ds_read_b128 v[222:225], v153
	ds_read_b128 v[226:229], v153 offset:1024
	ds_read_b128 v[230:233], v153 offset:2048
	ds_read_b128 v[234:237], v153 offset:3072
	global_load_lds_dwordx4 v[198:199], off
	v_lshl_add_u64 v[238:239], s[58:59], 0, v[130:131]
	s_add_i32 m0, s77, 0x2000
	s_nop 0
	global_load_lds_dwordx4 v[238:239], off
	s_barrier
; #define PG8_STAGE(bufoff, gbase, voff) do { _Pragma("unroll") for (int _i = 0; _i < 2; ++_i) \
;     __builtin_amdgcn_global_load_lds((const unsigned*)((const char*)(gbase) + (voff)[_i]), (PG8_LAS unsigned*)(lds + (bufoff) + ldsw + _i * 8192), 16, 0, 0); } while (0)
; #define PG8_LDA(dst, b, h) do { _Pragma("unroll") for (int m = 0; m < 4; ++m) _Pragma("unroll") for (int k = 0; k < 2; ++k) dst[m][k] = *(const PG8_LAS bf16x8*)(lds + PG8_SA(b, h) + aoff + m * 2048 + k * 1024); } while (0)
; #define PG8_LDB(dst, b, h) do { _Pragma("unroll") for (int n = 0; n < 2; ++n) _Pragma("unroll") for (int k = 0; k < 2; ++k) dst[n][k] = *(const PG8_LAS bf16x8*)(lds + PG8_SB(b, h) + boff + n * 2048 + k * 1024); } while (0)
; #define PG8_MMA(ai, bj, At, Bt) do { __builtin_amdgcn_s_setprio(1); _Pragma("unroll") for (int m = 0; m < 4; ++m) _Pragma("unroll") for (int n = 0; n < 2; ++n) _Pragma("unroll") for (int k = 0; k < 2; ++k) \
;     acc[ai][bj][m][n] = __builtin_amdgcn_mfma_f32_16x16x32_bf16(Bt[n][k], At[m][k], acc[ai][bj][m][n], 0, 0, 0); __builtin_amdgcn_s_setprio(0); } while (0)
; #define PG8_WAIT_V(n) asm volatile("s_waitcnt vmcnt(" #n ")" ::: "memory")
; #define PG8_WAIT_L(n) asm volatile("s_waitcnt lgkmcnt(" #n ")" ::: "memory")
; #define PG8_BAR __builtin_amdgcn_s_barrier()
; #define PG8_SCHED __builtin_amdgcn_sched_barrier(0)
; template <class Epi>
; DI void gemm_phase(PG8_LAS unsigned char* lds, const Gemm g, const StaticOrder& S, const Epi& E) {
;     ...
;       PG8_BAR; PG8_WAIT_L(0); PG8_MMA(0, 1, At, B1); PG8_BAR;
;       PG8_LDA(At, 0, 1); PG8_STAGE(PG8_SA(0, 0), a2, voffA);
;       PG8_BAR; PG8_WAIT_L(0); PG8_MMA(1, 0, At, B0); PG8_BAR; PG8_SCHED;
;       PG8_STAGE(PG8_SB(0, 1), b2 + hstepB, voffB);
;       PG8_WAIT_V(6); PG8_BAR; PG8_MMA(1, 1, At, B1); PG8_BAR;
;       PG8_LDB(B0, 1, 0); PG8_SCHED; PG8_LDA(At, 1, 0); PG8_STAGE(PG8_SA(0, 1), a2 + hstepA, voffA);
;       PG8_WAIT_L(8); PG8_BAR; PG8_WAIT_L(0); PG8_MMA(0, 0, At, B0); PG8_BAR; PG8_SCHED;
	s_waitcnt lgkmcnt(0)
	v_mfma_f32_16x16x32_bf16 v[118:121], v[222:225], v[166:169], v[118:121]
	v_mfma_f32_16x16x32_bf16 v[114:117], v[230:233], v[166:169], v[114:117]
	v_mfma_f32_16x16x32_bf16 v[102:105], v[222:225], v[174:177], v[102:105]
	v_mfma_f32_16x16x32_bf16 v[98:101], v[230:233], v[174:177], v[98:101]
	v_mfma_f32_16x16x32_bf16 v[86:89], v[222:225], v[182:185], v[86:89]
	v_mfma_f32_16x16x32_bf16 v[82:85], v[230:233], v[182:185], v[82:85]
	v_mfma_f32_16x16x32_bf16 v[70:73], v[222:225], v[190:193], v[70:73]
	v_mfma_f32_16x16x32_bf16 v[66:69], v[230:233], v[190:193], v[66:69]
	v_mfma_f32_16x16x32_bf16 v[118:121], v[226:229], v[170:173], v[118:121]
	v_mfma_f32_16x16x32_bf16 v[114:117], v[234:237], v[170:173], v[114:117]
	v_mfma_f32_16x16x32_bf16 v[102:105], v[226:229], v[178:181], v[102:105]
	v_mfma_f32_16x16x32_bf16 v[98:101], v[234:237], v[178:181], v[98:101]
	v_mfma_f32_16x16x32_bf16 v[86:89], v[226:229], v[186:189], v[86:89]
	v_mfma_f32_16x16x32_bf16 v[82:85], v[234:237], v[186:189], v[82:85]
	v_mfma_f32_16x16x32_bf16 v[70:73], v[226:229], v[194:197], v[70:73]
	v_mfma_f32_16x16x32_bf16 v[66:69], v[234:237], v[194:197], v[66:69]
	s_mov_b32 m0, s37
	v_lshl_add_u64 v[240:241], s[60:61], 0, v[0:1]
	s_barrier
	ds_read_b128 v[166:169], v152 offset:16384
	ds_read_b128 v[170:173], v152 offset:17408
	ds_read_b128 v[174:177], v152 offset:18432
	ds_read_b128 v[178:181], v152 offset:19456
	ds_read_b128 v[182:185], v152 offset:20480
	ds_read_b128 v[186:189], v152 offset:21504
	ds_read_b128 v[190:193], v152 offset:22528
	ds_read_b128 v[194:197], v152 offset:23552
	global_load_lds_dwordx4 v[240:241], off
	v_lshl_add_u64 v[242:243], s[60:61], 0, v[130:131]
	s_mov_b32 m0, s62
	s_nop 0
	global_load_lds_dwordx4 v[242:243], off
	s_barrier
	s_waitcnt lgkmcnt(0)
	v_mfma_f32_16x16x32_bf16 v[62:65], v[144:147], v[166:169], v[62:65]
	v_mfma_f32_16x16x32_bf16 v[58:61], v[158:161], v[166:169], v[58:61]
	v_mfma_f32_16x16x32_bf16 v[46:49], v[144:147], v[174:177], v[46:49]
	v_mfma_f32_16x16x32_bf16 v[42:45], v[158:161], v[174:177], v[42:45]
	v_mfma_f32_16x16x32_bf16 v[30:33], v[144:147], v[182:185], v[30:33]
	v_mfma_f32_16x16x32_bf16 v[26:29], v[158:161], v[182:185], v[26:29]
	v_mfma_f32_16x16x32_bf16 v[14:17], v[144:147], v[190:193], v[14:17]
	v_mfma_f32_16x16x32_bf16 v[10:13], v[158:161], v[190:193], v[10:13]
	v_mfma_f32_16x16x32_bf16 v[62:65], v[154:157], v[170:173], v[62:65]
	v_mfma_f32_16x16x32_bf16 v[58:61], v[162:165], v[170:173], v[58:61]
	v_mfma_f32_16x16x32_bf16 v[46:49], v[154:157], v[178:181], v[46:49]
	v_mfma_f32_16x16x32_bf16 v[42:45], v[162:165], v[178:181], v[42:45]
	v_mfma_f32_16x16x32_bf16 v[30:33], v[154:157], v[186:189], v[30:33]
	v_mfma_f32_16x16x32_bf16 v[26:29], v[162:165], v[186:189], v[26:29]
	v_mfma_f32_16x16x32_bf16 v[14:17], v[154:157], v[194:197], v[14:17]
	v_mfma_f32_16x16x32_bf16 v[10:13], v[162:165], v[194:197], v[10:13]
	s_barrier
	s_add_u32 s78, s58, 0x40000
	s_addc_u32 s79, s59, 0
	s_add_i32 s77, s80, s34
	v_lshl_add_u64 v[144:145], s[78:79], 0, v[0:1]
	s_mov_b32 m0, s77
	s_nop 0
	global_load_lds_dwordx4 v[144:145], off
	v_lshl_add_u64 v[144:145], s[78:79], 0, v[130:131]
	s_add_i32 m0, s77, 0x2000
	s_nop 0
	global_load_lds_dwordx4 v[144:145], off
	s_waitcnt vmcnt(6)
	s_barrier
	v_mfma_f32_16x16x32_bf16 v[54:57], v[222:225], v[166:169], v[54:57]
	v_mfma_f32_16x16x32_bf16 v[50:53], v[230:233], v[166:169], v[50:53]
	v_mfma_f32_16x16x32_bf16 v[38:41], v[222:225], v[174:177], v[38:41]
	v_mfma_f32_16x16x32_bf16 v[34:37], v[230:233], v[174:177], v[34:37]
	v_mfma_f32_16x16x32_bf16 v[22:25], v[222:225], v[182:185], v[22:25]
	v_mfma_f32_16x16x32_bf16 v[18:21], v[230:233], v[182:185], v[18:21]
	v_mfma_f32_16x16x32_bf16 v[6:9], v[222:225], v[190:193], v[6:9]
	v_mfma_f32_16x16x32_bf16 v[2:5], v[230:233], v[190:193], v[2:5]
	v_mfma_f32_16x16x32_bf16 v[54:57], v[226:229], v[170:173], v[54:57]
	v_mfma_f32_16x16x32_bf16 v[50:53], v[234:237], v[170:173], v[50:53]
	v_mfma_f32_16x16x32_bf16 v[38:41], v[226:229], v[178:181], v[38:41]
	v_mfma_f32_16x16x32_bf16 v[34:37], v[234:237], v[178:181], v[34:37]
	v_mfma_f32_16x16x32_bf16 v[22:25], v[226:229], v[186:189], v[22:25]
	v_mfma_f32_16x16x32_bf16 v[18:21], v[234:237], v[186:189], v[18:21]
	v_mfma_f32_16x16x32_bf16 v[6:9], v[226:229], v[194:197], v[6:9]
	v_mfma_f32_16x16x32_bf16 v[2:5], v[234:237], v[194:197], v[2:5]
	s_add_i32 s77, 0, 0x18000
	v_add_u32_e32 v153, s77, v149
	s_barrier
	ds_read_b128 v[144:147], v153
	ds_read_b128 v[154:157], v153 offset:1024
	ds_read_b128 v[158:161], v153 offset:2048
	ds_read_b128 v[162:165], v153 offset:3072
	s_add_u32 s60, s60, 0x40000
	s_addc_u32 s61, s61, 0
	s_mov_b32 m0, s63
	v_lshl_add_u64 v[222:223], s[60:61], 0, v[0:1]
	ds_read_b128 v[166:169], v152 offset:32768
	ds_read_b128 v[170:173], v152 offset:33792
	ds_read_b128 v[174:177], v152 offset:34816
	ds_read_b128 v[178:181], v152 offset:35840
	ds_read_b128 v[182:185], v152 offset:36864
	ds_read_b128 v[186:189], v152 offset:37888
	ds_read_b128 v[190:193], v152 offset:38912
	ds_read_b128 v[194:197], v152 offset:39936
	global_load_lds_dwordx4 v[222:223], off
	v_lshl_add_u64 v[222:223], s[60:61], 0, v[130:131]
	s_mov_b32 m0, s64
	s_nop 0
	global_load_lds_dwordx4 v[222:223], off
	s_waitcnt lgkmcnt(8)
	s_barrier
; #define PG8_STAGE(bufoff, gbase, voff) do { _Pragma("unroll") for (int _i = 0; _i < 2; ++_i) \
;     __builtin_amdgcn_global_load_lds((const unsigned*)((const char*)(gbase) + (voff)[_i]), (PG8_LAS unsigned*)(lds + (bufoff) + ldsw + _i * 8192), 16, 0, 0); } while (0)
; #define PG8_LDA(dst, b, h) do { _Pragma("unroll") for (int m = 0; m < 4; ++m) _Pragma("unroll") for (int k = 0; k < 2; ++k) dst[m][k] = *(const PG8_LAS bf16x8*)(lds + PG8_SA(b, h) + aoff + m * 2048 + k * 1024); } while (0)
; #define PG8_LDB(dst, b, h) do { _Pragma("unroll") for (int n = 0; n < 2; ++n) _Pragma("unroll") for (int k = 0; k < 2; ++k) dst[n][k] = *(const PG8_LAS bf16x8*)(lds + PG8_SB(b, h) + boff + n * 2048 + k * 1024); } while (0)
; #define PG8_MMA(ai, bj, At, Bt) do { __builtin_amdgcn_s_setprio(1); _Pragma("unroll") for (int m = 0; m < 4; ++m) _Pragma("unroll") for (int n = 0; n < 2; ++n) _Pragma("unroll") for (int k = 0; k < 2; ++k) \
;     acc[ai][bj][m][n] = __builtin_amdgcn_mfma_f32_16x16x32_bf16(Bt[n][k], At[m][k], acc[ai][bj][m][n], 0, 0, 0); __builtin_amdgcn_s_setprio(0); } while (0)
; #define PG8_WAIT_V(n) asm volatile("s_waitcnt vmcnt(" #n ")" ::: "memory")
; #define PG8_WAIT_L(n) asm volatile("s_waitcnt lgkmcnt(" #n ")" ::: "memory")
; #define PG8_BAR __builtin_amdgcn_s_barrier()
; #define PG8_SCHED __builtin_amdgcn_sched_barrier(0)
; template <class Epi>
; DI void gemm_phase(PG8_LAS unsigned char* lds, const Gemm g, const StaticOrder& S, const Epi& E) {
;     ...
;       PG8_WAIT_L(8); PG8_BAR; PG8_WAIT_L(0); PG8_MMA(0, 0, At, B0); PG8_BAR; PG8_SCHED;
;       PG8_LDB(B1, 1, 1); PG8_STAGE(PG8_SB(1, 0), b3, voffB);
;       PG8_BAR; PG8_WAIT_L(0); PG8_MMA(0, 1, At, B1); PG8_BAR;
;       PG8_LDA(At, 1, 1); PG8_STAGE(PG8_SA(1, 0), a3, voffA);
;       PG8_BAR; PG8_WAIT_L(0); PG8_MMA(1, 0, At, B0); PG8_BAR; PG8_SCHED;
;       PG8_STAGE(PG8_SB(1, 1), b3 + hstepB, voffB);
;       PG8_WAIT_V(6); PG8_BAR; PG8_MMA(1, 1, At, B1); PG8_BAR;
	s_waitcnt lgkmcnt(0)
	v_mfma_f32_16x16x32_bf16 v[126:129], v[144:147], v[166:169], v[126:129]
	v_mfma_f32_16x16x32_bf16 v[122:125], v[158:161], v[166:169], v[122:125]
	v_mfma_f32_16x16x32_bf16 v[110:113], v[144:147], v[174:177], v[110:113]
	v_mfma_f32_16x16x32_bf16 v[106:109], v[158:161], v[174:177], v[106:109]
	v_mfma_f32_16x16x32_bf16 v[94:97], v[144:147], v[182:185], v[94:97]
	v_mfma_f32_16x16x32_bf16 v[90:93], v[158:161], v[182:185], v[90:93]
	v_mfma_f32_16x16x32_bf16 v[78:81], v[144:147], v[190:193], v[78:81]
	v_mfma_f32_16x16x32_bf16 v[74:77], v[158:161], v[190:193], v[74:77]
	v_mfma_f32_16x16x32_bf16 v[126:129], v[154:157], v[170:173], v[126:129]
	v_mfma_f32_16x16x32_bf16 v[122:125], v[162:165], v[170:173], v[122:125]
	v_mfma_f32_16x16x32_bf16 v[110:113], v[154:157], v[178:181], v[110:113]
	v_mfma_f32_16x16x32_bf16 v[106:109], v[162:165], v[178:181], v[106:109]
	v_mfma_f32_16x16x32_bf16 v[94:97], v[154:157], v[186:189], v[94:97]
	v_mfma_f32_16x16x32_bf16 v[90:93], v[162:165], v[186:189], v[90:93]
	v_mfma_f32_16x16x32_bf16 v[78:81], v[154:157], v[194:197], v[78:81]
	v_mfma_f32_16x16x32_bf16 v[74:77], v[162:165], v[194:197], v[74:77]
	s_barrier
	s_add_i32 s60, 0, 0x1c000
	s_add_i32 s61, s77, s34
	v_add_u32_e32 v153, s60, v149
	v_lshl_add_u64 v[198:199], v[198:199], 0, s[86:87]
	s_mov_b32 m0, s61
	ds_read_b128 v[222:225], v153
	ds_read_b128 v[226:229], v153 offset:1024
	ds_read_b128 v[230:233], v153 offset:2048
	ds_read_b128 v[234:237], v153 offset:3072
	global_load_lds_dwordx4 v[198:199], off
	v_lshl_add_u64 v[198:199], v[238:239], 0, s[86:87]
	s_add_i32 m0, s61, 0x2000
	s_nop 0
	global_load_lds_dwordx4 v[198:199], off
	s_barrier
	s_waitcnt lgkmcnt(0)
	v_mfma_f32_16x16x32_bf16 v[118:121], v[222:225], v[166:169], v[118:121]
	v_mfma_f32_16x16x32_bf16 v[114:117], v[230:233], v[166:169], v[114:117]
	v_mfma_f32_16x16x32_bf16 v[102:105], v[222:225], v[174:177], v[102:105]
	v_mfma_f32_16x16x32_bf16 v[98:101], v[230:233], v[174:177], v[98:101]
	v_mfma_f32_16x16x32_bf16 v[86:89], v[222:225], v[182:185], v[86:89]
	v_mfma_f32_16x16x32_bf16 v[82:85], v[230:233], v[182:185], v[82:85]
	v_mfma_f32_16x16x32_bf16 v[70:73], v[222:225], v[190:193], v[70:73]
	v_mfma_f32_16x16x32_bf16 v[66:69], v[230:233], v[190:193], v[66:69]
	v_mfma_f32_16x16x32_bf16 v[118:121], v[226:229], v[170:173], v[118:121]
	v_mfma_f32_16x16x32_bf16 v[114:117], v[234:237], v[170:173], v[114:117]
	v_mfma_f32_16x16x32_bf16 v[102:105], v[226:229], v[178:181], v[102:105]
	v_mfma_f32_16x16x32_bf16 v[98:101], v[234:237], v[178:181], v[98:101]
	v_mfma_f32_16x16x32_bf16 v[86:89], v[226:229], v[186:189], v[86:89]
	v_mfma_f32_16x16x32_bf16 v[82:85], v[234:237], v[186:189], v[82:85]
	v_mfma_f32_16x16x32_bf16 v[70:73], v[226:229], v[194:197], v[70:73]
	v_mfma_f32_16x16x32_bf16 v[66:69], v[234:237], v[194:197], v[66:69]
	s_mov_b32 m0, s65
	v_lshl_add_u64 v[198:199], v[240:241], 0, s[86:87]
	s_barrier
	ds_read_b128 v[166:169], v152 offset:49152
	ds_read_b128 v[170:173], v152 offset:50176
	ds_read_b128 v[174:177], v152 offset:51200
	ds_read_b128 v[178:181], v152 offset:52224
	ds_read_b128 v[182:185], v152 offset:53248
	ds_read_b128 v[186:189], v152 offset:54272
	ds_read_b128 v[190:193], v152 offset:55296
	ds_read_b128 v[194:197], v152 offset:56320
	global_load_lds_dwordx4 v[198:199], off
	v_lshl_add_u64 v[198:199], v[242:243], 0, s[86:87]
	s_mov_b32 m0, s66
	s_nop 0
	global_load_lds_dwordx4 v[198:199], off
	s_barrier
	s_waitcnt lgkmcnt(0)
	v_mfma_f32_16x16x32_bf16 v[62:65], v[144:147], v[166:169], v[62:65]
	v_mfma_f32_16x16x32_bf16 v[58:61], v[158:161], v[166:169], v[58:61]
	v_mfma_f32_16x16x32_bf16 v[46:49], v[144:147], v[174:177], v[46:49]
	v_mfma_f32_16x16x32_bf16 v[42:45], v[158:161], v[174:177], v[42:45]
	v_mfma_f32_16x16x32_bf16 v[30:33], v[144:147], v[182:185], v[30:33]
	v_mfma_f32_16x16x32_bf16 v[26:29], v[158:161], v[182:185], v[26:29]
	v_mfma_f32_16x16x32_bf16 v[14:17], v[144:147], v[190:193], v[14:17]
	v_mfma_f32_16x16x32_bf16 v[10:13], v[158:161], v[190:193], v[10:13]
	v_mfma_f32_16x16x32_bf16 v[62:65], v[154:157], v[170:173], v[62:65]
	v_mfma_f32_16x16x32_bf16 v[58:61], v[162:165], v[170:173], v[58:61]
	v_mfma_f32_16x16x32_bf16 v[46:49], v[154:157], v[178:181], v[46:49]
	v_mfma_f32_16x16x32_bf16 v[42:45], v[162:165], v[178:181], v[42:45]
	v_mfma_f32_16x16x32_bf16 v[30:33], v[154:157], v[186:189], v[30:33]
	v_mfma_f32_16x16x32_bf16 v[26:29], v[162:165], v[186:189], v[26:29]
	v_mfma_f32_16x16x32_bf16 v[14:17], v[154:157], v[194:197], v[14:17]
	v_mfma_f32_16x16x32_bf16 v[10:13], v[162:165], v[194:197], v[10:13]
	s_barrier
	s_add_u32 s58, s58, 0x40080
	s_addc_u32 s59, s59, 0
	s_add_i32 s60, s60, s34
	v_lshl_add_u64 v[144:145], s[58:59], 0, v[0:1]
	s_mov_b32 m0, s60
	s_nop 0
	global_load_lds_dwordx4 v[144:145], off
	v_lshl_add_u64 v[144:145], s[58:59], 0, v[130:131]
	s_add_i32 m0, s60, 0x2000
	s_nop 0
	global_load_lds_dwordx4 v[144:145], off
	s_waitcnt vmcnt(6)
	s_barrier
	v_mfma_f32_16x16x32_bf16 v[54:57], v[222:225], v[166:169], v[54:57]
	v_mfma_f32_16x16x32_bf16 v[50:53], v[230:233], v[166:169], v[50:53]
	v_mfma_f32_16x16x32_bf16 v[38:41], v[222:225], v[174:177], v[38:41]
	v_mfma_f32_16x16x32_bf16 v[34:37], v[230:233], v[174:177], v[34:37]
	v_mfma_f32_16x16x32_bf16 v[22:25], v[222:225], v[182:185], v[22:25]
	v_mfma_f32_16x16x32_bf16 v[18:21], v[230:233], v[182:185], v[18:21]
	v_mfma_f32_16x16x32_bf16 v[6:9], v[222:225], v[190:193], v[6:9]
	v_mfma_f32_16x16x32_bf16 v[2:5], v[230:233], v[190:193], v[2:5]
	v_mfma_f32_16x16x32_bf16 v[54:57], v[226:229], v[170:173], v[54:57]
	v_mfma_f32_16x16x32_bf16 v[50:53], v[234:237], v[170:173], v[50:53]
	v_mfma_f32_16x16x32_bf16 v[38:41], v[226:229], v[178:181], v[38:41]
	v_mfma_f32_16x16x32_bf16 v[34:37], v[234:237], v[178:181], v[34:37]
	v_mfma_f32_16x16x32_bf16 v[22:25], v[226:229], v[186:189], v[22:25]
	v_mfma_f32_16x16x32_bf16 v[18:21], v[234:237], v[186:189], v[18:21]
	v_mfma_f32_16x16x32_bf16 v[6:9], v[226:229], v[194:197], v[6:9]
	v_mfma_f32_16x16x32_bf16 v[2:5], v[234:237], v[194:197], v[2:5]
	s_add_i32 s76, s76, 2
	s_add_u32 s56, s56, 0x100
	s_addc_u32 s57, s57, 0
	s_add_u32 s74, s74, 0x100
	s_addc_u32 s75, s75, 0
	s_cmp_gt_u32 s76, 13
	s_barrier
	s_cbranch_scc0 .LBB0_52

; #define PG8_STAGE(bufoff, gbase, voff) do { _Pragma("unroll") for (int _i = 0; _i < 2; ++_i) \
;     __builtin_amdgcn_global_load_lds((const unsigned*)((const char*)(gbase) + (voff)[_i]), (PG8_LAS unsigned*)(lds + (bufoff) + ldsw + _i * 8192), 16, 0, 0); } while (0)
; #define PG8_LDA(dst, b, h) do { _Pragma("unroll") for (int m = 0; m < 4; ++m) _Pragma("unroll") for (int k = 0; k < 2; ++k) dst[m][k] = *(const PG8_LAS bf16x8*)(lds + PG8_SA(b, h) + aoff + m * 2048 + k * 1024); } while (0)
; #define PG8_LDB(dst, b, h) do { _Pragma("unroll") for (int n = 0; n < 2; ++n) _Pragma("unroll") for (int k = 0; k < 2; ++k) dst[n][k] = *(const PG8_LAS bf16x8*)(lds + PG8_SB(b, h) + boff + n * 2048 + k * 1024); } while (0)
; #define PG8_MMA(ai, bj, At, Bt) do { __builtin_amdgcn_s_setprio(1); _Pragma("unroll") for (int m = 0; m < 4; ++m) _Pragma("unroll") for (int n = 0; n < 2; ++n) _Pragma("unroll") for (int k = 0; k < 2; ++k) \
;     acc[ai][bj][m][n] = __builtin_amdgcn_mfma_f32_16x16x32_bf16(Bt[n][k], At[m][k], acc[ai][bj][m][n], 0, 0, 0); __builtin_amdgcn_s_setprio(0); } while (0)
; #define PG8_WAIT_L(n) asm volatile("s_waitcnt lgkmcnt(" #n ")" ::: "memory")
; #define PG8_BAR __builtin_amdgcn_s_barrier()
; #define PG8_SCHED __builtin_amdgcn_sched_barrier(0)
; template <class Epi>
; DI void gemm_phase(PG8_LAS unsigned char* lds, const Gemm g, const StaticOrder& S, const Epi& E) {
;     ...
;     const bool has_next = S.next(ui + 1, nxt);
;     const char* nA = has_next ? (const char*)g.A + (size_t)nxt.pm * tstepA : cA; const char* nB = has_next ? (const char*)g.Bt + (size_t)nxt.pn * tstepB : cB;
;     for (int t = 0; t < nt; t += 2) {
;       const bool last = (t == nt - 2);
;       const char* a1 = cA + (size_t)(t + 1) * kstep;
;       const char* a2 = last ? nA : cA + (size_t)(t + 2) * kstep; const char* b2 = last ? nB : cB + (size_t)(t + 2) * kstep;
;       const char* a3 = a2 + kstep; const char* b3 = b2 + kstep;
;       PG8_LDB(B0, 0, 0); PG8_SCHED; PG8_LDA(At, 0, 0); PG8_STAGE(PG8_SA(1, 1), a1 + hstepA, voffA);
;       PG8_WAIT_L(8); PG8_BAR; PG8_WAIT_L(0); PG8_MMA(0, 0, At, B0); PG8_BAR; PG8_SCHED;
;       PG8_LDB(B1, 0, 1); PG8_STAGE(PG8_SB(0, 0), b2, voffB);
;       PG8_BAR; PG8_WAIT_L(0); PG8_MMA(0, 1, At, B1); PG8_BAR;
;       PG8_LDA(At, 0, 1); PG8_STAGE(PG8_SA(0, 0), a2, voffA);
;       PG8_BAR; PG8_WAIT_L(0); PG8_MMA(1, 0, At, B0); PG8_BAR; PG8_SCHED;
.LBB0_834:
	s_add_u32 s44, s58, 0x80
	s_addc_u32 s45, s59, 0
	s_add_u32 s79, s56, 0x100
	v_mov_b32_e32 v2, 0
	s_addc_u32 s80, s57, 0
	s_mov_b32 s56, 0
	s_add_i32 s81, s56, 2
	s_add_u32 s58, s44, 0x80
	s_addc_u32 s57, s45, 0
	s_add_i32 s82, 0, 0x10000
	v_add_u32_e32 v160, s82, v223
	ds_read_b128 v[130:133], v160
	ds_read_b128 v[152:155], v160 offset:1024
	ds_read_b128 v[156:159], v160 offset:2048
	ds_read_b128 v[160:163], v160 offset:3072
	s_cmp_eq_u32 s75, s56
	s_cselect_b32 s56, s0, s58
	s_cselect_b32 s57, s1, s57
	s_cselect_b32 s59, s55, s80
	s_cselect_b32 s58, s54, s79
	v_lshl_add_u64 v[196:197], s[44:45], 0, v[148:149]
	s_add_i32 m0, s66, 0xc000
	ds_read_b128 v[164:167], v225
	ds_read_b128 v[168:171], v225 offset:1024
	ds_read_b128 v[172:175], v225 offset:2048
	ds_read_b128 v[176:179], v225 offset:3072
	ds_read_b128 v[180:183], v225 offset:4096
	ds_read_b128 v[184:187], v225 offset:5120
	ds_read_b128 v[188:191], v225 offset:6144
	ds_read_b128 v[192:195], v225 offset:7168
	global_load_lds_dwordx4 v[196:197], off
	v_lshl_add_u64 v[196:197], s[44:45], 0, v[150:151]
	s_add_i32 m0, s66, 0xe000
	s_nop 0
	global_load_lds_dwordx4 v[196:197], off
	s_waitcnt lgkmcnt(8)
	s_barrier
	s_waitcnt lgkmcnt(0)
	v_mfma_f32_16x16x32_bf16 v[126:129], v[130:133], v[164:167], 0
	v_mfma_f32_16x16x32_bf16 v[122:125], v[156:159], v[164:167], 0
	v_mfma_f32_16x16x32_bf16 v[110:113], v[130:133], v[172:175], 0
	v_mfma_f32_16x16x32_bf16 v[106:109], v[156:159], v[172:175], 0
	v_mfma_f32_16x16x32_bf16 v[94:97], v[130:133], v[180:183], 0
	v_mfma_f32_16x16x32_bf16 v[90:93], v[156:159], v[180:183], 0
	v_mfma_f32_16x16x32_bf16 v[78:81], v[130:133], v[188:191], 0
	v_mfma_f32_16x16x32_bf16 v[74:77], v[156:159], v[188:191], 0
	v_mfma_f32_16x16x32_bf16 v[126:129], v[152:155], v[168:171], v[126:129]
	v_mfma_f32_16x16x32_bf16 v[122:125], v[160:163], v[168:171], v[122:125]
	v_mfma_f32_16x16x32_bf16 v[110:113], v[152:155], v[176:179], v[110:113]
	v_mfma_f32_16x16x32_bf16 v[106:109], v[160:163], v[176:179], v[106:109]
	v_mfma_f32_16x16x32_bf16 v[94:97], v[152:155], v[184:187], v[94:97]
	v_mfma_f32_16x16x32_bf16 v[90:93], v[160:163], v[184:187], v[90:93]
	v_mfma_f32_16x16x32_bf16 v[78:81], v[152:155], v[192:195], v[78:81]
	v_mfma_f32_16x16x32_bf16 v[74:77], v[160:163], v[192:195], v[74:77]
	s_barrier
	s_add_i32 s83, 0, 0x14000
	s_add_i32 s82, s82, s65
	v_add_u32_e32 v234, s83, v223
	v_lshl_add_u64 v[238:239], s[58:59], 0, v[0:1]
	s_mov_b32 m0, s82
	ds_read_b128 v[196:199], v234
	ds_read_b128 v[226:229], v234 offset:1024
	ds_read_b128 v[230:233], v234 offset:2048
	ds_read_b128 v[234:237], v234 offset:3072
	global_load_lds_dwordx4 v[238:239], off
	v_lshl_add_u64 v[240:241], s[58:59], 0, v[142:143]
	s_add_i32 m0, s82, 0x2000
	s_nop 0
	global_load_lds_dwordx4 v[240:241], off
	s_barrier
	s_waitcnt lgkmcnt(0)
	v_mfma_f32_16x16x32_bf16 v[118:121], v[196:199], v[164:167], 0
	v_mfma_f32_16x16x32_bf16 v[114:117], v[230:233], v[164:167], 0
	v_mfma_f32_16x16x32_bf16 v[102:105], v[196:199], v[172:175], 0
	v_mfma_f32_16x16x32_bf16 v[98:101], v[230:233], v[172:175], 0
	v_mfma_f32_16x16x32_bf16 v[86:89], v[196:199], v[180:183], 0
	v_mfma_f32_16x16x32_bf16 v[82:85], v[230:233], v[180:183], 0
	v_mfma_f32_16x16x32_bf16 v[70:73], v[196:199], v[188:191], 0
	v_mfma_f32_16x16x32_bf16 v[66:69], v[230:233], v[188:191], 0
	v_mfma_f32_16x16x32_bf16 v[118:121], v[226:229], v[168:171], v[118:121]
	v_mfma_f32_16x16x32_bf16 v[114:117], v[234:237], v[168:171], v[114:117]
	v_mfma_f32_16x16x32_bf16 v[102:105], v[226:229], v[176:179], v[102:105]
	v_mfma_f32_16x16x32_bf16 v[98:101], v[234:237], v[176:179], v[98:101]
	v_mfma_f32_16x16x32_bf16 v[86:89], v[226:229], v[184:187], v[86:89]
	v_mfma_f32_16x16x32_bf16 v[82:85], v[234:237], v[184:187], v[82:85]
	v_mfma_f32_16x16x32_bf16 v[70:73], v[226:229], v[192:195], v[70:73]
	v_mfma_f32_16x16x32_bf16 v[66:69], v[234:237], v[192:195], v[66:69]
	s_mov_b32 m0, s66
	v_lshl_add_u64 v[242:243], s[56:57], 0, v[146:147]
	s_barrier
	ds_read_b128 v[164:167], v225 offset:16384
	ds_read_b128 v[168:171], v225 offset:17408
	ds_read_b128 v[172:175], v225 offset:18432
	ds_read_b128 v[176:179], v225 offset:19456
	ds_read_b128 v[180:183], v225 offset:20480
	ds_read_b128 v[184:187], v225 offset:21504
	ds_read_b128 v[188:191], v225 offset:22528
	ds_read_b128 v[192:195], v225 offset:23552
	global_load_lds_dwordx4 v[242:243], off
	v_lshl_add_u64 v[244:245], s[56:57], 0, v[144:145]
	s_mov_b32 m0, s67
	s_nop 0
	global_load_lds_dwordx4 v[244:245], off
	s_barrier
	s_waitcnt lgkmcnt(0)
	v_mfma_f32_16x16x32_bf16 v[62:65], v[130:133], v[164:167], 0
	v_mfma_f32_16x16x32_bf16 v[58:61], v[156:159], v[164:167], 0
	v_mfma_f32_16x16x32_bf16 v[46:49], v[130:133], v[172:175], 0
	v_mfma_f32_16x16x32_bf16 v[42:45], v[156:159], v[172:175], 0
	v_mfma_f32_16x16x32_bf16 v[30:33], v[130:133], v[180:183], 0
	v_mfma_f32_16x16x32_bf16 v[26:29], v[156:159], v[180:183], 0
	v_mfma_f32_16x16x32_bf16 v[14:17], v[130:133], v[188:191], 0
	v_mfma_f32_16x16x32_bf16 v[10:13], v[156:159], v[188:191], 0
	v_mfma_f32_16x16x32_bf16 v[62:65], v[152:155], v[168:171], v[62:65]
	v_mfma_f32_16x16x32_bf16 v[58:61], v[160:163], v[168:171], v[58:61]
	v_mfma_f32_16x16x32_bf16 v[46:49], v[152:155], v[176:179], v[46:49]
	v_mfma_f32_16x16x32_bf16 v[42:45], v[160:163], v[176:179], v[42:45]
	v_mfma_f32_16x16x32_bf16 v[30:33], v[152:155], v[184:187], v[30:33]
	v_mfma_f32_16x16x32_bf16 v[26:29], v[160:163], v[184:187], v[26:29]
	v_mfma_f32_16x16x32_bf16 v[14:17], v[152:155], v[192:195], v[14:17]
	v_mfma_f32_16x16x32_bf16 v[10:13], v[160:163], v[192:195], v[10:13]
	s_barrier
; #define PG8_STAGE(bufoff, gbase, voff) do { _Pragma("unroll") for (int _i = 0; _i < 2; ++_i) \
;     __builtin_amdgcn_global_load_lds((const unsigned*)((const char*)(gbase) + (voff)[_i]), (PG8_LAS unsigned*)(lds + (bufoff) + ldsw + _i * 8192), 16, 0, 0); } while (0)
; #define PG8_LDA(dst, b, h) do { _Pragma("unroll") for (int m = 0; m < 4; ++m) _Pragma("unroll") for (int k = 0; k < 2; ++k) dst[m][k] = *(const PG8_LAS bf16x8*)(lds + PG8_SA(b, h) + aoff + m * 2048 + k * 1024); } while (0)
; #define PG8_LDB(dst, b, h) do { _Pragma("unroll") for (int n = 0; n < 2; ++n) _Pragma("unroll") for (int k = 0; k < 2; ++k) dst[n][k] = *(const PG8_LAS bf16x8*)(lds + PG8_SB(b, h) + boff + n * 2048 + k * 1024); } while (0)
; #define PG8_MMA(ai, bj, At, Bt) do { __builtin_amdgcn_s_setprio(1); _Pragma("unroll") for (int m = 0; m < 4; ++m) _Pragma("unroll") for (int n = 0; n < 2; ++n) _Pragma("unroll") for (int k = 0; k < 2; ++k) \
;     acc[ai][bj][m][n] = __builtin_amdgcn_mfma_f32_16x16x32_bf16(Bt[n][k], At[m][k], acc[ai][bj][m][n], 0, 0, 0); __builtin_amdgcn_s_setprio(0); } while (0)
; #define PG8_WAIT_V(n) asm volatile("s_waitcnt vmcnt(" #n ")" ::: "memory")
; #define PG8_WAIT_L(n) asm volatile("s_waitcnt lgkmcnt(" #n ")" ::: "memory")
; #define PG8_BAR __builtin_amdgcn_s_barrier()
; #define PG8_SCHED __builtin_amdgcn_sched_barrier(0)
; template <class Epi>
; DI void gemm_phase(PG8_LAS unsigned char* lds, const Gemm g, const StaticOrder& S, const Epi& E) {
;     ...
;       PG8_STAGE(PG8_SB(0, 1), b2 + hstepB, voffB);
;       PG8_WAIT_V(6); PG8_BAR; PG8_MMA(1, 1, At, B1); PG8_BAR;
;       PG8_LDB(B0, 1, 0); PG8_SCHED; PG8_LDA(At, 1, 0); PG8_STAGE(PG8_SA(0, 1), a2 + hstepA, voffA);
;       PG8_WAIT_L(8); PG8_BAR; PG8_WAIT_L(0); PG8_MMA(0, 0, At, B0); PG8_BAR; PG8_SCHED;
;       PG8_LDB(B1, 1, 1); PG8_STAGE(PG8_SB(1, 0), b3, voffB);
;       PG8_BAR; PG8_WAIT_L(0); PG8_MMA(0, 1, At, B1); PG8_BAR;
;       PG8_LDA(At, 1, 1); PG8_STAGE(PG8_SA(1, 0), a3, voffA);
	s_add_u32 s58, s58, s62
	s_addc_u32 s59, s59, 0
	s_add_i32 s82, s83, s65
	v_lshl_add_u64 v[246:247], s[58:59], 0, v[0:1]
	s_mov_b32 m0, s82
	v_lshl_add_u64 v[248:249], s[58:59], 0, v[142:143]
	global_load_lds_dwordx4 v[246:247], off
	s_add_i32 m0, s82, 0x2000
	s_nop 0
	global_load_lds_dwordx4 v[248:249], off
	s_waitcnt vmcnt(6)
	s_barrier
	v_mfma_f32_16x16x32_bf16 v[54:57], v[196:199], v[164:167], 0
	v_mfma_f32_16x16x32_bf16 v[50:53], v[230:233], v[164:167], 0
	v_mfma_f32_16x16x32_bf16 v[38:41], v[196:199], v[172:175], 0
	v_mfma_f32_16x16x32_bf16 v[34:37], v[230:233], v[172:175], 0
	v_mfma_f32_16x16x32_bf16 v[22:25], v[196:199], v[180:183], 0
	v_mfma_f32_16x16x32_bf16 v[18:21], v[230:233], v[180:183], 0
	v_mfma_f32_16x16x32_bf16 v[6:9], v[196:199], v[188:191], 0
	v_mfma_f32_16x16x32_bf16 v[2:5], v[230:233], v[188:191], 0
	v_mfma_f32_16x16x32_bf16 v[54:57], v[226:229], v[168:171], v[54:57]
	v_mfma_f32_16x16x32_bf16 v[50:53], v[234:237], v[168:171], v[50:53]
	v_mfma_f32_16x16x32_bf16 v[38:41], v[226:229], v[176:179], v[38:41]
	v_mfma_f32_16x16x32_bf16 v[34:37], v[234:237], v[176:179], v[34:37]
	v_mfma_f32_16x16x32_bf16 v[22:25], v[226:229], v[184:187], v[22:25]
	v_mfma_f32_16x16x32_bf16 v[18:21], v[234:237], v[184:187], v[18:21]
	v_mfma_f32_16x16x32_bf16 v[6:9], v[226:229], v[192:195], v[6:9]
	v_mfma_f32_16x16x32_bf16 v[2:5], v[234:237], v[192:195], v[2:5]
	s_add_i32 s58, 0, 0x18000
	v_add_u32_e32 v160, s58, v223
	s_barrier
	ds_read_b128 v[130:133], v160
	ds_read_b128 v[152:155], v160 offset:1024
	ds_read_b128 v[156:159], v160 offset:2048
	ds_read_b128 v[160:163], v160 offset:3072
	s_add_u32 s56, s56, s50
	s_addc_u32 s57, s57, 0
	s_mov_b32 m0, s68
	v_lshl_add_u64 v[196:197], s[56:57], 0, v[146:147]
	ds_read_b128 v[164:167], v225 offset:32768
	ds_read_b128 v[168:171], v225 offset:33792
	ds_read_b128 v[172:175], v225 offset:34816
	ds_read_b128 v[176:179], v225 offset:35840
	ds_read_b128 v[180:183], v225 offset:36864
	ds_read_b128 v[184:187], v225 offset:37888
	ds_read_b128 v[188:191], v225 offset:38912
	ds_read_b128 v[192:195], v225 offset:39936
	global_load_lds_dwordx4 v[196:197], off
	v_lshl_add_u64 v[196:197], s[56:57], 0, v[144:145]
	s_mov_b32 m0, s69
	s_nop 0
	global_load_lds_dwordx4 v[196:197], off
	s_waitcnt lgkmcnt(8)
	s_barrier
	s_waitcnt lgkmcnt(0)
	v_mfma_f32_16x16x32_bf16 v[126:129], v[130:133], v[164:167], v[126:129]
	v_mfma_f32_16x16x32_bf16 v[122:125], v[156:159], v[164:167], v[122:125]
	v_mfma_f32_16x16x32_bf16 v[110:113], v[130:133], v[172:175], v[110:113]
	v_mfma_f32_16x16x32_bf16 v[106:109], v[156:159], v[172:175], v[106:109]
	v_mfma_f32_16x16x32_bf16 v[94:97], v[130:133], v[180:183], v[94:97]
	v_mfma_f32_16x16x32_bf16 v[90:93], v[156:159], v[180:183], v[90:93]
	v_mfma_f32_16x16x32_bf16 v[78:81], v[130:133], v[188:191], v[78:81]
	v_mfma_f32_16x16x32_bf16 v[74:77], v[156:159], v[188:191], v[74:77]
	v_mfma_f32_16x16x32_bf16 v[126:129], v[152:155], v[168:171], v[126:129]
	v_mfma_f32_16x16x32_bf16 v[122:125], v[160:163], v[168:171], v[122:125]
	v_mfma_f32_16x16x32_bf16 v[110:113], v[152:155], v[176:179], v[110:113]
	v_mfma_f32_16x16x32_bf16 v[106:109], v[160:163], v[176:179], v[106:109]
	v_mfma_f32_16x16x32_bf16 v[94:97], v[152:155], v[184:187], v[94:97]
	v_mfma_f32_16x16x32_bf16 v[90:93], v[160:163], v[184:187], v[90:93]
	v_mfma_f32_16x16x32_bf16 v[78:81], v[152:155], v[192:195], v[78:81]
	v_mfma_f32_16x16x32_bf16 v[74:77], v[160:163], v[192:195], v[74:77]
	s_barrier
	s_add_i32 s56, 0, 0x1c000
	s_add_i32 s57, s58, s65
	v_add_u32_e32 v234, s56, v223
	v_lshl_add_u64 v[238:239], v[238:239], 0, s[86:87]
	s_mov_b32 m0, s57
	ds_read_b128 v[196:199], v234
	ds_read_b128 v[226:229], v234 offset:1024
	ds_read_b128 v[230:233], v234 offset:2048
	ds_read_b128 v[234:237], v234 offset:3072
	global_load_lds_dwordx4 v[238:239], off
	v_lshl_add_u64 v[238:239], v[240:241], 0, s[86:87]
	s_add_i32 m0, s57, 0x2000
	s_nop 0
	global_load_lds_dwordx4 v[238:239], off
	s_barrier
	s_waitcnt lgkmcnt(0)
	v_mfma_f32_16x16x32_bf16 v[118:121], v[196:199], v[164:167], v[118:121]
	v_mfma_f32_16x16x32_bf16 v[114:117], v[230:233], v[164:167], v[114:117]
	v_mfma_f32_16x16x32_bf16 v[102:105], v[196:199], v[172:175], v[102:105]
	v_mfma_f32_16x16x32_bf16 v[98:101], v[230:233], v[172:175], v[98:101]
	v_mfma_f32_16x16x32_bf16 v[86:89], v[196:199], v[180:183], v[86:89]
	v_mfma_f32_16x16x32_bf16 v[82:85], v[230:233], v[180:183], v[82:85]
	v_mfma_f32_16x16x32_bf16 v[70:73], v[196:199], v[188:191], v[70:73]
	v_mfma_f32_16x16x32_bf16 v[66:69], v[230:233], v[188:191], v[66:69]
	v_mfma_f32_16x16x32_bf16 v[118:121], v[226:229], v[168:171], v[118:121]
	v_mfma_f32_16x16x32_bf16 v[114:117], v[234:237], v[168:171], v[114:117]
	v_mfma_f32_16x16x32_bf16 v[102:105], v[226:229], v[176:179], v[102:105]
	v_mfma_f32_16x16x32_bf16 v[98:101], v[234:237], v[176:179], v[98:101]
	v_mfma_f32_16x16x32_bf16 v[86:89], v[226:229], v[184:187], v[86:89]
	v_mfma_f32_16x16x32_bf16 v[82:85], v[234:237], v[184:187], v[82:85]
	v_mfma_f32_16x16x32_bf16 v[70:73], v[226:229], v[192:195], v[70:73]
	v_mfma_f32_16x16x32_bf16 v[66:69], v[234:237], v[192:195], v[66:69]
	s_mov_b32 m0, s72
	v_lshl_add_u64 v[238:239], v[242:243], 0, s[86:87]
	s_barrier
	ds_read_b128 v[164:167], v225 offset:49152
	ds_read_b128 v[168:171], v225 offset:50176
	ds_read_b128 v[172:175], v225 offset:51200
	ds_read_b128 v[176:179], v225 offset:52224
	ds_read_b128 v[180:183], v225 offset:53248
	ds_read_b128 v[184:187], v225 offset:54272
	ds_read_b128 v[188:191], v225 offset:55296
	ds_read_b128 v[192:195], v225 offset:56320
	global_load_lds_dwordx4 v[238:239], off
	v_lshl_add_u64 v[238:239], v[244:245], 0, s[86:87]
	s_mov_b32 m0, s73
	s_nop 0
	global_load_lds_dwordx4 v[238:239], off
	s_barrier
; #define PG8_STAGE(bufoff, gbase, voff) do { _Pragma("unroll") for (int _i = 0; _i < 2; ++_i) \
;     __builtin_amdgcn_global_load_lds((const unsigned*)((const char*)(gbase) + (voff)[_i]), (PG8_LAS unsigned*)(lds + (bufoff) + ldsw + _i * 8192), 16, 0, 0); } while (0)
; #define PG8_LDA(dst, b, h) do { _Pragma("unroll") for (int m = 0; m < 4; ++m) _Pragma("unroll") for (int k = 0; k < 2; ++k) dst[m][k] = *(const PG8_LAS bf16x8*)(lds + PG8_SA(b, h) + aoff + m * 2048 + k * 1024); } while (0)
; #define PG8_LDB(dst, b, h) do { _Pragma("unroll") for (int n = 0; n < 2; ++n) _Pragma("unroll") for (int k = 0; k < 2; ++k) dst[n][k] = *(const PG8_LAS bf16x8*)(lds + PG8_SB(b, h) + boff + n * 2048 + k * 1024); } while (0)
; #define PG8_MMA(ai, bj, At, Bt) do { __builtin_amdgcn_s_setprio(1); _Pragma("unroll") for (int m = 0; m < 4; ++m) _Pragma("unroll") for (int n = 0; n < 2; ++n) _Pragma("unroll") for (int k = 0; k < 2; ++k) \
;     acc[ai][bj][m][n] = __builtin_amdgcn_mfma_f32_16x16x32_bf16(Bt[n][k], At[m][k], acc[ai][bj][m][n], 0, 0, 0); __builtin_amdgcn_s_setprio(0); } while (0)
; #define PG8_WAIT_V(n) asm volatile("s_waitcnt vmcnt(" #n ")" ::: "memory")
; #define PG8_WAIT_L(n) asm volatile("s_waitcnt lgkmcnt(" #n ")" ::: "memory")
; #define PG8_BAR __builtin_amdgcn_s_barrier()
; #define PG8_SCHED __builtin_amdgcn_sched_barrier(0)
; template <class Epi>
; DI void gemm_phase(PG8_LAS unsigned char* lds, const Gemm g, const StaticOrder& S, const Epi& E) {
;     ...
;     for (int t = 0; t < nt; t += 2) {
;       const bool last = (t == nt - 2);
;       const char* a1 = cA + (size_t)(t + 1) * kstep;
;       const char* a2 = last ? nA : cA + (size_t)(t + 2) * kstep; const char* b2 = last ? nB : cB + (size_t)(t + 2) * kstep;
;       const char* a3 = a2 + kstep; const char* b3 = b2 + kstep;
;       PG8_LDB(B0, 0, 0); PG8_SCHED; PG8_LDA(At, 0, 0); PG8_STAGE(PG8_SA(1, 1), a1 + hstepA, voffA);
;       PG8_WAIT_L(8); PG8_BAR; PG8_WAIT_L(0); PG8_MMA(0, 0, At, B0); PG8_BAR; PG8_SCHED;
;       PG8_LDB(B1, 0, 1); PG8_STAGE(PG8_SB(0, 0), b2, voffB);
;     ...
;       PG8_BAR; PG8_WAIT_L(0); PG8_MMA(1, 0, At, B0); PG8_BAR; PG8_SCHED;
;       PG8_STAGE(PG8_SB(1, 1), b3 + hstepB, voffB);
;       PG8_WAIT_V(6); PG8_BAR; PG8_MMA(1, 1, At, B1); PG8_BAR;
	s_waitcnt lgkmcnt(0)
	v_mfma_f32_16x16x32_bf16 v[62:65], v[130:133], v[164:167], v[62:65]
	v_mfma_f32_16x16x32_bf16 v[58:61], v[156:159], v[164:167], v[58:61]
	v_mfma_f32_16x16x32_bf16 v[46:49], v[130:133], v[172:175], v[46:49]
	v_mfma_f32_16x16x32_bf16 v[42:45], v[156:159], v[172:175], v[42:45]
	v_mfma_f32_16x16x32_bf16 v[30:33], v[130:133], v[180:183], v[30:33]
	v_mfma_f32_16x16x32_bf16 v[26:29], v[156:159], v[180:183], v[26:29]
	v_mfma_f32_16x16x32_bf16 v[14:17], v[130:133], v[188:191], v[14:17]
	v_mfma_f32_16x16x32_bf16 v[10:13], v[156:159], v[188:191], v[10:13]
	v_mfma_f32_16x16x32_bf16 v[62:65], v[152:155], v[168:171], v[62:65]
	v_mfma_f32_16x16x32_bf16 v[58:61], v[160:163], v[168:171], v[58:61]
	v_mfma_f32_16x16x32_bf16 v[46:49], v[152:155], v[176:179], v[46:49]
	v_mfma_f32_16x16x32_bf16 v[42:45], v[160:163], v[176:179], v[42:45]
	v_mfma_f32_16x16x32_bf16 v[30:33], v[152:155], v[184:187], v[30:33]
	v_mfma_f32_16x16x32_bf16 v[26:29], v[160:163], v[184:187], v[26:29]
	v_mfma_f32_16x16x32_bf16 v[14:17], v[152:155], v[192:195], v[14:17]
	v_mfma_f32_16x16x32_bf16 v[10:13], v[160:163], v[192:195], v[10:13]
	s_barrier
	s_add_i32 s56, s56, s65
	v_lshl_add_u64 v[130:131], v[246:247], 0, s[86:87]
	s_mov_b32 m0, s56
	s_nop 0
	global_load_lds_dwordx4 v[130:131], off
	v_lshl_add_u64 v[130:131], v[248:249], 0, s[86:87]
	s_add_i32 m0, s56, 0x2000
	s_nop 0
	global_load_lds_dwordx4 v[130:131], off
	s_waitcnt vmcnt(6)
	s_barrier
	v_mfma_f32_16x16x32_bf16 v[54:57], v[196:199], v[164:167], v[54:57]
	v_mfma_f32_16x16x32_bf16 v[50:53], v[230:233], v[164:167], v[50:53]
	v_mfma_f32_16x16x32_bf16 v[38:41], v[196:199], v[172:175], v[38:41]
	v_mfma_f32_16x16x32_bf16 v[34:37], v[230:233], v[172:175], v[34:37]
	v_mfma_f32_16x16x32_bf16 v[22:25], v[196:199], v[180:183], v[22:25]
	v_mfma_f32_16x16x32_bf16 v[18:21], v[230:233], v[180:183], v[18:21]
	v_mfma_f32_16x16x32_bf16 v[6:9], v[196:199], v[188:191], v[6:9]
	v_mfma_f32_16x16x32_bf16 v[2:5], v[230:233], v[188:191], v[2:5]
	v_mfma_f32_16x16x32_bf16 v[54:57], v[226:229], v[168:171], v[54:57]
	v_mfma_f32_16x16x32_bf16 v[50:53], v[234:237], v[168:171], v[50:53]
	v_mfma_f32_16x16x32_bf16 v[38:41], v[226:229], v[176:179], v[38:41]
	v_mfma_f32_16x16x32_bf16 v[34:37], v[234:237], v[176:179], v[34:37]
	v_mfma_f32_16x16x32_bf16 v[22:25], v[226:229], v[184:187], v[22:25]
	v_mfma_f32_16x16x32_bf16 v[18:21], v[234:237], v[184:187], v[18:21]
	v_mfma_f32_16x16x32_bf16 v[6:9], v[226:229], v[192:195], v[6:9]
	v_mfma_f32_16x16x32_bf16 v[2:5], v[234:237], v[192:195], v[2:5]
	s_add_u32 s44, s44, 0x100
	s_addc_u32 s45, s45, 0
	s_add_u32 s79, s79, 0x100
	s_addc_u32 s80, s80, 0
	s_cmp_ge_u32 s81, s71
	s_mov_b32 s56, s81
	s_barrier
	s_cbranch_scc1 .Lpeel_exit_1
.LBB0_835:
	s_add_i32 s81, s56, 2
	s_add_u32 s58, s44, 0x80
	s_addc_u32 s57, s45, 0
	s_add_i32 s82, 0, 0x10000
	v_add_u32_e32 v160, s82, v223
	ds_read_b128 v[130:133], v160
	ds_read_b128 v[152:155], v160 offset:1024
	ds_read_b128 v[156:159], v160 offset:2048
	ds_read_b128 v[160:163], v160 offset:3072
	s_cmp_eq_u32 s75, s56
	s_cselect_b32 s56, s0, s58
	s_cselect_b32 s57, s1, s57
	s_cselect_b32 s59, s55, s80
	s_cselect_b32 s58, s54, s79
	v_lshl_add_u64 v[196:197], s[44:45], 0, v[148:149]
	s_add_i32 m0, s66, 0xc000
	ds_read_b128 v[164:167], v225
	ds_read_b128 v[168:171], v225 offset:1024
	ds_read_b128 v[172:175], v225 offset:2048
	ds_read_b128 v[176:179], v225 offset:3072
	ds_read_b128 v[180:183], v225 offset:4096
	ds_read_b128 v[184:187], v225 offset:5120
	ds_read_b128 v[188:191], v225 offset:6144
	ds_read_b128 v[192:195], v225 offset:7168
	global_load_lds_dwordx4 v[196:197], off
	v_lshl_add_u64 v[196:197], s[44:45], 0, v[150:151]
	s_add_i32 m0, s66, 0xe000
	s_nop 0
	global_load_lds_dwordx4 v[196:197], off
	s_waitcnt lgkmcnt(8)
	s_barrier
	s_waitcnt lgkmcnt(0)
	v_mfma_f32_16x16x32_bf16 v[126:129], v[130:133], v[164:167], v[126:129]
	v_mfma_f32_16x16x32_bf16 v[122:125], v[156:159], v[164:167], v[122:125]
	v_mfma_f32_16x16x32_bf16 v[110:113], v[130:133], v[172:175], v[110:113]
	v_mfma_f32_16x16x32_bf16 v[106:109], v[156:159], v[172:175], v[106:109]
	v_mfma_f32_16x16x32_bf16 v[94:97], v[130:133], v[180:183], v[94:97]
	v_mfma_f32_16x16x32_bf16 v[90:93], v[156:159], v[180:183], v[90:93]
	v_mfma_f32_16x16x32_bf16 v[78:81], v[130:133], v[188:191], v[78:81]
	v_mfma_f32_16x16x32_bf16 v[74:77], v[156:159], v[188:191], v[74:77]
	v_mfma_f32_16x16x32_bf16 v[126:129], v[152:155], v[168:171], v[126:129]
	v_mfma_f32_16x16x32_bf16 v[122:125], v[160:163], v[168:171], v[122:125]
	v_mfma_f32_16x16x32_bf16 v[110:113], v[152:155], v[176:179], v[110:113]
	v_mfma_f32_16x16x32_bf16 v[106:109], v[160:163], v[176:179], v[106:109]
	v_mfma_f32_16x16x32_bf16 v[94:97], v[152:155], v[184:187], v[94:97]
	v_mfma_f32_16x16x32_bf16 v[90:93], v[160:163], v[184:187], v[90:93]
	v_mfma_f32_16x16x32_bf16 v[78:81], v[152:155], v[192:195], v[78:81]
	v_mfma_f32_16x16x32_bf16 v[74:77], v[160:163], v[192:195], v[74:77]
	s_barrier
	s_add_i32 s83, 0, 0x14000
	s_add_i32 s82, s82, s65
	v_add_u32_e32 v234, s83, v223
	v_lshl_add_u64 v[238:239], s[58:59], 0, v[0:1]
	s_mov_b32 m0, s82
	ds_read_b128 v[196:199], v234
	ds_read_b128 v[226:229], v234 offset:1024
	ds_read_b128 v[230:233], v234 offset:2048
	ds_read_b128 v[234:237], v234 offset:3072
	global_load_lds_dwordx4 v[238:239], off
	v_lshl_add_u64 v[240:241], s[58:59], 0, v[142:143]
	s_add_i32 m0, s82, 0x2000
	s_nop 0
	global_load_lds_dwordx4 v[240:241], off
	s_barrier
; #define PG8_STAGE(bufoff, gbase, voff) do { _Pragma("unroll") for (int _i = 0; _i < 2; ++_i) \
;     __builtin_amdgcn_global_load_lds((const unsigned*)((const char*)(gbase) + (voff)[_i]), (PG8_LAS unsigned*)(lds + (bufoff) + ldsw + _i * 8192), 16, 0, 0); } while (0)
; #define PG8_LDA(dst, b, h) do { _Pragma("unroll") for (int m = 0; m < 4; ++m) _Pragma("unroll") for (int k = 0; k < 2; ++k) dst[m][k] = *(const PG8_LAS bf16x8*)(lds + PG8_SA(b, h) + aoff + m * 2048 + k * 1024); } while (0)
; #define PG8_LDB(dst, b, h) do { _Pragma("unroll") for (int n = 0; n < 2; ++n) _Pragma("unroll") for (int k = 0; k < 2; ++k) dst[n][k] = *(const PG8_LAS bf16x8*)(lds + PG8_SB(b, h) + boff + n * 2048 + k * 1024); } while (0)
; #define PG8_MMA(ai, bj, At, Bt) do { __builtin_amdgcn_s_setprio(1); _Pragma("unroll") for (int m = 0; m < 4; ++m) _Pragma("unroll") for (int n = 0; n < 2; ++n) _Pragma("unroll") for (int k = 0; k < 2; ++k) \
;     acc[ai][bj][m][n] = __builtin_amdgcn_mfma_f32_16x16x32_bf16(Bt[n][k], At[m][k], acc[ai][bj][m][n], 0, 0, 0); __builtin_amdgcn_s_setprio(0); } while (0)
; #define PG8_WAIT_V(n) asm volatile("s_waitcnt vmcnt(" #n ")" ::: "memory")
; #define PG8_WAIT_L(n) asm volatile("s_waitcnt lgkmcnt(" #n ")" ::: "memory")
; #define PG8_BAR __builtin_amdgcn_s_barrier()
; #define PG8_SCHED __builtin_amdgcn_sched_barrier(0)
; template <class Epi>
; DI void gemm_phase(PG8_LAS unsigned char* lds, const Gemm g, const StaticOrder& S, const Epi& E) {
;     ...
;       PG8_BAR; PG8_WAIT_L(0); PG8_MMA(0, 1, At, B1); PG8_BAR;
;       PG8_LDA(At, 0, 1); PG8_STAGE(PG8_SA(0, 0), a2, voffA);
;       PG8_BAR; PG8_WAIT_L(0); PG8_MMA(1, 0, At, B0); PG8_BAR; PG8_SCHED;
;       PG8_STAGE(PG8_SB(0, 1), b2 + hstepB, voffB);
;       PG8_WAIT_V(6); PG8_BAR; PG8_MMA(1, 1, At, B1); PG8_BAR;
;       PG8_LDB(B0, 1, 0); PG8_SCHED; PG8_LDA(At, 1, 0); PG8_STAGE(PG8_SA(0, 1), a2 + hstepA, voffA);
;       PG8_WAIT_L(8); PG8_BAR; PG8_WAIT_L(0); PG8_MMA(0, 0, At, B0); PG8_BAR; PG8_SCHED;
	s_waitcnt lgkmcnt(0)
	v_mfma_f32_16x16x32_bf16 v[118:121], v[196:199], v[164:167], v[118:121]
	v_mfma_f32_16x16x32_bf16 v[114:117], v[230:233], v[164:167], v[114:117]
	v_mfma_f32_16x16x32_bf16 v[102:105], v[196:199], v[172:175], v[102:105]
	v_mfma_f32_16x16x32_bf16 v[98:101], v[230:233], v[172:175], v[98:101]
	v_mfma_f32_16x16x32_bf16 v[86:89], v[196:199], v[180:183], v[86:89]
	v_mfma_f32_16x16x32_bf16 v[82:85], v[230:233], v[180:183], v[82:85]
	v_mfma_f32_16x16x32_bf16 v[70:73], v[196:199], v[188:191], v[70:73]
	v_mfma_f32_16x16x32_bf16 v[66:69], v[230:233], v[188:191], v[66:69]
	v_mfma_f32_16x16x32_bf16 v[118:121], v[226:229], v[168:171], v[118:121]
	v_mfma_f32_16x16x32_bf16 v[114:117], v[234:237], v[168:171], v[114:117]
	v_mfma_f32_16x16x32_bf16 v[102:105], v[226:229], v[176:179], v[102:105]
	v_mfma_f32_16x16x32_bf16 v[98:101], v[234:237], v[176:179], v[98:101]
	v_mfma_f32_16x16x32_bf16 v[86:89], v[226:229], v[184:187], v[86:89]
	v_mfma_f32_16x16x32_bf16 v[82:85], v[234:237], v[184:187], v[82:85]
	v_mfma_f32_16x16x32_bf16 v[70:73], v[226:229], v[192:195], v[70:73]
	v_mfma_f32_16x16x32_bf16 v[66:69], v[234:237], v[192:195], v[66:69]
	s_mov_b32 m0, s66
	v_lshl_add_u64 v[242:243], s[56:57], 0, v[146:147]
	s_barrier
	ds_read_b128 v[164:167], v225 offset:16384
	ds_read_b128 v[168:171], v225 offset:17408
	ds_read_b128 v[172:175], v225 offset:18432
	ds_read_b128 v[176:179], v225 offset:19456
	ds_read_b128 v[180:183], v225 offset:20480
	ds_read_b128 v[184:187], v225 offset:21504
	ds_read_b128 v[188:191], v225 offset:22528
	ds_read_b128 v[192:195], v225 offset:23552
	global_load_lds_dwordx4 v[242:243], off
	v_lshl_add_u64 v[244:245], s[56:57], 0, v[144:145]
	s_mov_b32 m0, s67
	s_nop 0
	global_load_lds_dwordx4 v[244:245], off
	s_barrier
	s_waitcnt lgkmcnt(0)
	v_mfma_f32_16x16x32_bf16 v[62:65], v[130:133], v[164:167], v[62:65]
	v_mfma_f32_16x16x32_bf16 v[58:61], v[156:159], v[164:167], v[58:61]
	v_mfma_f32_16x16x32_bf16 v[46:49], v[130:133], v[172:175], v[46:49]
	v_mfma_f32_16x16x32_bf16 v[42:45], v[156:159], v[172:175], v[42:45]
	v_mfma_f32_16x16x32_bf16 v[30:33], v[130:133], v[180:183], v[30:33]
	v_mfma_f32_16x16x32_bf16 v[26:29], v[156:159], v[180:183], v[26:29]
	v_mfma_f32_16x16x32_bf16 v[14:17], v[130:133], v[188:191], v[14:17]
	v_mfma_f32_16x16x32_bf16 v[10:13], v[156:159], v[188:191], v[10:13]
	v_mfma_f32_16x16x32_bf16 v[62:65], v[152:155], v[168:171], v[62:65]
	v_mfma_f32_16x16x32_bf16 v[58:61], v[160:163], v[168:171], v[58:61]
	v_mfma_f32_16x16x32_bf16 v[46:49], v[152:155], v[176:179], v[46:49]
	v_mfma_f32_16x16x32_bf16 v[42:45], v[160:163], v[176:179], v[42:45]
	v_mfma_f32_16x16x32_bf16 v[30:33], v[152:155], v[184:187], v[30:33]
	v_mfma_f32_16x16x32_bf16 v[26:29], v[160:163], v[184:187], v[26:29]
	v_mfma_f32_16x16x32_bf16 v[14:17], v[152:155], v[192:195], v[14:17]
	v_mfma_f32_16x16x32_bf16 v[10:13], v[160:163], v[192:195], v[10:13]
	s_barrier
	s_add_u32 s58, s58, s62
	s_addc_u32 s59, s59, 0
	s_add_i32 s82, s83, s65
	v_lshl_add_u64 v[246:247], s[58:59], 0, v[0:1]
	s_mov_b32 m0, s82
	v_lshl_add_u64 v[248:249], s[58:59], 0, v[142:143]
	global_load_lds_dwordx4 v[246:247], off
	s_add_i32 m0, s82, 0x2000
	s_nop 0
	global_load_lds_dwordx4 v[248:249], off
	s_waitcnt vmcnt(6)
	s_barrier
	v_mfma_f32_16x16x32_bf16 v[54:57], v[196:199], v[164:167], v[54:57]
	v_mfma_f32_16x16x32_bf16 v[50:53], v[230:233], v[164:167], v[50:53]
	v_mfma_f32_16x16x32_bf16 v[38:41], v[196:199], v[172:175], v[38:41]
	v_mfma_f32_16x16x32_bf16 v[34:37], v[230:233], v[172:175], v[34:37]
	v_mfma_f32_16x16x32_bf16 v[22:25], v[196:199], v[180:183], v[22:25]
	v_mfma_f32_16x16x32_bf16 v[18:21], v[230:233], v[180:183], v[18:21]
	v_mfma_f32_16x16x32_bf16 v[6:9], v[196:199], v[188:191], v[6:9]
	v_mfma_f32_16x16x32_bf16 v[2:5], v[230:233], v[188:191], v[2:5]
	v_mfma_f32_16x16x32_bf16 v[54:57], v[226:229], v[168:171], v[54:57]
	v_mfma_f32_16x16x32_bf16 v[50:53], v[234:237], v[168:171], v[50:53]
	v_mfma_f32_16x16x32_bf16 v[38:41], v[226:229], v[176:179], v[38:41]
	v_mfma_f32_16x16x32_bf16 v[34:37], v[234:237], v[176:179], v[34:37]
	v_mfma_f32_16x16x32_bf16 v[22:25], v[226:229], v[184:187], v[22:25]
	v_mfma_f32_16x16x32_bf16 v[18:21], v[234:237], v[184:187], v[18:21]
	v_mfma_f32_16x16x32_bf16 v[6:9], v[226:229], v[192:195], v[6:9]
	v_mfma_f32_16x16x32_bf16 v[2:5], v[234:237], v[192:195], v[2:5]
	s_add_i32 s58, 0, 0x18000
	v_add_u32_e32 v160, s58, v223
	s_barrier
	ds_read_b128 v[130:133], v160
	ds_read_b128 v[152:155], v160 offset:1024
	ds_read_b128 v[156:159], v160 offset:2048
	ds_read_b128 v[160:163], v160 offset:3072
	s_add_u32 s56, s56, s50
	s_addc_u32 s57, s57, 0
	s_mov_b32 m0, s68
	v_lshl_add_u64 v[196:197], s[56:57], 0, v[146:147]
	ds_read_b128 v[164:167], v225 offset:32768
	ds_read_b128 v[168:171], v225 offset:33792
	ds_read_b128 v[172:175], v225 offset:34816
	ds_read_b128 v[176:179], v225 offset:35840
	ds_read_b128 v[180:183], v225 offset:36864
	ds_read_b128 v[184:187], v225 offset:37888
	ds_read_b128 v[188:191], v225 offset:38912
	ds_read_b128 v[192:195], v225 offset:39936
	global_load_lds_dwordx4 v[196:197], off
	v_lshl_add_u64 v[196:197], s[56:57], 0, v[144:145]
	s_mov_b32 m0, s69
	s_nop 0
	global_load_lds_dwordx4 v[196:197], off
	s_waitcnt lgkmcnt(8)
	s_barrier
; #define PG8_STAGE(bufoff, gbase, voff) do { _Pragma("unroll") for (int _i = 0; _i < 2; ++_i) \
;     __builtin_amdgcn_global_load_lds((const unsigned*)((const char*)(gbase) + (voff)[_i]), (PG8_LAS unsigned*)(lds + (bufoff) + ldsw + _i * 8192), 16, 0, 0); } while (0)
; #define PG8_LDA(dst, b, h) do { _Pragma("unroll") for (int m = 0; m < 4; ++m) _Pragma("unroll") for (int k = 0; k < 2; ++k) dst[m][k] = *(const PG8_LAS bf16x8*)(lds + PG8_SA(b, h) + aoff + m * 2048 + k * 1024); } while (0)
; #define PG8_LDB(dst, b, h) do { _Pragma("unroll") for (int n = 0; n < 2; ++n) _Pragma("unroll") for (int k = 0; k < 2; ++k) dst[n][k] = *(const PG8_LAS bf16x8*)(lds + PG8_SB(b, h) + boff + n * 2048 + k * 1024); } while (0)
; #define PG8_MMA(ai, bj, At, Bt) do { __builtin_amdgcn_s_setprio(1); _Pragma("unroll") for (int m = 0; m < 4; ++m) _Pragma("unroll") for (int n = 0; n < 2; ++n) _Pragma("unroll") for (int k = 0; k < 2; ++k) \
;     acc[ai][bj][m][n] = __builtin_amdgcn_mfma_f32_16x16x32_bf16(Bt[n][k], At[m][k], acc[ai][bj][m][n], 0, 0, 0); __builtin_amdgcn_s_setprio(0); } while (0)
; #define PG8_WAIT_V(n) asm volatile("s_waitcnt vmcnt(" #n ")" ::: "memory")
; #define PG8_WAIT_L(n) asm volatile("s_waitcnt lgkmcnt(" #n ")" ::: "memory")
; #define PG8_BAR __builtin_amdgcn_s_barrier()
; #define PG8_SCHED __builtin_amdgcn_sched_barrier(0)
; template <class Epi>
; DI void gemm_phase(PG8_LAS unsigned char* lds, const Gemm g, const StaticOrder& S, const Epi& E) {
;     ...
;       PG8_WAIT_L(8); PG8_BAR; PG8_WAIT_L(0); PG8_MMA(0, 0, At, B0); PG8_BAR; PG8_SCHED;
;       PG8_LDB(B1, 1, 1); PG8_STAGE(PG8_SB(1, 0), b3, voffB);
;       PG8_BAR; PG8_WAIT_L(0); PG8_MMA(0, 1, At, B1); PG8_BAR;
;       PG8_LDA(At, 1, 1); PG8_STAGE(PG8_SA(1, 0), a3, voffA);
;       PG8_BAR; PG8_WAIT_L(0); PG8_MMA(1, 0, At, B0); PG8_BAR; PG8_SCHED;
;       PG8_STAGE(PG8_SB(1, 1), b3 + hstepB, voffB);
;       PG8_WAIT_V(6); PG8_BAR; PG8_MMA(1, 1, At, B1); PG8_BAR;
	s_waitcnt lgkmcnt(0)
	v_mfma_f32_16x16x32_bf16 v[126:129], v[130:133], v[164:167], v[126:129]
	v_mfma_f32_16x16x32_bf16 v[122:125], v[156:159], v[164:167], v[122:125]
	v_mfma_f32_16x16x32_bf16 v[110:113], v[130:133], v[172:175], v[110:113]
	v_mfma_f32_16x16x32_bf16 v[106:109], v[156:159], v[172:175], v[106:109]
	v_mfma_f32_16x16x32_bf16 v[94:97], v[130:133], v[180:183], v[94:97]
	v_mfma_f32_16x16x32_bf16 v[90:93], v[156:159], v[180:183], v[90:93]
	v_mfma_f32_16x16x32_bf16 v[78:81], v[130:133], v[188:191], v[78:81]
	v_mfma_f32_16x16x32_bf16 v[74:77], v[156:159], v[188:191], v[74:77]
	v_mfma_f32_16x16x32_bf16 v[126:129], v[152:155], v[168:171], v[126:129]
	v_mfma_f32_16x16x32_bf16 v[122:125], v[160:163], v[168:171], v[122:125]
	v_mfma_f32_16x16x32_bf16 v[110:113], v[152:155], v[176:179], v[110:113]
	v_mfma_f32_16x16x32_bf16 v[106:109], v[160:163], v[176:179], v[106:109]
	v_mfma_f32_16x16x32_bf16 v[94:97], v[152:155], v[184:187], v[94:97]
	v_mfma_f32_16x16x32_bf16 v[90:93], v[160:163], v[184:187], v[90:93]
	v_mfma_f32_16x16x32_bf16 v[78:81], v[152:155], v[192:195], v[78:81]
	v_mfma_f32_16x16x32_bf16 v[74:77], v[160:163], v[192:195], v[74:77]
	s_barrier
	s_add_i32 s56, 0, 0x1c000
	s_add_i32 s57, s58, s65
	v_add_u32_e32 v234, s56, v223
	v_lshl_add_u64 v[238:239], v[238:239], 0, s[86:87]
	s_mov_b32 m0, s57
	ds_read_b128 v[196:199], v234
	ds_read_b128 v[226:229], v234 offset:1024
	ds_read_b128 v[230:233], v234 offset:2048
	ds_read_b128 v[234:237], v234 offset:3072
	global_load_lds_dwordx4 v[238:239], off
	v_lshl_add_u64 v[238:239], v[240:241], 0, s[86:87]
	s_add_i32 m0, s57, 0x2000
	s_nop 0
	global_load_lds_dwordx4 v[238:239], off
	s_barrier
	s_waitcnt lgkmcnt(0)
	v_mfma_f32_16x16x32_bf16 v[118:121], v[196:199], v[164:167], v[118:121]
	v_mfma_f32_16x16x32_bf16 v[114:117], v[230:233], v[164:167], v[114:117]
	v_mfma_f32_16x16x32_bf16 v[102:105], v[196:199], v[172:175], v[102:105]
	v_mfma_f32_16x16x32_bf16 v[98:101], v[230:233], v[172:175], v[98:101]
	v_mfma_f32_16x16x32_bf16 v[86:89], v[196:199], v[180:183], v[86:89]
	v_mfma_f32_16x16x32_bf16 v[82:85], v[230:233], v[180:183], v[82:85]
	v_mfma_f32_16x16x32_bf16 v[70:73], v[196:199], v[188:191], v[70:73]
	v_mfma_f32_16x16x32_bf16 v[66:69], v[230:233], v[188:191], v[66:69]
	v_mfma_f32_16x16x32_bf16 v[118:121], v[226:229], v[168:171], v[118:121]
	v_mfma_f32_16x16x32_bf16 v[114:117], v[234:237], v[168:171], v[114:117]
	v_mfma_f32_16x16x32_bf16 v[102:105], v[226:229], v[176:179], v[102:105]
	v_mfma_f32_16x16x32_bf16 v[98:101], v[234:237], v[176:179], v[98:101]
	v_mfma_f32_16x16x32_bf16 v[86:89], v[226:229], v[184:187], v[86:89]
	v_mfma_f32_16x16x32_bf16 v[82:85], v[234:237], v[184:187], v[82:85]
	v_mfma_f32_16x16x32_bf16 v[70:73], v[226:229], v[192:195], v[70:73]
	v_mfma_f32_16x16x32_bf16 v[66:69], v[234:237], v[192:195], v[66:69]
	s_mov_b32 m0, s72
	v_lshl_add_u64 v[238:239], v[242:243], 0, s[86:87]
	s_barrier
	ds_read_b128 v[164:167], v225 offset:49152
	ds_read_b128 v[168:171], v225 offset:50176
	ds_read_b128 v[172:175], v225 offset:51200
	ds_read_b128 v[176:179], v225 offset:52224
	ds_read_b128 v[180:183], v225 offset:53248
	ds_read_b128 v[184:187], v225 offset:54272
	ds_read_b128 v[188:191], v225 offset:55296
	ds_read_b128 v[192:195], v225 offset:56320
	global_load_lds_dwordx4 v[238:239], off
	v_lshl_add_u64 v[238:239], v[244:245], 0, s[86:87]
	s_mov_b32 m0, s73
	s_nop 0
	global_load_lds_dwordx4 v[238:239], off
	s_barrier
	s_waitcnt lgkmcnt(0)
	v_mfma_f32_16x16x32_bf16 v[62:65], v[130:133], v[164:167], v[62:65]
	v_mfma_f32_16x16x32_bf16 v[58:61], v[156:159], v[164:167], v[58:61]
	v_mfma_f32_16x16x32_bf16 v[46:49], v[130:133], v[172:175], v[46:49]
	v_mfma_f32_16x16x32_bf16 v[42:45], v[156:159], v[172:175], v[42:45]
	v_mfma_f32_16x16x32_bf16 v[30:33], v[130:133], v[180:183], v[30:33]
	v_mfma_f32_16x16x32_bf16 v[26:29], v[156:159], v[180:183], v[26:29]
	v_mfma_f32_16x16x32_bf16 v[14:17], v[130:133], v[188:191], v[14:17]
	v_mfma_f32_16x16x32_bf16 v[10:13], v[156:159], v[188:191], v[10:13]
	v_mfma_f32_16x16x32_bf16 v[62:65], v[152:155], v[168:171], v[62:65]
	v_mfma_f32_16x16x32_bf16 v[58:61], v[160:163], v[168:171], v[58:61]
	v_mfma_f32_16x16x32_bf16 v[46:49], v[152:155], v[176:179], v[46:49]
	v_mfma_f32_16x16x32_bf16 v[42:45], v[160:163], v[176:179], v[42:45]
	v_mfma_f32_16x16x32_bf16 v[30:33], v[152:155], v[184:187], v[30:33]
	v_mfma_f32_16x16x32_bf16 v[26:29], v[160:163], v[184:187], v[26:29]
	v_mfma_f32_16x16x32_bf16 v[14:17], v[152:155], v[192:195], v[14:17]
	v_mfma_f32_16x16x32_bf16 v[10:13], v[160:163], v[192:195], v[10:13]
	s_barrier
	s_add_i32 s56, s56, s65
	v_lshl_add_u64 v[130:131], v[246:247], 0, s[86:87]
	s_mov_b32 m0, s56
	s_nop 0
	global_load_lds_dwordx4 v[130:131], off
	v_lshl_add_u64 v[130:131], v[248:249], 0, s[86:87]
	s_add_i32 m0, s56, 0x2000
	s_nop 0
	global_load_lds_dwordx4 v[130:131], off
	s_waitcnt vmcnt(6)
	s_barrier
	v_mfma_f32_16x16x32_bf16 v[54:57], v[196:199], v[164:167], v[54:57]
	v_mfma_f32_16x16x32_bf16 v[50:53], v[230:233], v[164:167], v[50:53]
	v_mfma_f32_16x16x32_bf16 v[38:41], v[196:199], v[172:175], v[38:41]
	v_mfma_f32_16x16x32_bf16 v[34:37], v[230:233], v[172:175], v[34:37]
	v_mfma_f32_16x16x32_bf16 v[22:25], v[196:199], v[180:183], v[22:25]
	v_mfma_f32_16x16x32_bf16 v[18:21], v[230:233], v[180:183], v[18:21]
	v_mfma_f32_16x16x32_bf16 v[6:9], v[196:199], v[188:191], v[6:9]
	v_mfma_f32_16x16x32_bf16 v[2:5], v[230:233], v[188:191], v[2:5]
	v_mfma_f32_16x16x32_bf16 v[54:57], v[226:229], v[168:171], v[54:57]
	v_mfma_f32_16x16x32_bf16 v[50:53], v[234:237], v[168:171], v[50:53]
	v_mfma_f32_16x16x32_bf16 v[38:41], v[226:229], v[176:179], v[38:41]
	v_mfma_f32_16x16x32_bf16 v[34:37], v[234:237], v[176:179], v[34:37]
	v_mfma_f32_16x16x32_bf16 v[22:25], v[226:229], v[184:187], v[22:25]
	v_mfma_f32_16x16x32_bf16 v[18:21], v[234:237], v[184:187], v[18:21]
	v_mfma_f32_16x16x32_bf16 v[6:9], v[226:229], v[192:195], v[6:9]
	v_mfma_f32_16x16x32_bf16 v[2:5], v[234:237], v[192:195], v[2:5]
	s_add_u32 s44, s44, 0x100
	s_addc_u32 s45, s45, 0
	s_add_u32 s79, s79, 0x100
	s_addc_u32 s80, s80, 0
	s_cmp_ge_u32 s81, s71
	s_mov_b32 s56, s81
	s_barrier
	s_cbranch_scc0 .LBB0_835

; #define PG8_STAGE(bufoff, gbase, voff) do { _Pragma("unroll") for (int _i = 0; _i < 2; ++_i) \
;     __builtin_amdgcn_global_load_lds((const unsigned*)((const char*)(gbase) + (voff)[_i]), (PG8_LAS unsigned*)(lds + (bufoff) + ldsw + _i * 8192), 16, 0, 0); } while (0)
; #define PG8_LDA(dst, b, h) do { _Pragma("unroll") for (int m = 0; m < 4; ++m) _Pragma("unroll") for (int k = 0; k < 2; ++k) dst[m][k] = *(const PG8_LAS bf16x8*)(lds + PG8_SA(b, h) + aoff + m * 2048 + k * 1024); } while (0)
; #define PG8_LDB(dst, b, h) do { _Pragma("unroll") for (int n = 0; n < 2; ++n) _Pragma("unroll") for (int k = 0; k < 2; ++k) dst[n][k] = *(const PG8_LAS bf16x8*)(lds + PG8_SB(b, h) + boff + n * 2048 + k * 1024); } while (0)
; #define PG8_MMA(ai, bj, At, Bt) do { __builtin_amdgcn_s_setprio(1); _Pragma("unroll") for (int m = 0; m < 4; ++m) _Pragma("unroll") for (int n = 0; n < 2; ++n) _Pragma("unroll") for (int k = 0; k < 2; ++k) \
;     acc[ai][bj][m][n] = __builtin_amdgcn_mfma_f32_16x16x32_bf16(Bt[n][k], At[m][k], acc[ai][bj][m][n], 0, 0, 0); __builtin_amdgcn_s_setprio(0); } while (0)
; #define PG8_WAIT_L(n) asm volatile("s_waitcnt lgkmcnt(" #n ")" ::: "memory")
; #define PG8_BAR __builtin_amdgcn_s_barrier()
; #define PG8_SCHED __builtin_amdgcn_sched_barrier(0)
; template <class Epi>
; DI void gemm_phase(PG8_LAS unsigned char* lds, const Gemm g, const StaticOrder& S, const Epi& E) {
;     ...
;     const bool has_next = S.next(ui + 1, nxt);
;     const char* nA = has_next ? (const char*)g.A + (size_t)nxt.pm * tstepA : cA; const char* nB = has_next ? (const char*)g.Bt + (size_t)nxt.pn * tstepB : cB;
;     for (int t = 0; t < nt; t += 2) {
;       const bool last = (t == nt - 2);
;       const char* a1 = cA + (size_t)(t + 1) * kstep;
;       const char* a2 = last ? nA : cA + (size_t)(t + 2) * kstep; const char* b2 = last ? nB : cB + (size_t)(t + 2) * kstep;
;       const char* a3 = a2 + kstep; const char* b3 = b2 + kstep;
;       PG8_LDB(B0, 0, 0); PG8_SCHED; PG8_LDA(At, 0, 0); PG8_STAGE(PG8_SA(1, 1), a1 + hstepA, voffA);
;       PG8_WAIT_L(8); PG8_BAR; PG8_WAIT_L(0); PG8_MMA(0, 0, At, B0); PG8_BAR; PG8_SCHED;
;       PG8_LDB(B1, 0, 1); PG8_STAGE(PG8_SB(0, 0), b2, voffB);
;       PG8_BAR; PG8_WAIT_L(0); PG8_MMA(0, 1, At, B1); PG8_BAR;
;       PG8_LDA(At, 0, 1); PG8_STAGE(PG8_SA(0, 0), a2, voffA);
.LBB0_1174:
	s_ashr_i32 s47, s46, 31
	v_cmp_lt_i64_e32 vcc, s[48:49], v[136:137]
	s_lshl_b64 s[48:49], s[46:47], 19
	s_add_u32 s48, s22, s48
	s_addc_u32 s49, s23, s49
	s_and_b64 s[50:51], vcc, exec
	s_cselect_b32 s47, s49, s31
	s_cselect_b32 s66, s48, s30
	s_ashr_i32 s45, s44, 31
	v_readlane_b32 s4, v253, 16
	s_lshl_b64 s[50:51], s[44:45], 19
	v_readlane_b32 s14, v253, 26
	v_readlane_b32 s15, v253, 27
	s_add_u32 s50, s14, s50
	s_addc_u32 s51, s15, s51
	s_and_b64 s[54:55], vcc, exec
	s_cselect_b32 s45, s51, s53
	s_cselect_b32 s67, s50, s52
	s_add_u32 s30, s30, 0x40080
	s_addc_u32 s31, s31, 0
	s_add_u32 s68, s52, 0x100
	v_mov_b32_e32 v18, 0
	s_addc_u32 s69, s53, 0
	s_mov_b32 s70, -2
	v_readlane_b32 s5, v253, 17
	v_readlane_b32 s6, v253, 18
	v_readlane_b32 s7, v253, 19
	v_readlane_b32 s8, v253, 20
	v_readlane_b32 s9, v253, 21
	v_readlane_b32 s10, v253, 22
	v_readlane_b32 s11, v253, 23
	v_readlane_b32 s12, v253, 24
	v_readlane_b32 s13, v253, 25
	v_readlane_b32 s16, v253, 28
	v_readlane_b32 s17, v253, 29
	v_readlane_b32 s18, v253, 30
	v_readlane_b32 s19, v253, 31
	s_add_u32 s52, s30, 0xfffc0080
	s_addc_u32 s53, s31, -1
	s_add_i32 s71, 0, 0x10000
	v_add_u32_e32 v156, s71, v160
	ds_read_b128 v[152:155], v156
	ds_read_b128 v[164:167], v156 offset:1024
	ds_read_b128 v[168:171], v156 offset:2048
	ds_read_b128 v[172:175], v156 offset:3072
	s_cmp_eq_u32 s70, 12
	s_cselect_b32 s55, s47, s53
	s_cselect_b32 s54, s66, s52
	s_cselect_b32 s53, s45, s69
	s_cselect_b32 s52, s67, s68
	v_lshl_add_u64 v[156:157], s[30:31], 0, v[148:149]
	s_add_i32 m0, s58, 0xc000
	ds_read_b128 v[176:179], v162
	ds_read_b128 v[180:183], v162 offset:1024
	ds_read_b128 v[184:187], v162 offset:2048
	ds_read_b128 v[188:191], v162 offset:3072
	ds_read_b128 v[192:195], v162 offset:4096
	ds_read_b128 v[196:199], v162 offset:5120
	ds_read_b128 v[222:225], v162 offset:6144
	ds_read_b128 v[226:229], v162 offset:7168
	global_load_lds_dwordx4 v[156:157], off
	v_lshl_add_u64 v[156:157], s[30:31], 0, v[150:151]
	s_add_i32 m0, s58, 0xe000
	s_nop 0
	global_load_lds_dwordx4 v[156:157], off
	s_waitcnt lgkmcnt(8)
	s_barrier
	s_waitcnt lgkmcnt(0)
	v_mfma_f32_16x16x32_bf16 v[70:73], v[152:155], v[176:179], 0
	v_mfma_f32_16x16x32_bf16 v[66:69], v[168:171], v[176:179], 0
	v_mfma_f32_16x16x32_bf16 v[62:65], v[152:155], v[184:187], 0
	v_mfma_f32_16x16x32_bf16 v[58:61], v[168:171], v[184:187], 0
	v_mfma_f32_16x16x32_bf16 v[54:57], v[152:155], v[192:195], 0
	v_mfma_f32_16x16x32_bf16 v[50:53], v[168:171], v[192:195], 0
	v_mfma_f32_16x16x32_bf16 v[46:49], v[152:155], v[222:225], 0
	v_mfma_f32_16x16x32_bf16 v[42:45], v[168:171], v[222:225], 0
	v_mfma_f32_16x16x32_bf16 v[70:73], v[164:167], v[180:183], v[70:73]
	v_mfma_f32_16x16x32_bf16 v[66:69], v[172:175], v[180:183], v[66:69]
	v_mfma_f32_16x16x32_bf16 v[62:65], v[164:167], v[188:191], v[62:65]
	v_mfma_f32_16x16x32_bf16 v[58:61], v[172:175], v[188:191], v[58:61]
	v_mfma_f32_16x16x32_bf16 v[54:57], v[164:167], v[196:199], v[54:57]
	v_mfma_f32_16x16x32_bf16 v[50:53], v[172:175], v[196:199], v[50:53]
	v_mfma_f32_16x16x32_bf16 v[46:49], v[164:167], v[226:229], v[46:49]
	v_mfma_f32_16x16x32_bf16 v[42:45], v[172:175], v[226:229], v[42:45]
	s_barrier
	s_add_i32 s74, 0, 0x14000
	v_add_u32_e32 v156, s74, v160
	s_add_i32 s71, s71, s57
	ds_read_b128 v[230:233], v156
	ds_read_b128 v[234:237], v156 offset:1024
	ds_read_b128 v[238:241], v156 offset:2048
	ds_read_b128 v[242:245], v156 offset:3072
	v_lshl_add_u64 v[156:157], s[52:53], 0, v[0:1]
	s_mov_b32 m0, s71
	v_lshl_add_u64 v[246:247], s[52:53], 0, v[130:131]
	global_load_lds_dwordx4 v[156:157], off
	s_add_i32 m0, s71, 0x2000
	s_nop 0
	global_load_lds_dwordx4 v[246:247], off
	s_barrier
	s_waitcnt lgkmcnt(0)
	v_mfma_f32_16x16x32_bf16 v[126:129], v[230:233], v[176:179], 0
	v_mfma_f32_16x16x32_bf16 v[122:125], v[238:241], v[176:179], 0
	v_mfma_f32_16x16x32_bf16 v[118:121], v[230:233], v[184:187], 0
	v_mfma_f32_16x16x32_bf16 v[114:117], v[238:241], v[184:187], 0
	v_mfma_f32_16x16x32_bf16 v[110:113], v[230:233], v[192:195], 0
	v_mfma_f32_16x16x32_bf16 v[106:109], v[238:241], v[192:195], 0
	v_mfma_f32_16x16x32_bf16 v[102:105], v[230:233], v[222:225], 0
	v_mfma_f32_16x16x32_bf16 v[98:101], v[238:241], v[222:225], 0
	v_mfma_f32_16x16x32_bf16 v[126:129], v[234:237], v[180:183], v[126:129]
	v_mfma_f32_16x16x32_bf16 v[122:125], v[242:245], v[180:183], v[122:125]
	v_mfma_f32_16x16x32_bf16 v[118:121], v[234:237], v[188:191], v[118:121]
	v_mfma_f32_16x16x32_bf16 v[114:117], v[242:245], v[188:191], v[114:117]
	v_mfma_f32_16x16x32_bf16 v[110:113], v[234:237], v[196:199], v[110:113]
	v_mfma_f32_16x16x32_bf16 v[106:109], v[242:245], v[196:199], v[106:109]
	v_mfma_f32_16x16x32_bf16 v[102:105], v[234:237], v[226:229], v[102:105]
	v_mfma_f32_16x16x32_bf16 v[98:101], v[242:245], v[226:229], v[98:101]
	s_mov_b32 m0, s58
	v_lshl_add_u64 v[248:249], s[54:55], 0, v[142:143]
	s_barrier
	ds_read_b128 v[176:179], v162 offset:16384
	ds_read_b128 v[180:183], v162 offset:17408
	ds_read_b128 v[184:187], v162 offset:18432
	ds_read_b128 v[188:191], v162 offset:19456
	ds_read_b128 v[192:195], v162 offset:20480
	ds_read_b128 v[196:199], v162 offset:21504
	ds_read_b128 v[222:225], v162 offset:22528
	ds_read_b128 v[226:229], v162 offset:23552
	global_load_lds_dwordx4 v[248:249], off
	v_lshl_add_u64 v[250:251], s[54:55], 0, v[132:133]
	s_mov_b32 m0, s59
	s_nop 0
	global_load_lds_dwordx4 v[250:251], off
	s_barrier
; #define PG8_STAGE(bufoff, gbase, voff) do { _Pragma("unroll") for (int _i = 0; _i < 2; ++_i) \
;     __builtin_amdgcn_global_load_lds((const unsigned*)((const char*)(gbase) + (voff)[_i]), (PG8_LAS unsigned*)(lds + (bufoff) + ldsw + _i * 8192), 16, 0, 0); } while (0)
; #define PG8_LDA(dst, b, h) do { _Pragma("unroll") for (int m = 0; m < 4; ++m) _Pragma("unroll") for (int k = 0; k < 2; ++k) dst[m][k] = *(const PG8_LAS bf16x8*)(lds + PG8_SA(b, h) + aoff + m * 2048 + k * 1024); } while (0)
; #define PG8_LDB(dst, b, h) do { _Pragma("unroll") for (int n = 0; n < 2; ++n) _Pragma("unroll") for (int k = 0; k < 2; ++k) dst[n][k] = *(const PG8_LAS bf16x8*)(lds + PG8_SB(b, h) + boff + n * 2048 + k * 1024); } while (0)
; #define PG8_MMA(ai, bj, At, Bt) do { __builtin_amdgcn_s_setprio(1); _Pragma("unroll") for (int m = 0; m < 4; ++m) _Pragma("unroll") for (int n = 0; n < 2; ++n) _Pragma("unroll") for (int k = 0; k < 2; ++k) \
;     acc[ai][bj][m][n] = __builtin_amdgcn_mfma_f32_16x16x32_bf16(Bt[n][k], At[m][k], acc[ai][bj][m][n], 0, 0, 0); __builtin_amdgcn_s_setprio(0); } while (0)
; #define PG8_WAIT_V(n) asm volatile("s_waitcnt vmcnt(" #n ")" ::: "memory")
; #define PG8_WAIT_L(n) asm volatile("s_waitcnt lgkmcnt(" #n ")" ::: "memory")
; #define PG8_BAR __builtin_amdgcn_s_barrier()
; #define PG8_SCHED __builtin_amdgcn_sched_barrier(0)
; template <class Epi>
; DI void gemm_phase(PG8_LAS unsigned char* lds, const Gemm g, const StaticOrder& S, const Epi& E) {
;     ...
;       PG8_BAR; PG8_WAIT_L(0); PG8_MMA(1, 0, At, B0); PG8_BAR; PG8_SCHED;
;       PG8_STAGE(PG8_SB(0, 1), b2 + hstepB, voffB);
;       PG8_WAIT_V(6); PG8_BAR; PG8_MMA(1, 1, At, B1); PG8_BAR;
;       PG8_LDB(B0, 1, 0); PG8_SCHED; PG8_LDA(At, 1, 0); PG8_STAGE(PG8_SA(0, 1), a2 + hstepA, voffA);
;       PG8_WAIT_L(8); PG8_BAR; PG8_WAIT_L(0); PG8_MMA(0, 0, At, B0); PG8_BAR; PG8_SCHED;
;       PG8_LDB(B1, 1, 1); PG8_STAGE(PG8_SB(1, 0), b3, voffB);
;       PG8_BAR; PG8_WAIT_L(0); PG8_MMA(0, 1, At, B1); PG8_BAR;
;       PG8_LDA(At, 1, 1); PG8_STAGE(PG8_SA(1, 0), a3, voffA);
	s_waitcnt lgkmcnt(0)
	v_mfma_f32_16x16x32_bf16 v[38:41], v[152:155], v[176:179], 0
	v_mfma_f32_16x16x32_bf16 v[34:37], v[168:171], v[176:179], 0
	v_mfma_f32_16x16x32_bf16 v[30:33], v[152:155], v[184:187], 0
	v_mfma_f32_16x16x32_bf16 v[26:29], v[168:171], v[184:187], 0
	v_mfma_f32_16x16x32_bf16 v[14:17], v[152:155], v[192:195], 0
	v_mfma_f32_16x16x32_bf16 v[10:13], v[168:171], v[192:195], 0
	v_mfma_f32_16x16x32_bf16 v[6:9], v[152:155], v[222:225], 0
	v_mfma_f32_16x16x32_bf16 v[2:5], v[168:171], v[222:225], 0
	v_mfma_f32_16x16x32_bf16 v[38:41], v[164:167], v[180:183], v[38:41]
	v_mfma_f32_16x16x32_bf16 v[34:37], v[172:175], v[180:183], v[34:37]
	v_mfma_f32_16x16x32_bf16 v[30:33], v[164:167], v[188:191], v[30:33]
	v_mfma_f32_16x16x32_bf16 v[26:29], v[172:175], v[188:191], v[26:29]
	v_mfma_f32_16x16x32_bf16 v[14:17], v[164:167], v[196:199], v[14:17]
	v_mfma_f32_16x16x32_bf16 v[10:13], v[172:175], v[196:199], v[10:13]
	v_mfma_f32_16x16x32_bf16 v[6:9], v[164:167], v[226:229], v[6:9]
	v_mfma_f32_16x16x32_bf16 v[2:5], v[172:175], v[226:229], v[2:5]
	s_barrier
	s_add_u32 s72, s52, 0x40000
	s_addc_u32 s73, s53, 0
	s_add_i32 s71, s74, s57
	v_lshl_add_u64 v[152:153], s[72:73], 0, v[0:1]
	s_mov_b32 m0, s71
	s_nop 0
	global_load_lds_dwordx4 v[152:153], off
	v_lshl_add_u64 v[152:153], s[72:73], 0, v[130:131]
	s_add_i32 m0, s71, 0x2000
	s_nop 0
	global_load_lds_dwordx4 v[152:153], off
	s_waitcnt vmcnt(6)
	s_barrier
	v_mfma_f32_16x16x32_bf16 v[94:97], v[230:233], v[176:179], 0
	v_mfma_f32_16x16x32_bf16 v[90:93], v[238:241], v[176:179], 0
	v_mfma_f32_16x16x32_bf16 v[86:89], v[230:233], v[184:187], 0
	v_mfma_f32_16x16x32_bf16 v[82:85], v[238:241], v[184:187], 0
	v_mfma_f32_16x16x32_bf16 v[78:81], v[230:233], v[192:195], 0
	v_mfma_f32_16x16x32_bf16 v[74:77], v[238:241], v[192:195], 0
	v_mfma_f32_16x16x32_bf16 v[22:25], v[230:233], v[222:225], 0
	v_mfma_f32_16x16x32_bf16 v[18:21], v[238:241], v[222:225], 0
	v_mfma_f32_16x16x32_bf16 v[94:97], v[234:237], v[180:183], v[94:97]
	v_mfma_f32_16x16x32_bf16 v[90:93], v[242:245], v[180:183], v[90:93]
	v_mfma_f32_16x16x32_bf16 v[86:89], v[234:237], v[188:191], v[86:89]
	v_mfma_f32_16x16x32_bf16 v[82:85], v[242:245], v[188:191], v[82:85]
	v_mfma_f32_16x16x32_bf16 v[78:81], v[234:237], v[196:199], v[78:81]
	v_mfma_f32_16x16x32_bf16 v[74:77], v[242:245], v[196:199], v[74:77]
	v_mfma_f32_16x16x32_bf16 v[22:25], v[234:237], v[226:229], v[22:25]
	v_mfma_f32_16x16x32_bf16 v[18:21], v[242:245], v[226:229], v[18:21]
	s_add_i32 s71, 0, 0x18000
	v_add_u32_e32 v163, s71, v160
	s_barrier
	ds_read_b128 v[152:155], v163
	ds_read_b128 v[164:167], v163 offset:1024
	ds_read_b128 v[168:171], v163 offset:2048
	ds_read_b128 v[172:175], v163 offset:3072
	s_add_u32 s54, s54, 0x40000
	s_addc_u32 s55, s55, 0
	s_mov_b32 m0, s60
	v_lshl_add_u64 v[230:231], s[54:55], 0, v[142:143]
	ds_read_b128 v[176:179], v162 offset:32768
	ds_read_b128 v[180:183], v162 offset:33792
	ds_read_b128 v[184:187], v162 offset:34816
	ds_read_b128 v[188:191], v162 offset:35840
	ds_read_b128 v[192:195], v162 offset:36864
	ds_read_b128 v[196:199], v162 offset:37888
	ds_read_b128 v[222:225], v162 offset:38912
	ds_read_b128 v[226:229], v162 offset:39936
	global_load_lds_dwordx4 v[230:231], off
	v_lshl_add_u64 v[230:231], s[54:55], 0, v[132:133]
	s_mov_b32 m0, s61
	s_nop 0
	global_load_lds_dwordx4 v[230:231], off
	s_waitcnt lgkmcnt(8)
	s_barrier
	s_waitcnt lgkmcnt(0)
	v_mfma_f32_16x16x32_bf16 v[70:73], v[152:155], v[176:179], v[70:73]
	v_mfma_f32_16x16x32_bf16 v[66:69], v[168:171], v[176:179], v[66:69]
	v_mfma_f32_16x16x32_bf16 v[62:65], v[152:155], v[184:187], v[62:65]
	v_mfma_f32_16x16x32_bf16 v[58:61], v[168:171], v[184:187], v[58:61]
	v_mfma_f32_16x16x32_bf16 v[54:57], v[152:155], v[192:195], v[54:57]
	v_mfma_f32_16x16x32_bf16 v[50:53], v[168:171], v[192:195], v[50:53]
	v_mfma_f32_16x16x32_bf16 v[46:49], v[152:155], v[222:225], v[46:49]
	v_mfma_f32_16x16x32_bf16 v[42:45], v[168:171], v[222:225], v[42:45]
	v_mfma_f32_16x16x32_bf16 v[70:73], v[164:167], v[180:183], v[70:73]
	v_mfma_f32_16x16x32_bf16 v[66:69], v[172:175], v[180:183], v[66:69]
	v_mfma_f32_16x16x32_bf16 v[62:65], v[164:167], v[188:191], v[62:65]
	v_mfma_f32_16x16x32_bf16 v[58:61], v[172:175], v[188:191], v[58:61]
	v_mfma_f32_16x16x32_bf16 v[54:57], v[164:167], v[196:199], v[54:57]
	v_mfma_f32_16x16x32_bf16 v[50:53], v[172:175], v[196:199], v[50:53]
	v_mfma_f32_16x16x32_bf16 v[46:49], v[164:167], v[226:229], v[46:49]
	v_mfma_f32_16x16x32_bf16 v[42:45], v[172:175], v[226:229], v[42:45]
	s_barrier
	s_add_i32 s54, 0, 0x1c000
	s_add_i32 s55, s71, s57
	v_add_u32_e32 v163, s54, v160
	v_lshl_add_u64 v[156:157], v[156:157], 0, s[86:87]
	s_mov_b32 m0, s55
	ds_read_b128 v[230:233], v163
	ds_read_b128 v[234:237], v163 offset:1024
	ds_read_b128 v[238:241], v163 offset:2048
	ds_read_b128 v[242:245], v163 offset:3072
	global_load_lds_dwordx4 v[156:157], off
	v_lshl_add_u64 v[156:157], v[246:247], 0, s[86:87]
	s_add_i32 m0, s55, 0x2000
	s_nop 0
	global_load_lds_dwordx4 v[156:157], off
	s_barrier
	s_waitcnt lgkmcnt(0)
	v_mfma_f32_16x16x32_bf16 v[126:129], v[230:233], v[176:179], v[126:129]
	v_mfma_f32_16x16x32_bf16 v[122:125], v[238:241], v[176:179], v[122:125]
	v_mfma_f32_16x16x32_bf16 v[118:121], v[230:233], v[184:187], v[118:121]
	v_mfma_f32_16x16x32_bf16 v[114:117], v[238:241], v[184:187], v[114:117]
	v_mfma_f32_16x16x32_bf16 v[110:113], v[230:233], v[192:195], v[110:113]
	v_mfma_f32_16x16x32_bf16 v[106:109], v[238:241], v[192:195], v[106:109]
	v_mfma_f32_16x16x32_bf16 v[102:105], v[230:233], v[222:225], v[102:105]
	v_mfma_f32_16x16x32_bf16 v[98:101], v[238:241], v[222:225], v[98:101]
	v_mfma_f32_16x16x32_bf16 v[126:129], v[234:237], v[180:183], v[126:129]
	v_mfma_f32_16x16x32_bf16 v[122:125], v[242:245], v[180:183], v[122:125]
	v_mfma_f32_16x16x32_bf16 v[118:121], v[234:237], v[188:191], v[118:121]
	v_mfma_f32_16x16x32_bf16 v[114:117], v[242:245], v[188:191], v[114:117]
	v_mfma_f32_16x16x32_bf16 v[110:113], v[234:237], v[196:199], v[110:113]
	v_mfma_f32_16x16x32_bf16 v[106:109], v[242:245], v[196:199], v[106:109]
	v_mfma_f32_16x16x32_bf16 v[102:105], v[234:237], v[226:229], v[102:105]
	v_mfma_f32_16x16x32_bf16 v[98:101], v[242:245], v[226:229], v[98:101]
	s_mov_b32 m0, s34
	v_lshl_add_u64 v[156:157], v[248:249], 0, s[86:87]
	s_barrier
; #define PG8_STAGE(bufoff, gbase, voff) do { _Pragma("unroll") for (int _i = 0; _i < 2; ++_i) \
;     __builtin_amdgcn_global_load_lds((const unsigned*)((const char*)(gbase) + (voff)[_i]), (PG8_LAS unsigned*)(lds + (bufoff) + ldsw + _i * 8192), 16, 0, 0); } while (0)
; #define PG8_LDA(dst, b, h) do { _Pragma("unroll") for (int m = 0; m < 4; ++m) _Pragma("unroll") for (int k = 0; k < 2; ++k) dst[m][k] = *(const PG8_LAS bf16x8*)(lds + PG8_SA(b, h) + aoff + m * 2048 + k * 1024); } while (0)
; #define PG8_LDB(dst, b, h) do { _Pragma("unroll") for (int n = 0; n < 2; ++n) _Pragma("unroll") for (int k = 0; k < 2; ++k) dst[n][k] = *(const PG8_LAS bf16x8*)(lds + PG8_SB(b, h) + boff + n * 2048 + k * 1024); } while (0)
; #define PG8_MMA(ai, bj, At, Bt) do { __builtin_amdgcn_s_setprio(1); _Pragma("unroll") for (int m = 0; m < 4; ++m) _Pragma("unroll") for (int n = 0; n < 2; ++n) _Pragma("unroll") for (int k = 0; k < 2; ++k) \
;     acc[ai][bj][m][n] = __builtin_amdgcn_mfma_f32_16x16x32_bf16(Bt[n][k], At[m][k], acc[ai][bj][m][n], 0, 0, 0); __builtin_amdgcn_s_setprio(0); } while (0)
; #define PG8_WAIT_V(n) asm volatile("s_waitcnt vmcnt(" #n ")" ::: "memory")
; #define PG8_WAIT_L(n) asm volatile("s_waitcnt lgkmcnt(" #n ")" ::: "memory")
; #define PG8_BAR __builtin_amdgcn_s_barrier()
; #define PG8_SCHED __builtin_amdgcn_sched_barrier(0)
; template <class Epi>
; DI void gemm_phase(PG8_LAS unsigned char* lds, const Gemm g, const StaticOrder& S, const Epi& E) {
;     ...
;     for (int t = 0; t < nt; t += 2) {
;       const bool last = (t == nt - 2);
;       const char* a1 = cA + (size_t)(t + 1) * kstep;
;       const char* a2 = last ? nA : cA + (size_t)(t + 2) * kstep; const char* b2 = last ? nB : cB + (size_t)(t + 2) * kstep;
;       const char* a3 = a2 + kstep; const char* b3 = b2 + kstep;
;       PG8_LDB(B0, 0, 0); PG8_SCHED; PG8_LDA(At, 0, 0); PG8_STAGE(PG8_SA(1, 1), a1 + hstepA, voffA);
;       PG8_WAIT_L(8); PG8_BAR; PG8_WAIT_L(0); PG8_MMA(0, 0, At, B0); PG8_BAR; PG8_SCHED;
;     ...
;       PG8_LDA(At, 1, 1); PG8_STAGE(PG8_SA(1, 0), a3, voffA);
;       PG8_BAR; PG8_WAIT_L(0); PG8_MMA(1, 0, At, B0); PG8_BAR; PG8_SCHED;
;       PG8_STAGE(PG8_SB(1, 1), b3 + hstepB, voffB);
;       PG8_WAIT_V(6); PG8_BAR; PG8_MMA(1, 1, At, B1); PG8_BAR;
	ds_read_b128 v[176:179], v162 offset:49152
	ds_read_b128 v[180:183], v162 offset:50176
	ds_read_b128 v[184:187], v162 offset:51200
	ds_read_b128 v[188:191], v162 offset:52224
	ds_read_b128 v[192:195], v162 offset:53248
	ds_read_b128 v[196:199], v162 offset:54272
	ds_read_b128 v[222:225], v162 offset:55296
	ds_read_b128 v[226:229], v162 offset:56320
	global_load_lds_dwordx4 v[156:157], off
	v_lshl_add_u64 v[156:157], v[250:251], 0, s[86:87]
	s_mov_b32 m0, s62
	s_nop 0
	global_load_lds_dwordx4 v[156:157], off
	s_barrier
	s_waitcnt lgkmcnt(0)
	v_mfma_f32_16x16x32_bf16 v[38:41], v[152:155], v[176:179], v[38:41]
	v_mfma_f32_16x16x32_bf16 v[34:37], v[168:171], v[176:179], v[34:37]
	v_mfma_f32_16x16x32_bf16 v[30:33], v[152:155], v[184:187], v[30:33]
	v_mfma_f32_16x16x32_bf16 v[26:29], v[168:171], v[184:187], v[26:29]
	v_mfma_f32_16x16x32_bf16 v[14:17], v[152:155], v[192:195], v[14:17]
	v_mfma_f32_16x16x32_bf16 v[10:13], v[168:171], v[192:195], v[10:13]
	v_mfma_f32_16x16x32_bf16 v[6:9], v[152:155], v[222:225], v[6:9]
	v_mfma_f32_16x16x32_bf16 v[2:5], v[168:171], v[222:225], v[2:5]
	v_mfma_f32_16x16x32_bf16 v[38:41], v[164:167], v[180:183], v[38:41]
	v_mfma_f32_16x16x32_bf16 v[34:37], v[172:175], v[180:183], v[34:37]
	v_mfma_f32_16x16x32_bf16 v[30:33], v[164:167], v[188:191], v[30:33]
	v_mfma_f32_16x16x32_bf16 v[26:29], v[172:175], v[188:191], v[26:29]
	v_mfma_f32_16x16x32_bf16 v[14:17], v[164:167], v[196:199], v[14:17]
	v_mfma_f32_16x16x32_bf16 v[10:13], v[172:175], v[196:199], v[10:13]
	v_mfma_f32_16x16x32_bf16 v[6:9], v[164:167], v[226:229], v[6:9]
	v_mfma_f32_16x16x32_bf16 v[2:5], v[172:175], v[226:229], v[2:5]
	s_barrier
	s_add_u32 s52, s52, 0x40080
	s_addc_u32 s53, s53, 0
	s_add_i32 s54, s54, s57
	v_lshl_add_u64 v[152:153], s[52:53], 0, v[0:1]
	s_mov_b32 m0, s54
	s_nop 0
	global_load_lds_dwordx4 v[152:153], off
	v_lshl_add_u64 v[152:153], s[52:53], 0, v[130:131]
	s_add_i32 m0, s54, 0x2000
	s_nop 0
	global_load_lds_dwordx4 v[152:153], off
	s_waitcnt vmcnt(6)
	s_barrier
	v_mfma_f32_16x16x32_bf16 v[94:97], v[230:233], v[176:179], v[94:97]
	v_mfma_f32_16x16x32_bf16 v[90:93], v[238:241], v[176:179], v[90:93]
	v_mfma_f32_16x16x32_bf16 v[86:89], v[230:233], v[184:187], v[86:89]
	v_mfma_f32_16x16x32_bf16 v[82:85], v[238:241], v[184:187], v[82:85]
	v_mfma_f32_16x16x32_bf16 v[78:81], v[230:233], v[192:195], v[78:81]
	v_mfma_f32_16x16x32_bf16 v[74:77], v[238:241], v[192:195], v[74:77]
	v_mfma_f32_16x16x32_bf16 v[22:25], v[230:233], v[222:225], v[22:25]
	v_mfma_f32_16x16x32_bf16 v[18:21], v[238:241], v[222:225], v[18:21]
	v_mfma_f32_16x16x32_bf16 v[94:97], v[234:237], v[180:183], v[94:97]
	v_mfma_f32_16x16x32_bf16 v[90:93], v[242:245], v[180:183], v[90:93]
	v_mfma_f32_16x16x32_bf16 v[86:89], v[234:237], v[188:191], v[86:89]
	v_mfma_f32_16x16x32_bf16 v[82:85], v[242:245], v[188:191], v[82:85]
	v_mfma_f32_16x16x32_bf16 v[78:81], v[234:237], v[196:199], v[78:81]
	v_mfma_f32_16x16x32_bf16 v[74:77], v[242:245], v[196:199], v[74:77]
	v_mfma_f32_16x16x32_bf16 v[22:25], v[234:237], v[226:229], v[22:25]
	v_mfma_f32_16x16x32_bf16 v[18:21], v[242:245], v[226:229], v[18:21]
	s_add_i32 s70, s70, 2
	s_add_u32 s30, s30, 0x100
	s_addc_u32 s31, s31, 0
	s_add_u32 s68, s68, 0x100
	s_addc_u32 s69, s69, 0
	s_cmp_gt_u32 s70, 13
	s_barrier
	s_cbranch_scc1 .Lpeel_exit_2
.LBB0_1175:
	s_add_u32 s52, s30, 0xfffc0080
	s_addc_u32 s53, s31, -1
	s_add_i32 s71, 0, 0x10000
	v_add_u32_e32 v156, s71, v160
	ds_read_b128 v[152:155], v156
	ds_read_b128 v[164:167], v156 offset:1024
	ds_read_b128 v[168:171], v156 offset:2048
	ds_read_b128 v[172:175], v156 offset:3072
	s_cmp_eq_u32 s70, 12
	s_cselect_b32 s55, s47, s53
	s_cselect_b32 s54, s66, s52
	s_cselect_b32 s53, s45, s69
	s_cselect_b32 s52, s67, s68
	v_lshl_add_u64 v[156:157], s[30:31], 0, v[148:149]
	s_add_i32 m0, s58, 0xc000
	ds_read_b128 v[176:179], v162
	ds_read_b128 v[180:183], v162 offset:1024
	ds_read_b128 v[184:187], v162 offset:2048
	ds_read_b128 v[188:191], v162 offset:3072
	ds_read_b128 v[192:195], v162 offset:4096
	ds_read_b128 v[196:199], v162 offset:5120
	ds_read_b128 v[222:225], v162 offset:6144
	ds_read_b128 v[226:229], v162 offset:7168
	global_load_lds_dwordx4 v[156:157], off
	v_lshl_add_u64 v[156:157], s[30:31], 0, v[150:151]
	s_add_i32 m0, s58, 0xe000
	s_nop 0
	global_load_lds_dwordx4 v[156:157], off
	s_waitcnt lgkmcnt(8)
	s_barrier
	s_waitcnt lgkmcnt(0)
	v_mfma_f32_16x16x32_bf16 v[70:73], v[152:155], v[176:179], v[70:73]
	v_mfma_f32_16x16x32_bf16 v[66:69], v[168:171], v[176:179], v[66:69]
	v_mfma_f32_16x16x32_bf16 v[62:65], v[152:155], v[184:187], v[62:65]
	v_mfma_f32_16x16x32_bf16 v[58:61], v[168:171], v[184:187], v[58:61]
	v_mfma_f32_16x16x32_bf16 v[54:57], v[152:155], v[192:195], v[54:57]
	v_mfma_f32_16x16x32_bf16 v[50:53], v[168:171], v[192:195], v[50:53]
	v_mfma_f32_16x16x32_bf16 v[46:49], v[152:155], v[222:225], v[46:49]
	v_mfma_f32_16x16x32_bf16 v[42:45], v[168:171], v[222:225], v[42:45]
	v_mfma_f32_16x16x32_bf16 v[70:73], v[164:167], v[180:183], v[70:73]
	v_mfma_f32_16x16x32_bf16 v[66:69], v[172:175], v[180:183], v[66:69]
	v_mfma_f32_16x16x32_bf16 v[62:65], v[164:167], v[188:191], v[62:65]
	v_mfma_f32_16x16x32_bf16 v[58:61], v[172:175], v[188:191], v[58:61]
	v_mfma_f32_16x16x32_bf16 v[54:57], v[164:167], v[196:199], v[54:57]
	v_mfma_f32_16x16x32_bf16 v[50:53], v[172:175], v[196:199], v[50:53]
	v_mfma_f32_16x16x32_bf16 v[46:49], v[164:167], v[226:229], v[46:49]
	v_mfma_f32_16x16x32_bf16 v[42:45], v[172:175], v[226:229], v[42:45]
	s_barrier
; #define PG8_STAGE(bufoff, gbase, voff) do { _Pragma("unroll") for (int _i = 0; _i < 2; ++_i) \
;     __builtin_amdgcn_global_load_lds((const unsigned*)((const char*)(gbase) + (voff)[_i]), (PG8_LAS unsigned*)(lds + (bufoff) + ldsw + _i * 8192), 16, 0, 0); } while (0)
; #define PG8_LDA(dst, b, h) do { _Pragma("unroll") for (int m = 0; m < 4; ++m) _Pragma("unroll") for (int k = 0; k < 2; ++k) dst[m][k] = *(const PG8_LAS bf16x8*)(lds + PG8_SA(b, h) + aoff + m * 2048 + k * 1024); } while (0)
; #define PG8_LDB(dst, b, h) do { _Pragma("unroll") for (int n = 0; n < 2; ++n) _Pragma("unroll") for (int k = 0; k < 2; ++k) dst[n][k] = *(const PG8_LAS bf16x8*)(lds + PG8_SB(b, h) + boff + n * 2048 + k * 1024); } while (0)
; #define PG8_MMA(ai, bj, At, Bt) do { __builtin_amdgcn_s_setprio(1); _Pragma("unroll") for (int m = 0; m < 4; ++m) _Pragma("unroll") for (int n = 0; n < 2; ++n) _Pragma("unroll") for (int k = 0; k < 2; ++k) \
;     acc[ai][bj][m][n] = __builtin_amdgcn_mfma_f32_16x16x32_bf16(Bt[n][k], At[m][k], acc[ai][bj][m][n], 0, 0, 0); __builtin_amdgcn_s_setprio(0); } while (0)
; #define PG8_WAIT_V(n) asm volatile("s_waitcnt vmcnt(" #n ")" ::: "memory")
; #define PG8_WAIT_L(n) asm volatile("s_waitcnt lgkmcnt(" #n ")" ::: "memory")
; #define PG8_BAR __builtin_amdgcn_s_barrier()
; #define PG8_SCHED __builtin_amdgcn_sched_barrier(0)
; template <class Epi>
; DI void gemm_phase(PG8_LAS unsigned char* lds, const Gemm g, const StaticOrder& S, const Epi& E) {
;     ...
;       PG8_LDB(B1, 0, 1); PG8_STAGE(PG8_SB(0, 0), b2, voffB);
;       PG8_BAR; PG8_WAIT_L(0); PG8_MMA(0, 1, At, B1); PG8_BAR;
;       PG8_LDA(At, 0, 1); PG8_STAGE(PG8_SA(0, 0), a2, voffA);
;       PG8_BAR; PG8_WAIT_L(0); PG8_MMA(1, 0, At, B0); PG8_BAR; PG8_SCHED;
;       PG8_STAGE(PG8_SB(0, 1), b2 + hstepB, voffB);
;       PG8_WAIT_V(6); PG8_BAR; PG8_MMA(1, 1, At, B1); PG8_BAR;
;       PG8_LDB(B0, 1, 0); PG8_SCHED; PG8_LDA(At, 1, 0); PG8_STAGE(PG8_SA(0, 1), a2 + hstepA, voffA);
;       PG8_WAIT_L(8); PG8_BAR; PG8_WAIT_L(0); PG8_MMA(0, 0, At, B0); PG8_BAR; PG8_SCHED;
	s_add_i32 s74, 0, 0x14000
	v_add_u32_e32 v156, s74, v160
	s_add_i32 s71, s71, s57
	ds_read_b128 v[230:233], v156
	ds_read_b128 v[234:237], v156 offset:1024
	ds_read_b128 v[238:241], v156 offset:2048
	ds_read_b128 v[242:245], v156 offset:3072
	v_lshl_add_u64 v[156:157], s[52:53], 0, v[0:1]
	s_mov_b32 m0, s71
	v_lshl_add_u64 v[246:247], s[52:53], 0, v[130:131]
	global_load_lds_dwordx4 v[156:157], off
	s_add_i32 m0, s71, 0x2000
	s_nop 0
	global_load_lds_dwordx4 v[246:247], off
	s_barrier
	s_waitcnt lgkmcnt(0)
	v_mfma_f32_16x16x32_bf16 v[126:129], v[230:233], v[176:179], v[126:129]
	v_mfma_f32_16x16x32_bf16 v[122:125], v[238:241], v[176:179], v[122:125]
	v_mfma_f32_16x16x32_bf16 v[118:121], v[230:233], v[184:187], v[118:121]
	v_mfma_f32_16x16x32_bf16 v[114:117], v[238:241], v[184:187], v[114:117]
	v_mfma_f32_16x16x32_bf16 v[110:113], v[230:233], v[192:195], v[110:113]
	v_mfma_f32_16x16x32_bf16 v[106:109], v[238:241], v[192:195], v[106:109]
	v_mfma_f32_16x16x32_bf16 v[102:105], v[230:233], v[222:225], v[102:105]
	v_mfma_f32_16x16x32_bf16 v[98:101], v[238:241], v[222:225], v[98:101]
	v_mfma_f32_16x16x32_bf16 v[126:129], v[234:237], v[180:183], v[126:129]
	v_mfma_f32_16x16x32_bf16 v[122:125], v[242:245], v[180:183], v[122:125]
	v_mfma_f32_16x16x32_bf16 v[118:121], v[234:237], v[188:191], v[118:121]
	v_mfma_f32_16x16x32_bf16 v[114:117], v[242:245], v[188:191], v[114:117]
	v_mfma_f32_16x16x32_bf16 v[110:113], v[234:237], v[196:199], v[110:113]
	v_mfma_f32_16x16x32_bf16 v[106:109], v[242:245], v[196:199], v[106:109]
	v_mfma_f32_16x16x32_bf16 v[102:105], v[234:237], v[226:229], v[102:105]
	v_mfma_f32_16x16x32_bf16 v[98:101], v[242:245], v[226:229], v[98:101]
	s_mov_b32 m0, s58
	v_lshl_add_u64 v[248:249], s[54:55], 0, v[142:143]
	s_barrier
	ds_read_b128 v[176:179], v162 offset:16384
	ds_read_b128 v[180:183], v162 offset:17408
	ds_read_b128 v[184:187], v162 offset:18432
	ds_read_b128 v[188:191], v162 offset:19456
	ds_read_b128 v[192:195], v162 offset:20480
	ds_read_b128 v[196:199], v162 offset:21504
	ds_read_b128 v[222:225], v162 offset:22528
	ds_read_b128 v[226:229], v162 offset:23552
	global_load_lds_dwordx4 v[248:249], off
	v_lshl_add_u64 v[250:251], s[54:55], 0, v[132:133]
	s_mov_b32 m0, s59
	s_nop 0
	global_load_lds_dwordx4 v[250:251], off
	s_barrier
	s_waitcnt lgkmcnt(0)
	v_mfma_f32_16x16x32_bf16 v[38:41], v[152:155], v[176:179], v[38:41]
	v_mfma_f32_16x16x32_bf16 v[34:37], v[168:171], v[176:179], v[34:37]
	v_mfma_f32_16x16x32_bf16 v[30:33], v[152:155], v[184:187], v[30:33]
	v_mfma_f32_16x16x32_bf16 v[26:29], v[168:171], v[184:187], v[26:29]
	v_mfma_f32_16x16x32_bf16 v[14:17], v[152:155], v[192:195], v[14:17]
	v_mfma_f32_16x16x32_bf16 v[10:13], v[168:171], v[192:195], v[10:13]
	v_mfma_f32_16x16x32_bf16 v[6:9], v[152:155], v[222:225], v[6:9]
	v_mfma_f32_16x16x32_bf16 v[2:5], v[168:171], v[222:225], v[2:5]
	v_mfma_f32_16x16x32_bf16 v[38:41], v[164:167], v[180:183], v[38:41]
	v_mfma_f32_16x16x32_bf16 v[34:37], v[172:175], v[180:183], v[34:37]
	v_mfma_f32_16x16x32_bf16 v[30:33], v[164:167], v[188:191], v[30:33]
	v_mfma_f32_16x16x32_bf16 v[26:29], v[172:175], v[188:191], v[26:29]
	v_mfma_f32_16x16x32_bf16 v[14:17], v[164:167], v[196:199], v[14:17]
	v_mfma_f32_16x16x32_bf16 v[10:13], v[172:175], v[196:199], v[10:13]
	v_mfma_f32_16x16x32_bf16 v[6:9], v[164:167], v[226:229], v[6:9]
	v_mfma_f32_16x16x32_bf16 v[2:5], v[172:175], v[226:229], v[2:5]
	s_barrier
	s_add_u32 s72, s52, 0x40000
	s_addc_u32 s73, s53, 0
	s_add_i32 s71, s74, s57
	v_lshl_add_u64 v[152:153], s[72:73], 0, v[0:1]
	s_mov_b32 m0, s71
	s_nop 0
	global_load_lds_dwordx4 v[152:153], off
	v_lshl_add_u64 v[152:153], s[72:73], 0, v[130:131]
	s_add_i32 m0, s71, 0x2000
	s_nop 0
	global_load_lds_dwordx4 v[152:153], off
	s_waitcnt vmcnt(6)
	s_barrier
	v_mfma_f32_16x16x32_bf16 v[94:97], v[230:233], v[176:179], v[94:97]
	v_mfma_f32_16x16x32_bf16 v[90:93], v[238:241], v[176:179], v[90:93]
	v_mfma_f32_16x16x32_bf16 v[86:89], v[230:233], v[184:187], v[86:89]
	v_mfma_f32_16x16x32_bf16 v[82:85], v[238:241], v[184:187], v[82:85]
	v_mfma_f32_16x16x32_bf16 v[78:81], v[230:233], v[192:195], v[78:81]
	v_mfma_f32_16x16x32_bf16 v[74:77], v[238:241], v[192:195], v[74:77]
	v_mfma_f32_16x16x32_bf16 v[22:25], v[230:233], v[222:225], v[22:25]
	v_mfma_f32_16x16x32_bf16 v[18:21], v[238:241], v[222:225], v[18:21]
	v_mfma_f32_16x16x32_bf16 v[94:97], v[234:237], v[180:183], v[94:97]
	v_mfma_f32_16x16x32_bf16 v[90:93], v[242:245], v[180:183], v[90:93]
	v_mfma_f32_16x16x32_bf16 v[86:89], v[234:237], v[188:191], v[86:89]
	v_mfma_f32_16x16x32_bf16 v[82:85], v[242:245], v[188:191], v[82:85]
	v_mfma_f32_16x16x32_bf16 v[78:81], v[234:237], v[196:199], v[78:81]
	v_mfma_f32_16x16x32_bf16 v[74:77], v[242:245], v[196:199], v[74:77]
	v_mfma_f32_16x16x32_bf16 v[22:25], v[234:237], v[226:229], v[22:25]
	v_mfma_f32_16x16x32_bf16 v[18:21], v[242:245], v[226:229], v[18:21]
	s_add_i32 s71, 0, 0x18000
	v_add_u32_e32 v163, s71, v160
	s_barrier
	ds_read_b128 v[152:155], v163
	ds_read_b128 v[164:167], v163 offset:1024
	ds_read_b128 v[168:171], v163 offset:2048
	ds_read_b128 v[172:175], v163 offset:3072
	s_add_u32 s54, s54, 0x40000
	s_addc_u32 s55, s55, 0
	s_mov_b32 m0, s60
	v_lshl_add_u64 v[230:231], s[54:55], 0, v[142:143]
	ds_read_b128 v[176:179], v162 offset:32768
	ds_read_b128 v[180:183], v162 offset:33792
	ds_read_b128 v[184:187], v162 offset:34816
	ds_read_b128 v[188:191], v162 offset:35840
	ds_read_b128 v[192:195], v162 offset:36864
	ds_read_b128 v[196:199], v162 offset:37888
	ds_read_b128 v[222:225], v162 offset:38912
	ds_read_b128 v[226:229], v162 offset:39936
	global_load_lds_dwordx4 v[230:231], off
	v_lshl_add_u64 v[230:231], s[54:55], 0, v[132:133]
	s_mov_b32 m0, s61
	s_nop 0
	global_load_lds_dwordx4 v[230:231], off
	s_waitcnt lgkmcnt(8)
	s_barrier
; #define PG8_STAGE(bufoff, gbase, voff) do { _Pragma("unroll") for (int _i = 0; _i < 2; ++_i) \
;     __builtin_amdgcn_global_load_lds((const unsigned*)((const char*)(gbase) + (voff)[_i]), (PG8_LAS unsigned*)(lds + (bufoff) + ldsw + _i * 8192), 16, 0, 0); } while (0)
; #define PG8_LDA(dst, b, h) do { _Pragma("unroll") for (int m = 0; m < 4; ++m) _Pragma("unroll") for (int k = 0; k < 2; ++k) dst[m][k] = *(const PG8_LAS bf16x8*)(lds + PG8_SA(b, h) + aoff + m * 2048 + k * 1024); } while (0)
; #define PG8_LDB(dst, b, h) do { _Pragma("unroll") for (int n = 0; n < 2; ++n) _Pragma("unroll") for (int k = 0; k < 2; ++k) dst[n][k] = *(const PG8_LAS bf16x8*)(lds + PG8_SB(b, h) + boff + n * 2048 + k * 1024); } while (0)
; #define PG8_MMA(ai, bj, At, Bt) do { __builtin_amdgcn_s_setprio(1); _Pragma("unroll") for (int m = 0; m < 4; ++m) _Pragma("unroll") for (int n = 0; n < 2; ++n) _Pragma("unroll") for (int k = 0; k < 2; ++k) \
;     acc[ai][bj][m][n] = __builtin_amdgcn_mfma_f32_16x16x32_bf16(Bt[n][k], At[m][k], acc[ai][bj][m][n], 0, 0, 0); __builtin_amdgcn_s_setprio(0); } while (0)
; #define PG8_WAIT_V(n) asm volatile("s_waitcnt vmcnt(" #n ")" ::: "memory")
; #define PG8_WAIT_L(n) asm volatile("s_waitcnt lgkmcnt(" #n ")" ::: "memory")
; #define PG8_BAR __builtin_amdgcn_s_barrier()
; #define PG8_SCHED __builtin_amdgcn_sched_barrier(0)
; template <class Epi>
; DI void gemm_phase(PG8_LAS unsigned char* lds, const Gemm g, const StaticOrder& S, const Epi& E) {
;     ...
;       PG8_WAIT_L(8); PG8_BAR; PG8_WAIT_L(0); PG8_MMA(0, 0, At, B0); PG8_BAR; PG8_SCHED;
;       PG8_LDB(B1, 1, 1); PG8_STAGE(PG8_SB(1, 0), b3, voffB);
;       PG8_BAR; PG8_WAIT_L(0); PG8_MMA(0, 1, At, B1); PG8_BAR;
;       PG8_LDA(At, 1, 1); PG8_STAGE(PG8_SA(1, 0), a3, voffA);
;       PG8_BAR; PG8_WAIT_L(0); PG8_MMA(1, 0, At, B0); PG8_BAR; PG8_SCHED;
;       PG8_STAGE(PG8_SB(1, 1), b3 + hstepB, voffB);
;       PG8_WAIT_V(6); PG8_BAR; PG8_MMA(1, 1, At, B1); PG8_BAR;
	s_waitcnt lgkmcnt(0)
	v_mfma_f32_16x16x32_bf16 v[70:73], v[152:155], v[176:179], v[70:73]
	v_mfma_f32_16x16x32_bf16 v[66:69], v[168:171], v[176:179], v[66:69]
	v_mfma_f32_16x16x32_bf16 v[62:65], v[152:155], v[184:187], v[62:65]
	v_mfma_f32_16x16x32_bf16 v[58:61], v[168:171], v[184:187], v[58:61]
	v_mfma_f32_16x16x32_bf16 v[54:57], v[152:155], v[192:195], v[54:57]
	v_mfma_f32_16x16x32_bf16 v[50:53], v[168:171], v[192:195], v[50:53]
	v_mfma_f32_16x16x32_bf16 v[46:49], v[152:155], v[222:225], v[46:49]
	v_mfma_f32_16x16x32_bf16 v[42:45], v[168:171], v[222:225], v[42:45]
	v_mfma_f32_16x16x32_bf16 v[70:73], v[164:167], v[180:183], v[70:73]
	v_mfma_f32_16x16x32_bf16 v[66:69], v[172:175], v[180:183], v[66:69]
	v_mfma_f32_16x16x32_bf16 v[62:65], v[164:167], v[188:191], v[62:65]
	v_mfma_f32_16x16x32_bf16 v[58:61], v[172:175], v[188:191], v[58:61]
	v_mfma_f32_16x16x32_bf16 v[54:57], v[164:167], v[196:199], v[54:57]
	v_mfma_f32_16x16x32_bf16 v[50:53], v[172:175], v[196:199], v[50:53]
	v_mfma_f32_16x16x32_bf16 v[46:49], v[164:167], v[226:229], v[46:49]
	v_mfma_f32_16x16x32_bf16 v[42:45], v[172:175], v[226:229], v[42:45]
	s_barrier
	s_add_i32 s54, 0, 0x1c000
	s_add_i32 s55, s71, s57
	v_add_u32_e32 v163, s54, v160
	v_lshl_add_u64 v[156:157], v[156:157], 0, s[86:87]
	s_mov_b32 m0, s55
	ds_read_b128 v[230:233], v163
	ds_read_b128 v[234:237], v163 offset:1024
	ds_read_b128 v[238:241], v163 offset:2048
	ds_read_b128 v[242:245], v163 offset:3072
	global_load_lds_dwordx4 v[156:157], off
	v_lshl_add_u64 v[156:157], v[246:247], 0, s[86:87]
	s_add_i32 m0, s55, 0x2000
	s_nop 0
	global_load_lds_dwordx4 v[156:157], off
	s_barrier
	s_waitcnt lgkmcnt(0)
	v_mfma_f32_16x16x32_bf16 v[126:129], v[230:233], v[176:179], v[126:129]
	v_mfma_f32_16x16x32_bf16 v[122:125], v[238:241], v[176:179], v[122:125]
	v_mfma_f32_16x16x32_bf16 v[118:121], v[230:233], v[184:187], v[118:121]
	v_mfma_f32_16x16x32_bf16 v[114:117], v[238:241], v[184:187], v[114:117]
	v_mfma_f32_16x16x32_bf16 v[110:113], v[230:233], v[192:195], v[110:113]
	v_mfma_f32_16x16x32_bf16 v[106:109], v[238:241], v[192:195], v[106:109]
	v_mfma_f32_16x16x32_bf16 v[102:105], v[230:233], v[222:225], v[102:105]
	v_mfma_f32_16x16x32_bf16 v[98:101], v[238:241], v[222:225], v[98:101]
	v_mfma_f32_16x16x32_bf16 v[126:129], v[234:237], v[180:183], v[126:129]
	v_mfma_f32_16x16x32_bf16 v[122:125], v[242:245], v[180:183], v[122:125]
	v_mfma_f32_16x16x32_bf16 v[118:121], v[234:237], v[188:191], v[118:121]
	v_mfma_f32_16x16x32_bf16 v[114:117], v[242:245], v[188:191], v[114:117]
	v_mfma_f32_16x16x32_bf16 v[110:113], v[234:237], v[196:199], v[110:113]
	v_mfma_f32_16x16x32_bf16 v[106:109], v[242:245], v[196:199], v[106:109]
	v_mfma_f32_16x16x32_bf16 v[102:105], v[234:237], v[226:229], v[102:105]
	v_mfma_f32_16x16x32_bf16 v[98:101], v[242:245], v[226:229], v[98:101]
	s_mov_b32 m0, s34
	v_lshl_add_u64 v[156:157], v[248:249], 0, s[86:87]
	s_barrier
	ds_read_b128 v[176:179], v162 offset:49152
	ds_read_b128 v[180:183], v162 offset:50176
	ds_read_b128 v[184:187], v162 offset:51200
	ds_read_b128 v[188:191], v162 offset:52224
	ds_read_b128 v[192:195], v162 offset:53248
	ds_read_b128 v[196:199], v162 offset:54272
	ds_read_b128 v[222:225], v162 offset:55296
	ds_read_b128 v[226:229], v162 offset:56320
	global_load_lds_dwordx4 v[156:157], off
	v_lshl_add_u64 v[156:157], v[250:251], 0, s[86:87]
	s_mov_b32 m0, s62
	s_nop 0
	global_load_lds_dwordx4 v[156:157], off
	s_barrier
	s_waitcnt lgkmcnt(0)
	v_mfma_f32_16x16x32_bf16 v[38:41], v[152:155], v[176:179], v[38:41]
	v_mfma_f32_16x16x32_bf16 v[34:37], v[168:171], v[176:179], v[34:37]
	v_mfma_f32_16x16x32_bf16 v[30:33], v[152:155], v[184:187], v[30:33]
	v_mfma_f32_16x16x32_bf16 v[26:29], v[168:171], v[184:187], v[26:29]
	v_mfma_f32_16x16x32_bf16 v[14:17], v[152:155], v[192:195], v[14:17]
	v_mfma_f32_16x16x32_bf16 v[10:13], v[168:171], v[192:195], v[10:13]
	v_mfma_f32_16x16x32_bf16 v[6:9], v[152:155], v[222:225], v[6:9]
	v_mfma_f32_16x16x32_bf16 v[2:5], v[168:171], v[222:225], v[2:5]
	v_mfma_f32_16x16x32_bf16 v[38:41], v[164:167], v[180:183], v[38:41]
	v_mfma_f32_16x16x32_bf16 v[34:37], v[172:175], v[180:183], v[34:37]
	v_mfma_f32_16x16x32_bf16 v[30:33], v[164:167], v[188:191], v[30:33]
	v_mfma_f32_16x16x32_bf16 v[26:29], v[172:175], v[188:191], v[26:29]
	v_mfma_f32_16x16x32_bf16 v[14:17], v[164:167], v[196:199], v[14:17]
	v_mfma_f32_16x16x32_bf16 v[10:13], v[172:175], v[196:199], v[10:13]
	v_mfma_f32_16x16x32_bf16 v[6:9], v[164:167], v[226:229], v[6:9]
	v_mfma_f32_16x16x32_bf16 v[2:5], v[172:175], v[226:229], v[2:5]
	s_barrier
	s_add_u32 s52, s52, 0x40080
	s_addc_u32 s53, s53, 0
	s_add_i32 s54, s54, s57
	v_lshl_add_u64 v[152:153], s[52:53], 0, v[0:1]
	s_mov_b32 m0, s54
	s_nop 0
	global_load_lds_dwordx4 v[152:153], off
	v_lshl_add_u64 v[152:153], s[52:53], 0, v[130:131]
	s_add_i32 m0, s54, 0x2000
	s_nop 0
	global_load_lds_dwordx4 v[152:153], off
	s_waitcnt vmcnt(6)
	s_barrier
	v_mfma_f32_16x16x32_bf16 v[94:97], v[230:233], v[176:179], v[94:97]
	v_mfma_f32_16x16x32_bf16 v[90:93], v[238:241], v[176:179], v[90:93]
	v_mfma_f32_16x16x32_bf16 v[86:89], v[230:233], v[184:187], v[86:89]
	v_mfma_f32_16x16x32_bf16 v[82:85], v[238:241], v[184:187], v[82:85]
	v_mfma_f32_16x16x32_bf16 v[78:81], v[230:233], v[192:195], v[78:81]
	v_mfma_f32_16x16x32_bf16 v[74:77], v[238:241], v[192:195], v[74:77]
	v_mfma_f32_16x16x32_bf16 v[22:25], v[230:233], v[222:225], v[22:25]
	v_mfma_f32_16x16x32_bf16 v[18:21], v[238:241], v[222:225], v[18:21]
	v_mfma_f32_16x16x32_bf16 v[94:97], v[234:237], v[180:183], v[94:97]
	v_mfma_f32_16x16x32_bf16 v[90:93], v[242:245], v[180:183], v[90:93]
	v_mfma_f32_16x16x32_bf16 v[86:89], v[234:237], v[188:191], v[86:89]
	v_mfma_f32_16x16x32_bf16 v[82:85], v[242:245], v[188:191], v[82:85]
	v_mfma_f32_16x16x32_bf16 v[78:81], v[234:237], v[196:199], v[78:81]
	v_mfma_f32_16x16x32_bf16 v[74:77], v[242:245], v[196:199], v[74:77]
	v_mfma_f32_16x16x32_bf16 v[22:25], v[234:237], v[226:229], v[22:25]
	v_mfma_f32_16x16x32_bf16 v[18:21], v[242:245], v[226:229], v[18:21]
	s_add_i32 s70, s70, 2
	s_add_u32 s30, s30, 0x100
	s_addc_u32 s31, s31, 0
	s_add_u32 s68, s68, 0x100
	s_addc_u32 s69, s69, 0
	s_cmp_gt_u32 s70, 13
	s_barrier
	s_cbranch_scc0 .LBB0_1175

; #define PG8_STAGE(bufoff, gbase, voff) do { _Pragma("unroll") for (int _i = 0; _i < 2; ++_i) \
;     __builtin_amdgcn_global_load_lds((const unsigned*)((const char*)(gbase) + (voff)[_i]), (PG8_LAS unsigned*)(lds + (bufoff) + ldsw + _i * 8192), 16, 0, 0); } while (0)
; #define PG8_LDA(dst, b, h) do { _Pragma("unroll") for (int m = 0; m < 4; ++m) _Pragma("unroll") for (int k = 0; k < 2; ++k) dst[m][k] = *(const PG8_LAS bf16x8*)(lds + PG8_SA(b, h) + aoff + m * 2048 + k * 1024); } while (0)
; #define PG8_LDB(dst, b, h) do { _Pragma("unroll") for (int n = 0; n < 2; ++n) _Pragma("unroll") for (int k = 0; k < 2; ++k) dst[n][k] = *(const PG8_LAS bf16x8*)(lds + PG8_SB(b, h) + boff + n * 2048 + k * 1024); } while (0)
; #define PG8_MMA(ai, bj, At, Bt) do { __builtin_amdgcn_s_setprio(1); _Pragma("unroll") for (int m = 0; m < 4; ++m) _Pragma("unroll") for (int n = 0; n < 2; ++n) _Pragma("unroll") for (int k = 0; k < 2; ++k) \
;     acc[ai][bj][m][n] = __builtin_amdgcn_mfma_f32_16x16x32_bf16(Bt[n][k], At[m][k], acc[ai][bj][m][n], 0, 0, 0); __builtin_amdgcn_s_setprio(0); } while (0)
; #define PG8_WAIT_L(n) asm volatile("s_waitcnt lgkmcnt(" #n ")" ::: "memory")
; #define PG8_BAR __builtin_amdgcn_s_barrier()
; #define PG8_SCHED __builtin_amdgcn_sched_barrier(0)
; template <class Epi>
; DI void gemm_phase(PG8_LAS unsigned char* lds, const Gemm g, const StaticOrder& S, const Epi& E) {
;     ...
;     const bool has_next = S.next(ui + 1, nxt);
;     const char* nA = has_next ? (const char*)g.A + (size_t)nxt.pm * tstepA : cA; const char* nB = has_next ? (const char*)g.Bt + (size_t)nxt.pn * tstepB : cB;
;     for (int t = 0; t < nt; t += 2) {
;       const bool last = (t == nt - 2);
;       const char* a1 = cA + (size_t)(t + 1) * kstep;
;       const char* a2 = last ? nA : cA + (size_t)(t + 2) * kstep; const char* b2 = last ? nB : cB + (size_t)(t + 2) * kstep;
;       const char* a3 = a2 + kstep; const char* b3 = b2 + kstep;
;       PG8_LDB(B0, 0, 0); PG8_SCHED; PG8_LDA(At, 0, 0); PG8_STAGE(PG8_SA(1, 1), a1 + hstepA, voffA);
;       PG8_WAIT_L(8); PG8_BAR; PG8_WAIT_L(0); PG8_MMA(0, 0, At, B0); PG8_BAR; PG8_SCHED;
;       PG8_LDB(B1, 0, 1); PG8_STAGE(PG8_SB(0, 0), b2, voffB);
;       PG8_BAR; PG8_WAIT_L(0); PG8_MMA(0, 1, At, B1); PG8_BAR;
;       PG8_LDA(At, 0, 1); PG8_STAGE(PG8_SA(0, 0), a2, voffA);
;       PG8_BAR; PG8_WAIT_L(0); PG8_MMA(1, 0, At, B0); PG8_BAR; PG8_SCHED;
.LBB0_1196:
	s_ashr_i32 s43, s42, 31
	v_cmp_lt_i64_e32 vcc, s[44:45], v[140:141]
	s_lshl_b64 s[44:45], s[42:43], 19
	s_add_u32 s44, s22, s44
	s_addc_u32 s45, s23, s45
	s_and_b64 s[46:47], vcc, exec
	s_cselect_b32 s43, s45, s49
	s_cselect_b32 s63, s44, s48
	s_ashr_i32 s31, s30, 31
	v_readlane_b32 s4, v253, 16
	s_lshl_b64 s[46:47], s[30:31], 19
	v_readlane_b32 s14, v253, 26
	v_readlane_b32 s15, v253, 27
	s_add_u32 s46, s14, s46
	s_addc_u32 s47, s15, s47
	s_and_b64 s[52:53], vcc, exec
	s_cselect_b32 s31, s47, s51
	s_cselect_b32 s64, s46, s50
	s_add_u32 s48, s48, 0x40080
	s_addc_u32 s49, s49, 0
	s_add_u32 s65, s50, 0x100
	v_mov_b32_e32 v2, 0
	s_addc_u32 s66, s51, 0
	s_mov_b32 s67, -2
	v_readlane_b32 s5, v253, 17
	v_readlane_b32 s6, v253, 18
	v_readlane_b32 s7, v253, 19
	v_readlane_b32 s8, v253, 20
	v_readlane_b32 s9, v253, 21
	v_readlane_b32 s10, v253, 22
	v_readlane_b32 s11, v253, 23
	v_readlane_b32 s12, v253, 24
	v_readlane_b32 s13, v253, 25
	v_readlane_b32 s16, v253, 28
	v_readlane_b32 s17, v253, 29
	v_readlane_b32 s18, v253, 30
	v_readlane_b32 s19, v253, 31
	s_add_u32 s50, s48, 0xfffc0080
	s_addc_u32 s51, s49, -1
	s_add_i32 s68, 0, 0x10000
	v_add_u32_e32 v157, s68, v153
	ds_read_b128 v[148:151], v157
	ds_read_b128 v[158:161], v157 offset:1024
	ds_read_b128 v[162:165], v157 offset:2048
	ds_read_b128 v[166:169], v157 offset:3072
	s_cmp_eq_u32 s67, 12
	s_cselect_b32 s53, s43, s51
	s_cselect_b32 s52, s63, s50
	s_cselect_b32 s51, s31, s66
	s_cselect_b32 s50, s64, s65
	v_lshl_add_u64 v[198:199], s[48:49], 0, v[144:145]
	s_add_i32 m0, s37, 0xc000
	ds_read_b128 v[170:173], v156
	ds_read_b128 v[174:177], v156 offset:1024
	ds_read_b128 v[178:181], v156 offset:2048
	ds_read_b128 v[182:185], v156 offset:3072
	ds_read_b128 v[186:189], v156 offset:4096
	ds_read_b128 v[190:193], v156 offset:5120
	ds_read_b128 v[194:197], v156 offset:6144
	ds_read_b128 v[222:225], v156 offset:7168
	global_load_lds_dwordx4 v[198:199], off
	v_lshl_add_u64 v[198:199], s[48:49], 0, v[146:147]
	s_add_i32 m0, s37, 0xe000
	s_nop 0
	global_load_lds_dwordx4 v[198:199], off
	s_waitcnt lgkmcnt(8)
	s_barrier
	s_waitcnt lgkmcnt(0)
	v_mfma_f32_16x16x32_bf16 v[126:129], v[148:151], v[170:173], 0
	v_mfma_f32_16x16x32_bf16 v[122:125], v[162:165], v[170:173], 0
	v_mfma_f32_16x16x32_bf16 v[118:121], v[148:151], v[178:181], 0
	v_mfma_f32_16x16x32_bf16 v[110:113], v[162:165], v[178:181], 0
	v_mfma_f32_16x16x32_bf16 v[94:97], v[148:151], v[186:189], 0
	v_mfma_f32_16x16x32_bf16 v[90:93], v[162:165], v[186:189], 0
	v_mfma_f32_16x16x32_bf16 v[86:89], v[148:151], v[194:197], 0
	v_mfma_f32_16x16x32_bf16 v[78:81], v[162:165], v[194:197], 0
	v_mfma_f32_16x16x32_bf16 v[126:129], v[158:161], v[174:177], v[126:129]
	v_mfma_f32_16x16x32_bf16 v[122:125], v[166:169], v[174:177], v[122:125]
	v_mfma_f32_16x16x32_bf16 v[118:121], v[158:161], v[182:185], v[118:121]
	v_mfma_f32_16x16x32_bf16 v[110:113], v[166:169], v[182:185], v[110:113]
	v_mfma_f32_16x16x32_bf16 v[94:97], v[158:161], v[190:193], v[94:97]
	v_mfma_f32_16x16x32_bf16 v[90:93], v[166:169], v[190:193], v[90:93]
	v_mfma_f32_16x16x32_bf16 v[86:89], v[158:161], v[222:225], v[86:89]
	v_mfma_f32_16x16x32_bf16 v[78:81], v[166:169], v[222:225], v[78:81]
	s_barrier
	s_add_i32 s70, 0, 0x14000
	s_add_i32 s68, s68, s34
	v_add_u32_e32 v157, s70, v153
	v_lshl_add_u64 v[198:199], s[50:51], 0, v[0:1]
	s_mov_b32 m0, s68
	ds_read_b128 v[226:229], v157
	ds_read_b128 v[230:233], v157 offset:1024
	ds_read_b128 v[234:237], v157 offset:2048
	ds_read_b128 v[238:241], v157 offset:3072
	global_load_lds_dwordx4 v[198:199], off
	v_lshl_add_u64 v[242:243], s[50:51], 0, v[130:131]
	s_add_i32 m0, s68, 0x2000
	s_nop 0
	global_load_lds_dwordx4 v[242:243], off
	s_barrier
	s_waitcnt lgkmcnt(0)
	v_mfma_f32_16x16x32_bf16 v[114:117], v[226:229], v[170:173], 0
	v_mfma_f32_16x16x32_bf16 v[106:109], v[234:237], v[170:173], 0
	v_mfma_f32_16x16x32_bf16 v[102:105], v[226:229], v[178:181], 0
	v_mfma_f32_16x16x32_bf16 v[98:101], v[234:237], v[178:181], 0
	v_mfma_f32_16x16x32_bf16 v[82:85], v[226:229], v[186:189], 0
	v_mfma_f32_16x16x32_bf16 v[74:77], v[234:237], v[186:189], 0
	v_mfma_f32_16x16x32_bf16 v[70:73], v[226:229], v[194:197], 0
	v_mfma_f32_16x16x32_bf16 v[66:69], v[234:237], v[194:197], 0
	v_mfma_f32_16x16x32_bf16 v[114:117], v[230:233], v[174:177], v[114:117]
	v_mfma_f32_16x16x32_bf16 v[106:109], v[238:241], v[174:177], v[106:109]
	v_mfma_f32_16x16x32_bf16 v[102:105], v[230:233], v[182:185], v[102:105]
	v_mfma_f32_16x16x32_bf16 v[98:101], v[238:241], v[182:185], v[98:101]
	v_mfma_f32_16x16x32_bf16 v[82:85], v[230:233], v[190:193], v[82:85]
	v_mfma_f32_16x16x32_bf16 v[74:77], v[238:241], v[190:193], v[74:77]
	v_mfma_f32_16x16x32_bf16 v[70:73], v[230:233], v[222:225], v[70:73]
	v_mfma_f32_16x16x32_bf16 v[66:69], v[238:241], v[222:225], v[66:69]
	s_mov_b32 m0, s37
	v_lshl_add_u64 v[244:245], s[52:53], 0, v[142:143]
	s_barrier
	ds_read_b128 v[170:173], v156 offset:16384
	ds_read_b128 v[174:177], v156 offset:17408
	ds_read_b128 v[178:181], v156 offset:18432
	ds_read_b128 v[182:185], v156 offset:19456
	ds_read_b128 v[186:189], v156 offset:20480
	ds_read_b128 v[190:193], v156 offset:21504
	ds_read_b128 v[194:197], v156 offset:22528
	ds_read_b128 v[222:225], v156 offset:23552
	global_load_lds_dwordx4 v[244:245], off
	v_lshl_add_u64 v[246:247], s[52:53], 0, v[132:133]
	s_mov_b32 m0, s54
	s_nop 0
	global_load_lds_dwordx4 v[246:247], off
	s_barrier
; #define PG8_STAGE(bufoff, gbase, voff) do { _Pragma("unroll") for (int _i = 0; _i < 2; ++_i) \
;     __builtin_amdgcn_global_load_lds((const unsigned*)((const char*)(gbase) + (voff)[_i]), (PG8_LAS unsigned*)(lds + (bufoff) + ldsw + _i * 8192), 16, 0, 0); } while (0)
; #define PG8_LDA(dst, b, h) do { _Pragma("unroll") for (int m = 0; m < 4; ++m) _Pragma("unroll") for (int k = 0; k < 2; ++k) dst[m][k] = *(const PG8_LAS bf16x8*)(lds + PG8_SA(b, h) + aoff + m * 2048 + k * 1024); } while (0)
; #define PG8_LDB(dst, b, h) do { _Pragma("unroll") for (int n = 0; n < 2; ++n) _Pragma("unroll") for (int k = 0; k < 2; ++k) dst[n][k] = *(const PG8_LAS bf16x8*)(lds + PG8_SB(b, h) + boff + n * 2048 + k * 1024); } while (0)
; #define PG8_MMA(ai, bj, At, Bt) do { __builtin_amdgcn_s_setprio(1); _Pragma("unroll") for (int m = 0; m < 4; ++m) _Pragma("unroll") for (int n = 0; n < 2; ++n) _Pragma("unroll") for (int k = 0; k < 2; ++k) \
;     acc[ai][bj][m][n] = __builtin_amdgcn_mfma_f32_16x16x32_bf16(Bt[n][k], At[m][k], acc[ai][bj][m][n], 0, 0, 0); __builtin_amdgcn_s_setprio(0); } while (0)
; #define PG8_WAIT_V(n) asm volatile("s_waitcnt vmcnt(" #n ")" ::: "memory")
; #define PG8_WAIT_L(n) asm volatile("s_waitcnt lgkmcnt(" #n ")" ::: "memory")
; #define PG8_BAR __builtin_amdgcn_s_barrier()
; #define PG8_SCHED __builtin_amdgcn_sched_barrier(0)
; template <class Epi>
; DI void gemm_phase(PG8_LAS unsigned char* lds, const Gemm g, const StaticOrder& S, const Epi& E) {
;     ...
;       PG8_BAR; PG8_WAIT_L(0); PG8_MMA(1, 0, At, B0); PG8_BAR; PG8_SCHED;
;       PG8_STAGE(PG8_SB(0, 1), b2 + hstepB, voffB);
;       PG8_WAIT_V(6); PG8_BAR; PG8_MMA(1, 1, At, B1); PG8_BAR;
;       PG8_LDB(B0, 1, 0); PG8_SCHED; PG8_LDA(At, 1, 0); PG8_STAGE(PG8_SA(0, 1), a2 + hstepA, voffA);
;       PG8_WAIT_L(8); PG8_BAR; PG8_WAIT_L(0); PG8_MMA(0, 0, At, B0); PG8_BAR; PG8_SCHED;
;       PG8_LDB(B1, 1, 1); PG8_STAGE(PG8_SB(1, 0), b3, voffB);
	s_waitcnt lgkmcnt(0)
	v_mfma_f32_16x16x32_bf16 v[62:65], v[148:151], v[170:173], 0
	v_mfma_f32_16x16x32_bf16 v[58:61], v[162:165], v[170:173], 0
	v_mfma_f32_16x16x32_bf16 v[54:57], v[148:151], v[178:181], 0
	v_mfma_f32_16x16x32_bf16 v[46:49], v[162:165], v[178:181], 0
	v_mfma_f32_16x16x32_bf16 v[30:33], v[148:151], v[186:189], 0
	v_mfma_f32_16x16x32_bf16 v[26:29], v[162:165], v[186:189], 0
	v_mfma_f32_16x16x32_bf16 v[22:25], v[148:151], v[194:197], 0
	v_mfma_f32_16x16x32_bf16 v[14:17], v[162:165], v[194:197], 0
	v_mfma_f32_16x16x32_bf16 v[62:65], v[158:161], v[174:177], v[62:65]
	v_mfma_f32_16x16x32_bf16 v[58:61], v[166:169], v[174:177], v[58:61]
	v_mfma_f32_16x16x32_bf16 v[54:57], v[158:161], v[182:185], v[54:57]
	v_mfma_f32_16x16x32_bf16 v[46:49], v[166:169], v[182:185], v[46:49]
	v_mfma_f32_16x16x32_bf16 v[30:33], v[158:161], v[190:193], v[30:33]
	v_mfma_f32_16x16x32_bf16 v[26:29], v[166:169], v[190:193], v[26:29]
	v_mfma_f32_16x16x32_bf16 v[22:25], v[158:161], v[222:225], v[22:25]
	v_mfma_f32_16x16x32_bf16 v[14:17], v[166:169], v[222:225], v[14:17]
	s_barrier
	s_add_u32 s68, s50, 0x40000
	s_addc_u32 s69, s51, 0
	s_add_i32 s70, s70, s34
	v_lshl_add_u64 v[148:149], s[68:69], 0, v[0:1]
	s_mov_b32 m0, s70
	s_nop 0
	global_load_lds_dwordx4 v[148:149], off
	v_lshl_add_u64 v[148:149], s[68:69], 0, v[130:131]
	s_add_i32 m0, s70, 0x2000
	s_nop 0
	global_load_lds_dwordx4 v[148:149], off
	s_waitcnt vmcnt(6)
	s_barrier
	v_mfma_f32_16x16x32_bf16 v[50:53], v[226:229], v[170:173], 0
	v_mfma_f32_16x16x32_bf16 v[42:45], v[234:237], v[170:173], 0
	v_mfma_f32_16x16x32_bf16 v[38:41], v[226:229], v[178:181], 0
	v_mfma_f32_16x16x32_bf16 v[34:37], v[234:237], v[178:181], 0
	v_mfma_f32_16x16x32_bf16 v[18:21], v[226:229], v[186:189], 0
	v_mfma_f32_16x16x32_bf16 v[10:13], v[234:237], v[186:189], 0
	v_mfma_f32_16x16x32_bf16 v[6:9], v[226:229], v[194:197], 0
	v_mfma_f32_16x16x32_bf16 v[2:5], v[234:237], v[194:197], 0
	v_mfma_f32_16x16x32_bf16 v[50:53], v[230:233], v[174:177], v[50:53]
	v_mfma_f32_16x16x32_bf16 v[42:45], v[238:241], v[174:177], v[42:45]
	v_mfma_f32_16x16x32_bf16 v[38:41], v[230:233], v[182:185], v[38:41]
	v_mfma_f32_16x16x32_bf16 v[34:37], v[238:241], v[182:185], v[34:37]
	v_mfma_f32_16x16x32_bf16 v[18:21], v[230:233], v[190:193], v[18:21]
	v_mfma_f32_16x16x32_bf16 v[10:13], v[238:241], v[190:193], v[10:13]
	v_mfma_f32_16x16x32_bf16 v[6:9], v[230:233], v[222:225], v[6:9]
	v_mfma_f32_16x16x32_bf16 v[2:5], v[238:241], v[222:225], v[2:5]
	s_add_i32 s68, 0, 0x18000
	v_add_u32_e32 v157, s68, v153
	s_barrier
	ds_read_b128 v[148:151], v157
	ds_read_b128 v[158:161], v157 offset:1024
	ds_read_b128 v[162:165], v157 offset:2048
	ds_read_b128 v[166:169], v157 offset:3072
	s_add_u32 s52, s52, 0x40000
	s_addc_u32 s53, s53, 0
	s_mov_b32 m0, s55
	v_lshl_add_u64 v[226:227], s[52:53], 0, v[142:143]
	ds_read_b128 v[170:173], v156 offset:32768
	ds_read_b128 v[174:177], v156 offset:33792
	ds_read_b128 v[178:181], v156 offset:34816
	ds_read_b128 v[182:185], v156 offset:35840
	ds_read_b128 v[186:189], v156 offset:36864
	ds_read_b128 v[190:193], v156 offset:37888
	ds_read_b128 v[194:197], v156 offset:38912
	ds_read_b128 v[222:225], v156 offset:39936
	global_load_lds_dwordx4 v[226:227], off
	v_lshl_add_u64 v[226:227], s[52:53], 0, v[132:133]
	s_mov_b32 m0, s56
	s_nop 0
	global_load_lds_dwordx4 v[226:227], off
	s_waitcnt lgkmcnt(8)
	s_barrier
	s_waitcnt lgkmcnt(0)
	v_mfma_f32_16x16x32_bf16 v[126:129], v[148:151], v[170:173], v[126:129]
	v_mfma_f32_16x16x32_bf16 v[122:125], v[162:165], v[170:173], v[122:125]
	v_mfma_f32_16x16x32_bf16 v[118:121], v[148:151], v[178:181], v[118:121]
	v_mfma_f32_16x16x32_bf16 v[110:113], v[162:165], v[178:181], v[110:113]
	v_mfma_f32_16x16x32_bf16 v[94:97], v[148:151], v[186:189], v[94:97]
	v_mfma_f32_16x16x32_bf16 v[90:93], v[162:165], v[186:189], v[90:93]
	v_mfma_f32_16x16x32_bf16 v[86:89], v[148:151], v[194:197], v[86:89]
	v_mfma_f32_16x16x32_bf16 v[78:81], v[162:165], v[194:197], v[78:81]
	v_mfma_f32_16x16x32_bf16 v[126:129], v[158:161], v[174:177], v[126:129]
	v_mfma_f32_16x16x32_bf16 v[122:125], v[166:169], v[174:177], v[122:125]
	v_mfma_f32_16x16x32_bf16 v[118:121], v[158:161], v[182:185], v[118:121]
	v_mfma_f32_16x16x32_bf16 v[110:113], v[166:169], v[182:185], v[110:113]
	v_mfma_f32_16x16x32_bf16 v[94:97], v[158:161], v[190:193], v[94:97]
	v_mfma_f32_16x16x32_bf16 v[90:93], v[166:169], v[190:193], v[90:93]
	v_mfma_f32_16x16x32_bf16 v[86:89], v[158:161], v[222:225], v[86:89]
	v_mfma_f32_16x16x32_bf16 v[78:81], v[166:169], v[222:225], v[78:81]
	s_barrier
	s_add_i32 s52, 0, 0x1c000
	s_add_i32 s53, s68, s34
	v_add_u32_e32 v157, s52, v153
	v_lshl_add_u64 v[198:199], v[198:199], 0, s[86:87]
	s_mov_b32 m0, s53
	ds_read_b128 v[226:229], v157
	ds_read_b128 v[230:233], v157 offset:1024
	ds_read_b128 v[234:237], v157 offset:2048
	ds_read_b128 v[238:241], v157 offset:3072
	global_load_lds_dwordx4 v[198:199], off
	v_lshl_add_u64 v[198:199], v[242:243], 0, s[86:87]
	s_add_i32 m0, s53, 0x2000
	s_nop 0
	global_load_lds_dwordx4 v[198:199], off
	s_barrier
; #define PG8_STAGE(bufoff, gbase, voff) do { _Pragma("unroll") for (int _i = 0; _i < 2; ++_i) \
;     __builtin_amdgcn_global_load_lds((const unsigned*)((const char*)(gbase) + (voff)[_i]), (PG8_LAS unsigned*)(lds + (bufoff) + ldsw + _i * 8192), 16, 0, 0); } while (0)
; #define PG8_LDA(dst, b, h) do { _Pragma("unroll") for (int m = 0; m < 4; ++m) _Pragma("unroll") for (int k = 0; k < 2; ++k) dst[m][k] = *(const PG8_LAS bf16x8*)(lds + PG8_SA(b, h) + aoff + m * 2048 + k * 1024); } while (0)
; #define PG8_MMA(ai, bj, At, Bt) do { __builtin_amdgcn_s_setprio(1); _Pragma("unroll") for (int m = 0; m < 4; ++m) _Pragma("unroll") for (int n = 0; n < 2; ++n) _Pragma("unroll") for (int k = 0; k < 2; ++k) \
;     acc[ai][bj][m][n] = __builtin_amdgcn_mfma_f32_16x16x32_bf16(Bt[n][k], At[m][k], acc[ai][bj][m][n], 0, 0, 0); __builtin_amdgcn_s_setprio(0); } while (0)
; #define PG8_WAIT_V(n) asm volatile("s_waitcnt vmcnt(" #n ")" ::: "memory")
; #define PG8_WAIT_L(n) asm volatile("s_waitcnt lgkmcnt(" #n ")" ::: "memory")
; #define PG8_BAR __builtin_amdgcn_s_barrier()
; #define PG8_SCHED __builtin_amdgcn_sched_barrier(0)
; template <class Epi>
; DI void gemm_phase(PG8_LAS unsigned char* lds, const Gemm g, const StaticOrder& S, const Epi& E) {
;     ...
;       PG8_BAR; PG8_WAIT_L(0); PG8_MMA(0, 1, At, B1); PG8_BAR;
;       PG8_LDA(At, 1, 1); PG8_STAGE(PG8_SA(1, 0), a3, voffA);
;       PG8_BAR; PG8_WAIT_L(0); PG8_MMA(1, 0, At, B0); PG8_BAR; PG8_SCHED;
;       PG8_STAGE(PG8_SB(1, 1), b3 + hstepB, voffB);
;       PG8_WAIT_V(6); PG8_BAR; PG8_MMA(1, 1, At, B1); PG8_BAR;
	s_waitcnt lgkmcnt(0)
	v_mfma_f32_16x16x32_bf16 v[114:117], v[226:229], v[170:173], v[114:117]
	v_mfma_f32_16x16x32_bf16 v[106:109], v[234:237], v[170:173], v[106:109]
	v_mfma_f32_16x16x32_bf16 v[102:105], v[226:229], v[178:181], v[102:105]
	v_mfma_f32_16x16x32_bf16 v[98:101], v[234:237], v[178:181], v[98:101]
	v_mfma_f32_16x16x32_bf16 v[82:85], v[226:229], v[186:189], v[82:85]
	v_mfma_f32_16x16x32_bf16 v[74:77], v[234:237], v[186:189], v[74:77]
	v_mfma_f32_16x16x32_bf16 v[70:73], v[226:229], v[194:197], v[70:73]
	v_mfma_f32_16x16x32_bf16 v[66:69], v[234:237], v[194:197], v[66:69]
	v_mfma_f32_16x16x32_bf16 v[114:117], v[230:233], v[174:177], v[114:117]
	v_mfma_f32_16x16x32_bf16 v[106:109], v[238:241], v[174:177], v[106:109]
	v_mfma_f32_16x16x32_bf16 v[102:105], v[230:233], v[182:185], v[102:105]
	v_mfma_f32_16x16x32_bf16 v[98:101], v[238:241], v[182:185], v[98:101]
	v_mfma_f32_16x16x32_bf16 v[82:85], v[230:233], v[190:193], v[82:85]
	v_mfma_f32_16x16x32_bf16 v[74:77], v[238:241], v[190:193], v[74:77]
	v_mfma_f32_16x16x32_bf16 v[70:73], v[230:233], v[222:225], v[70:73]
	v_mfma_f32_16x16x32_bf16 v[66:69], v[238:241], v[222:225], v[66:69]
	s_mov_b32 m0, s57
	v_lshl_add_u64 v[198:199], v[244:245], 0, s[86:87]
	s_barrier
	ds_read_b128 v[170:173], v156 offset:49152
	ds_read_b128 v[174:177], v156 offset:50176
	ds_read_b128 v[178:181], v156 offset:51200
	ds_read_b128 v[182:185], v156 offset:52224
	ds_read_b128 v[186:189], v156 offset:53248
	ds_read_b128 v[190:193], v156 offset:54272
	ds_read_b128 v[194:197], v156 offset:55296
	ds_read_b128 v[222:225], v156 offset:56320
	global_load_lds_dwordx4 v[198:199], off
	v_lshl_add_u64 v[198:199], v[246:247], 0, s[86:87]
	s_mov_b32 m0, s58
	s_nop 0
	global_load_lds_dwordx4 v[198:199], off
	s_barrier
	s_waitcnt lgkmcnt(0)
	v_mfma_f32_16x16x32_bf16 v[62:65], v[148:151], v[170:173], v[62:65]
	v_mfma_f32_16x16x32_bf16 v[58:61], v[162:165], v[170:173], v[58:61]
	v_mfma_f32_16x16x32_bf16 v[54:57], v[148:151], v[178:181], v[54:57]
	v_mfma_f32_16x16x32_bf16 v[46:49], v[162:165], v[178:181], v[46:49]
	v_mfma_f32_16x16x32_bf16 v[30:33], v[148:151], v[186:189], v[30:33]
	v_mfma_f32_16x16x32_bf16 v[26:29], v[162:165], v[186:189], v[26:29]
	v_mfma_f32_16x16x32_bf16 v[22:25], v[148:151], v[194:197], v[22:25]
	v_mfma_f32_16x16x32_bf16 v[14:17], v[162:165], v[194:197], v[14:17]
	v_mfma_f32_16x16x32_bf16 v[62:65], v[158:161], v[174:177], v[62:65]
	v_mfma_f32_16x16x32_bf16 v[58:61], v[166:169], v[174:177], v[58:61]
	v_mfma_f32_16x16x32_bf16 v[54:57], v[158:161], v[182:185], v[54:57]
	v_mfma_f32_16x16x32_bf16 v[46:49], v[166:169], v[182:185], v[46:49]
	v_mfma_f32_16x16x32_bf16 v[30:33], v[158:161], v[190:193], v[30:33]
	v_mfma_f32_16x16x32_bf16 v[26:29], v[166:169], v[190:193], v[26:29]
	v_mfma_f32_16x16x32_bf16 v[22:25], v[158:161], v[222:225], v[22:25]
	v_mfma_f32_16x16x32_bf16 v[14:17], v[166:169], v[222:225], v[14:17]
	s_barrier
	s_add_u32 s50, s50, 0x40080
	s_addc_u32 s51, s51, 0
	s_add_i32 s52, s52, s34
	v_lshl_add_u64 v[148:149], s[50:51], 0, v[0:1]
	s_mov_b32 m0, s52
	s_nop 0
	global_load_lds_dwordx4 v[148:149], off
	v_lshl_add_u64 v[148:149], s[50:51], 0, v[130:131]
	s_add_i32 m0, s52, 0x2000
	s_nop 0
	global_load_lds_dwordx4 v[148:149], off
	s_waitcnt vmcnt(6)
	s_barrier
	v_mfma_f32_16x16x32_bf16 v[50:53], v[226:229], v[170:173], v[50:53]
	v_mfma_f32_16x16x32_bf16 v[42:45], v[234:237], v[170:173], v[42:45]
	v_mfma_f32_16x16x32_bf16 v[38:41], v[226:229], v[178:181], v[38:41]
	v_mfma_f32_16x16x32_bf16 v[34:37], v[234:237], v[178:181], v[34:37]
	v_mfma_f32_16x16x32_bf16 v[18:21], v[226:229], v[186:189], v[18:21]
	v_mfma_f32_16x16x32_bf16 v[10:13], v[234:237], v[186:189], v[10:13]
	v_mfma_f32_16x16x32_bf16 v[6:9], v[226:229], v[194:197], v[6:9]
	v_mfma_f32_16x16x32_bf16 v[2:5], v[234:237], v[194:197], v[2:5]
	v_mfma_f32_16x16x32_bf16 v[50:53], v[230:233], v[174:177], v[50:53]
	v_mfma_f32_16x16x32_bf16 v[42:45], v[238:241], v[174:177], v[42:45]
	v_mfma_f32_16x16x32_bf16 v[38:41], v[230:233], v[182:185], v[38:41]
	v_mfma_f32_16x16x32_bf16 v[34:37], v[238:241], v[182:185], v[34:37]
	v_mfma_f32_16x16x32_bf16 v[18:21], v[230:233], v[190:193], v[18:21]
	v_mfma_f32_16x16x32_bf16 v[10:13], v[238:241], v[190:193], v[10:13]
	v_mfma_f32_16x16x32_bf16 v[6:9], v[230:233], v[222:225], v[6:9]
	v_mfma_f32_16x16x32_bf16 v[2:5], v[238:241], v[222:225], v[2:5]
	s_add_i32 s67, s67, 2
	s_add_u32 s48, s48, 0x100
	s_addc_u32 s49, s49, 0
	s_add_u32 s65, s65, 0x100
	s_addc_u32 s66, s66, 0
	s_cmp_gt_u32 s67, 13
	s_barrier
	s_cbranch_scc1 .Lpeel_exit_3
; #define PG8_STAGE(bufoff, gbase, voff) do { _Pragma("unroll") for (int _i = 0; _i < 2; ++_i) \
;     __builtin_amdgcn_global_load_lds((const unsigned*)((const char*)(gbase) + (voff)[_i]), (PG8_LAS unsigned*)(lds + (bufoff) + ldsw + _i * 8192), 16, 0, 0); } while (0)
; #define PG8_LDA(dst, b, h) do { _Pragma("unroll") for (int m = 0; m < 4; ++m) _Pragma("unroll") for (int k = 0; k < 2; ++k) dst[m][k] = *(const PG8_LAS bf16x8*)(lds + PG8_SA(b, h) + aoff + m * 2048 + k * 1024); } while (0)
; #define PG8_LDB(dst, b, h) do { _Pragma("unroll") for (int n = 0; n < 2; ++n) _Pragma("unroll") for (int k = 0; k < 2; ++k) dst[n][k] = *(const PG8_LAS bf16x8*)(lds + PG8_SB(b, h) + boff + n * 2048 + k * 1024); } while (0)
; #define PG8_MMA(ai, bj, At, Bt) do { __builtin_amdgcn_s_setprio(1); _Pragma("unroll") for (int m = 0; m < 4; ++m) _Pragma("unroll") for (int n = 0; n < 2; ++n) _Pragma("unroll") for (int k = 0; k < 2; ++k) \
;     acc[ai][bj][m][n] = __builtin_amdgcn_mfma_f32_16x16x32_bf16(Bt[n][k], At[m][k], acc[ai][bj][m][n], 0, 0, 0); __builtin_amdgcn_s_setprio(0); } while (0)
; #define PG8_WAIT_L(n) asm volatile("s_waitcnt lgkmcnt(" #n ")" ::: "memory")
; #define PG8_BAR __builtin_amdgcn_s_barrier()
; #define PG8_SCHED __builtin_amdgcn_sched_barrier(0)
; template <class Epi>
; DI void gemm_phase(PG8_LAS unsigned char* lds, const Gemm g, const StaticOrder& S, const Epi& E) {
;     ...
;       PG8_LDB(B0, 0, 0); PG8_SCHED; PG8_LDA(At, 0, 0); PG8_STAGE(PG8_SA(1, 1), a1 + hstepA, voffA);
;       PG8_WAIT_L(8); PG8_BAR; PG8_WAIT_L(0); PG8_MMA(0, 0, At, B0); PG8_BAR; PG8_SCHED;
;       PG8_LDB(B1, 0, 1); PG8_STAGE(PG8_SB(0, 0), b2, voffB);
;       PG8_BAR; PG8_WAIT_L(0); PG8_MMA(0, 1, At, B1); PG8_BAR;
;       PG8_LDA(At, 0, 1); PG8_STAGE(PG8_SA(0, 0), a2, voffA);
;       PG8_BAR; PG8_WAIT_L(0); PG8_MMA(1, 0, At, B0); PG8_BAR; PG8_SCHED;
.LBB0_1197:
	s_add_u32 s50, s48, 0xfffc0080
	s_addc_u32 s51, s49, -1
	s_add_i32 s68, 0, 0x10000
	v_add_u32_e32 v157, s68, v153
	ds_read_b128 v[148:151], v157
	ds_read_b128 v[158:161], v157 offset:1024
	ds_read_b128 v[162:165], v157 offset:2048
	ds_read_b128 v[166:169], v157 offset:3072
	s_cmp_eq_u32 s67, 12
	s_cselect_b32 s53, s43, s51
	s_cselect_b32 s52, s63, s50
	s_cselect_b32 s51, s31, s66
	s_cselect_b32 s50, s64, s65
	v_lshl_add_u64 v[198:199], s[48:49], 0, v[144:145]
	s_add_i32 m0, s37, 0xc000
	ds_read_b128 v[170:173], v156
	ds_read_b128 v[174:177], v156 offset:1024
	ds_read_b128 v[178:181], v156 offset:2048
	ds_read_b128 v[182:185], v156 offset:3072
	ds_read_b128 v[186:189], v156 offset:4096
	ds_read_b128 v[190:193], v156 offset:5120
	ds_read_b128 v[194:197], v156 offset:6144
	ds_read_b128 v[222:225], v156 offset:7168
	global_load_lds_dwordx4 v[198:199], off
	v_lshl_add_u64 v[198:199], s[48:49], 0, v[146:147]
	s_add_i32 m0, s37, 0xe000
	s_nop 0
	global_load_lds_dwordx4 v[198:199], off
	s_waitcnt lgkmcnt(8)
	s_barrier
	s_waitcnt lgkmcnt(0)
	v_mfma_f32_16x16x32_bf16 v[126:129], v[148:151], v[170:173], v[126:129]
	v_mfma_f32_16x16x32_bf16 v[122:125], v[162:165], v[170:173], v[122:125]
	v_mfma_f32_16x16x32_bf16 v[118:121], v[148:151], v[178:181], v[118:121]
	v_mfma_f32_16x16x32_bf16 v[110:113], v[162:165], v[178:181], v[110:113]
	v_mfma_f32_16x16x32_bf16 v[94:97], v[148:151], v[186:189], v[94:97]
	v_mfma_f32_16x16x32_bf16 v[90:93], v[162:165], v[186:189], v[90:93]
	v_mfma_f32_16x16x32_bf16 v[86:89], v[148:151], v[194:197], v[86:89]
	v_mfma_f32_16x16x32_bf16 v[78:81], v[162:165], v[194:197], v[78:81]
	v_mfma_f32_16x16x32_bf16 v[126:129], v[158:161], v[174:177], v[126:129]
	v_mfma_f32_16x16x32_bf16 v[122:125], v[166:169], v[174:177], v[122:125]
	v_mfma_f32_16x16x32_bf16 v[118:121], v[158:161], v[182:185], v[118:121]
	v_mfma_f32_16x16x32_bf16 v[110:113], v[166:169], v[182:185], v[110:113]
	v_mfma_f32_16x16x32_bf16 v[94:97], v[158:161], v[190:193], v[94:97]
	v_mfma_f32_16x16x32_bf16 v[90:93], v[166:169], v[190:193], v[90:93]
	v_mfma_f32_16x16x32_bf16 v[86:89], v[158:161], v[222:225], v[86:89]
	v_mfma_f32_16x16x32_bf16 v[78:81], v[166:169], v[222:225], v[78:81]
	s_barrier
	s_add_i32 s70, 0, 0x14000
	s_add_i32 s68, s68, s34
	v_add_u32_e32 v157, s70, v153
	v_lshl_add_u64 v[198:199], s[50:51], 0, v[0:1]
	s_mov_b32 m0, s68
	ds_read_b128 v[226:229], v157
	ds_read_b128 v[230:233], v157 offset:1024
	ds_read_b128 v[234:237], v157 offset:2048
	ds_read_b128 v[238:241], v157 offset:3072
	global_load_lds_dwordx4 v[198:199], off
	v_lshl_add_u64 v[242:243], s[50:51], 0, v[130:131]
	s_add_i32 m0, s68, 0x2000
	s_nop 0
	global_load_lds_dwordx4 v[242:243], off
	s_barrier
	s_waitcnt lgkmcnt(0)
	v_mfma_f32_16x16x32_bf16 v[114:117], v[226:229], v[170:173], v[114:117]
	v_mfma_f32_16x16x32_bf16 v[106:109], v[234:237], v[170:173], v[106:109]
	v_mfma_f32_16x16x32_bf16 v[102:105], v[226:229], v[178:181], v[102:105]
	v_mfma_f32_16x16x32_bf16 v[98:101], v[234:237], v[178:181], v[98:101]
	v_mfma_f32_16x16x32_bf16 v[82:85], v[226:229], v[186:189], v[82:85]
	v_mfma_f32_16x16x32_bf16 v[74:77], v[234:237], v[186:189], v[74:77]
	v_mfma_f32_16x16x32_bf16 v[70:73], v[226:229], v[194:197], v[70:73]
	v_mfma_f32_16x16x32_bf16 v[66:69], v[234:237], v[194:197], v[66:69]
	v_mfma_f32_16x16x32_bf16 v[114:117], v[230:233], v[174:177], v[114:117]
	v_mfma_f32_16x16x32_bf16 v[106:109], v[238:241], v[174:177], v[106:109]
	v_mfma_f32_16x16x32_bf16 v[102:105], v[230:233], v[182:185], v[102:105]
	v_mfma_f32_16x16x32_bf16 v[98:101], v[238:241], v[182:185], v[98:101]
	v_mfma_f32_16x16x32_bf16 v[82:85], v[230:233], v[190:193], v[82:85]
	v_mfma_f32_16x16x32_bf16 v[74:77], v[238:241], v[190:193], v[74:77]
	v_mfma_f32_16x16x32_bf16 v[70:73], v[230:233], v[222:225], v[70:73]
	v_mfma_f32_16x16x32_bf16 v[66:69], v[238:241], v[222:225], v[66:69]
	s_mov_b32 m0, s37
	v_lshl_add_u64 v[244:245], s[52:53], 0, v[142:143]
	s_barrier
	ds_read_b128 v[170:173], v156 offset:16384
	ds_read_b128 v[174:177], v156 offset:17408
	ds_read_b128 v[178:181], v156 offset:18432
	ds_read_b128 v[182:185], v156 offset:19456
	ds_read_b128 v[186:189], v156 offset:20480
	ds_read_b128 v[190:193], v156 offset:21504
	ds_read_b128 v[194:197], v156 offset:22528
	ds_read_b128 v[222:225], v156 offset:23552
	global_load_lds_dwordx4 v[244:245], off
	v_lshl_add_u64 v[246:247], s[52:53], 0, v[132:133]
	s_mov_b32 m0, s54
	s_nop 0
	global_load_lds_dwordx4 v[246:247], off
	s_barrier
	s_waitcnt lgkmcnt(0)
	v_mfma_f32_16x16x32_bf16 v[62:65], v[148:151], v[170:173], v[62:65]
	v_mfma_f32_16x16x32_bf16 v[58:61], v[162:165], v[170:173], v[58:61]
	v_mfma_f32_16x16x32_bf16 v[54:57], v[148:151], v[178:181], v[54:57]
	v_mfma_f32_16x16x32_bf16 v[46:49], v[162:165], v[178:181], v[46:49]
	v_mfma_f32_16x16x32_bf16 v[30:33], v[148:151], v[186:189], v[30:33]
	v_mfma_f32_16x16x32_bf16 v[26:29], v[162:165], v[186:189], v[26:29]
	v_mfma_f32_16x16x32_bf16 v[22:25], v[148:151], v[194:197], v[22:25]
	v_mfma_f32_16x16x32_bf16 v[14:17], v[162:165], v[194:197], v[14:17]
	v_mfma_f32_16x16x32_bf16 v[62:65], v[158:161], v[174:177], v[62:65]
	v_mfma_f32_16x16x32_bf16 v[58:61], v[166:169], v[174:177], v[58:61]
	v_mfma_f32_16x16x32_bf16 v[54:57], v[158:161], v[182:185], v[54:57]
	v_mfma_f32_16x16x32_bf16 v[46:49], v[166:169], v[182:185], v[46:49]
	v_mfma_f32_16x16x32_bf16 v[30:33], v[158:161], v[190:193], v[30:33]
	v_mfma_f32_16x16x32_bf16 v[26:29], v[166:169], v[190:193], v[26:29]
	v_mfma_f32_16x16x32_bf16 v[22:25], v[158:161], v[222:225], v[22:25]
	v_mfma_f32_16x16x32_bf16 v[14:17], v[166:169], v[222:225], v[14:17]
	s_barrier
; #define PG8_STAGE(bufoff, gbase, voff) do { _Pragma("unroll") for (int _i = 0; _i < 2; ++_i) \
;     __builtin_amdgcn_global_load_lds((const unsigned*)((const char*)(gbase) + (voff)[_i]), (PG8_LAS unsigned*)(lds + (bufoff) + ldsw + _i * 8192), 16, 0, 0); } while (0)
; #define PG8_LDA(dst, b, h) do { _Pragma("unroll") for (int m = 0; m < 4; ++m) _Pragma("unroll") for (int k = 0; k < 2; ++k) dst[m][k] = *(const PG8_LAS bf16x8*)(lds + PG8_SA(b, h) + aoff + m * 2048 + k * 1024); } while (0)
; #define PG8_LDB(dst, b, h) do { _Pragma("unroll") for (int n = 0; n < 2; ++n) _Pragma("unroll") for (int k = 0; k < 2; ++k) dst[n][k] = *(const PG8_LAS bf16x8*)(lds + PG8_SB(b, h) + boff + n * 2048 + k * 1024); } while (0)
; #define PG8_MMA(ai, bj, At, Bt) do { __builtin_amdgcn_s_setprio(1); _Pragma("unroll") for (int m = 0; m < 4; ++m) _Pragma("unroll") for (int n = 0; n < 2; ++n) _Pragma("unroll") for (int k = 0; k < 2; ++k) \
;     acc[ai][bj][m][n] = __builtin_amdgcn_mfma_f32_16x16x32_bf16(Bt[n][k], At[m][k], acc[ai][bj][m][n], 0, 0, 0); __builtin_amdgcn_s_setprio(0); } while (0)
; #define PG8_WAIT_V(n) asm volatile("s_waitcnt vmcnt(" #n ")" ::: "memory")
; #define PG8_WAIT_L(n) asm volatile("s_waitcnt lgkmcnt(" #n ")" ::: "memory")
; #define PG8_BAR __builtin_amdgcn_s_barrier()
; #define PG8_SCHED __builtin_amdgcn_sched_barrier(0)
; template <class Epi>
; DI void gemm_phase(PG8_LAS unsigned char* lds, const Gemm g, const StaticOrder& S, const Epi& E) {
;     ...
;       PG8_STAGE(PG8_SB(0, 1), b2 + hstepB, voffB);
;       PG8_WAIT_V(6); PG8_BAR; PG8_MMA(1, 1, At, B1); PG8_BAR;
;       PG8_LDB(B0, 1, 0); PG8_SCHED; PG8_LDA(At, 1, 0); PG8_STAGE(PG8_SA(0, 1), a2 + hstepA, voffA);
;       PG8_WAIT_L(8); PG8_BAR; PG8_WAIT_L(0); PG8_MMA(0, 0, At, B0); PG8_BAR; PG8_SCHED;
;       PG8_LDB(B1, 1, 1); PG8_STAGE(PG8_SB(1, 0), b3, voffB);
;       PG8_BAR; PG8_WAIT_L(0); PG8_MMA(0, 1, At, B1); PG8_BAR;
	s_add_u32 s68, s50, 0x40000
	s_addc_u32 s69, s51, 0
	s_add_i32 s70, s70, s34
	v_lshl_add_u64 v[148:149], s[68:69], 0, v[0:1]
	s_mov_b32 m0, s70
	s_nop 0
	global_load_lds_dwordx4 v[148:149], off
	v_lshl_add_u64 v[148:149], s[68:69], 0, v[130:131]
	s_add_i32 m0, s70, 0x2000
	s_nop 0
	global_load_lds_dwordx4 v[148:149], off
	s_waitcnt vmcnt(6)
	s_barrier
	v_mfma_f32_16x16x32_bf16 v[50:53], v[226:229], v[170:173], v[50:53]
	v_mfma_f32_16x16x32_bf16 v[42:45], v[234:237], v[170:173], v[42:45]
	v_mfma_f32_16x16x32_bf16 v[38:41], v[226:229], v[178:181], v[38:41]
	v_mfma_f32_16x16x32_bf16 v[34:37], v[234:237], v[178:181], v[34:37]
	v_mfma_f32_16x16x32_bf16 v[18:21], v[226:229], v[186:189], v[18:21]
	v_mfma_f32_16x16x32_bf16 v[10:13], v[234:237], v[186:189], v[10:13]
	v_mfma_f32_16x16x32_bf16 v[6:9], v[226:229], v[194:197], v[6:9]
	v_mfma_f32_16x16x32_bf16 v[2:5], v[234:237], v[194:197], v[2:5]
	v_mfma_f32_16x16x32_bf16 v[50:53], v[230:233], v[174:177], v[50:53]
	v_mfma_f32_16x16x32_bf16 v[42:45], v[238:241], v[174:177], v[42:45]
	v_mfma_f32_16x16x32_bf16 v[38:41], v[230:233], v[182:185], v[38:41]
	v_mfma_f32_16x16x32_bf16 v[34:37], v[238:241], v[182:185], v[34:37]
	v_mfma_f32_16x16x32_bf16 v[18:21], v[230:233], v[190:193], v[18:21]
	v_mfma_f32_16x16x32_bf16 v[10:13], v[238:241], v[190:193], v[10:13]
	v_mfma_f32_16x16x32_bf16 v[6:9], v[230:233], v[222:225], v[6:9]
	v_mfma_f32_16x16x32_bf16 v[2:5], v[238:241], v[222:225], v[2:5]
	s_add_i32 s68, 0, 0x18000
	v_add_u32_e32 v157, s68, v153
	s_barrier
	ds_read_b128 v[148:151], v157
	ds_read_b128 v[158:161], v157 offset:1024
	ds_read_b128 v[162:165], v157 offset:2048
	ds_read_b128 v[166:169], v157 offset:3072
	s_add_u32 s52, s52, 0x40000
	s_addc_u32 s53, s53, 0
	s_mov_b32 m0, s55
	v_lshl_add_u64 v[226:227], s[52:53], 0, v[142:143]
	ds_read_b128 v[170:173], v156 offset:32768
	ds_read_b128 v[174:177], v156 offset:33792
	ds_read_b128 v[178:181], v156 offset:34816
	ds_read_b128 v[182:185], v156 offset:35840
	ds_read_b128 v[186:189], v156 offset:36864
	ds_read_b128 v[190:193], v156 offset:37888
	ds_read_b128 v[194:197], v156 offset:38912
	ds_read_b128 v[222:225], v156 offset:39936
	global_load_lds_dwordx4 v[226:227], off
	v_lshl_add_u64 v[226:227], s[52:53], 0, v[132:133]
	s_mov_b32 m0, s56
	s_nop 0
	global_load_lds_dwordx4 v[226:227], off
	s_waitcnt lgkmcnt(8)
	s_barrier
	s_waitcnt lgkmcnt(0)
	v_mfma_f32_16x16x32_bf16 v[126:129], v[148:151], v[170:173], v[126:129]
	v_mfma_f32_16x16x32_bf16 v[122:125], v[162:165], v[170:173], v[122:125]
	v_mfma_f32_16x16x32_bf16 v[118:121], v[148:151], v[178:181], v[118:121]
	v_mfma_f32_16x16x32_bf16 v[110:113], v[162:165], v[178:181], v[110:113]
	v_mfma_f32_16x16x32_bf16 v[94:97], v[148:151], v[186:189], v[94:97]
	v_mfma_f32_16x16x32_bf16 v[90:93], v[162:165], v[186:189], v[90:93]
	v_mfma_f32_16x16x32_bf16 v[86:89], v[148:151], v[194:197], v[86:89]
	v_mfma_f32_16x16x32_bf16 v[78:81], v[162:165], v[194:197], v[78:81]
	v_mfma_f32_16x16x32_bf16 v[126:129], v[158:161], v[174:177], v[126:129]
	v_mfma_f32_16x16x32_bf16 v[122:125], v[166:169], v[174:177], v[122:125]
	v_mfma_f32_16x16x32_bf16 v[118:121], v[158:161], v[182:185], v[118:121]
	v_mfma_f32_16x16x32_bf16 v[110:113], v[166:169], v[182:185], v[110:113]
	v_mfma_f32_16x16x32_bf16 v[94:97], v[158:161], v[190:193], v[94:97]
	v_mfma_f32_16x16x32_bf16 v[90:93], v[166:169], v[190:193], v[90:93]
	v_mfma_f32_16x16x32_bf16 v[86:89], v[158:161], v[222:225], v[86:89]
	v_mfma_f32_16x16x32_bf16 v[78:81], v[166:169], v[222:225], v[78:81]
	s_barrier
	s_add_i32 s52, 0, 0x1c000
	s_add_i32 s53, s68, s34
	v_add_u32_e32 v157, s52, v153
	v_lshl_add_u64 v[198:199], v[198:199], 0, s[86:87]
	s_mov_b32 m0, s53
	ds_read_b128 v[226:229], v157
	ds_read_b128 v[230:233], v157 offset:1024
	ds_read_b128 v[234:237], v157 offset:2048
	ds_read_b128 v[238:241], v157 offset:3072
	global_load_lds_dwordx4 v[198:199], off
	v_lshl_add_u64 v[198:199], v[242:243], 0, s[86:87]
	s_add_i32 m0, s53, 0x2000
	s_nop 0
	global_load_lds_dwordx4 v[198:199], off
	s_barrier
; #define PG8_STAGE(bufoff, gbase, voff) do { _Pragma("unroll") for (int _i = 0; _i < 2; ++_i) \
;     __builtin_amdgcn_global_load_lds((const unsigned*)((const char*)(gbase) + (voff)[_i]), (PG8_LAS unsigned*)(lds + (bufoff) + ldsw + _i * 8192), 16, 0, 0); } while (0)
; #define PG8_LDA(dst, b, h) do { _Pragma("unroll") for (int m = 0; m < 4; ++m) _Pragma("unroll") for (int k = 0; k < 2; ++k) dst[m][k] = *(const PG8_LAS bf16x8*)(lds + PG8_SA(b, h) + aoff + m * 2048 + k * 1024); } while (0)
; #define PG8_MMA(ai, bj, At, Bt) do { __builtin_amdgcn_s_setprio(1); _Pragma("unroll") for (int m = 0; m < 4; ++m) _Pragma("unroll") for (int n = 0; n < 2; ++n) _Pragma("unroll") for (int k = 0; k < 2; ++k) \
;     acc[ai][bj][m][n] = __builtin_amdgcn_mfma_f32_16x16x32_bf16(Bt[n][k], At[m][k], acc[ai][bj][m][n], 0, 0, 0); __builtin_amdgcn_s_setprio(0); } while (0)
; #define PG8_WAIT_V(n) asm volatile("s_waitcnt vmcnt(" #n ")" ::: "memory")
; #define PG8_WAIT_L(n) asm volatile("s_waitcnt lgkmcnt(" #n ")" ::: "memory")
; #define PG8_BAR __builtin_amdgcn_s_barrier()
; #define PG8_SCHED __builtin_amdgcn_sched_barrier(0)
; template <class Epi>
; DI void gemm_phase(PG8_LAS unsigned char* lds, const Gemm g, const StaticOrder& S, const Epi& E) {
;     ...
;       PG8_BAR; PG8_WAIT_L(0); PG8_MMA(0, 1, At, B1); PG8_BAR;
;       PG8_LDA(At, 1, 1); PG8_STAGE(PG8_SA(1, 0), a3, voffA);
;       PG8_BAR; PG8_WAIT_L(0); PG8_MMA(1, 0, At, B0); PG8_BAR; PG8_SCHED;
;       PG8_STAGE(PG8_SB(1, 1), b3 + hstepB, voffB);
;       PG8_WAIT_V(6); PG8_BAR; PG8_MMA(1, 1, At, B1); PG8_BAR;
	s_waitcnt lgkmcnt(0)
	v_mfma_f32_16x16x32_bf16 v[114:117], v[226:229], v[170:173], v[114:117]
	v_mfma_f32_16x16x32_bf16 v[106:109], v[234:237], v[170:173], v[106:109]
	v_mfma_f32_16x16x32_bf16 v[102:105], v[226:229], v[178:181], v[102:105]
	v_mfma_f32_16x16x32_bf16 v[98:101], v[234:237], v[178:181], v[98:101]
	v_mfma_f32_16x16x32_bf16 v[82:85], v[226:229], v[186:189], v[82:85]
	v_mfma_f32_16x16x32_bf16 v[74:77], v[234:237], v[186:189], v[74:77]
	v_mfma_f32_16x16x32_bf16 v[70:73], v[226:229], v[194:197], v[70:73]
	v_mfma_f32_16x16x32_bf16 v[66:69], v[234:237], v[194:197], v[66:69]
	v_mfma_f32_16x16x32_bf16 v[114:117], v[230:233], v[174:177], v[114:117]
	v_mfma_f32_16x16x32_bf16 v[106:109], v[238:241], v[174:177], v[106:109]
	v_mfma_f32_16x16x32_bf16 v[102:105], v[230:233], v[182:185], v[102:105]
	v_mfma_f32_16x16x32_bf16 v[98:101], v[238:241], v[182:185], v[98:101]
	v_mfma_f32_16x16x32_bf16 v[82:85], v[230:233], v[190:193], v[82:85]
	v_mfma_f32_16x16x32_bf16 v[74:77], v[238:241], v[190:193], v[74:77]
	v_mfma_f32_16x16x32_bf16 v[70:73], v[230:233], v[222:225], v[70:73]
	v_mfma_f32_16x16x32_bf16 v[66:69], v[238:241], v[222:225], v[66:69]
	s_mov_b32 m0, s57
	v_lshl_add_u64 v[198:199], v[244:245], 0, s[86:87]
	s_barrier
	ds_read_b128 v[170:173], v156 offset:49152
	ds_read_b128 v[174:177], v156 offset:50176
	ds_read_b128 v[178:181], v156 offset:51200
	ds_read_b128 v[182:185], v156 offset:52224
	ds_read_b128 v[186:189], v156 offset:53248
	ds_read_b128 v[190:193], v156 offset:54272
	ds_read_b128 v[194:197], v156 offset:55296
	ds_read_b128 v[222:225], v156 offset:56320
	global_load_lds_dwordx4 v[198:199], off
	v_lshl_add_u64 v[198:199], v[246:247], 0, s[86:87]
	s_mov_b32 m0, s58
	s_nop 0
	global_load_lds_dwordx4 v[198:199], off
	s_barrier
	s_waitcnt lgkmcnt(0)
	v_mfma_f32_16x16x32_bf16 v[62:65], v[148:151], v[170:173], v[62:65]
	v_mfma_f32_16x16x32_bf16 v[58:61], v[162:165], v[170:173], v[58:61]
	v_mfma_f32_16x16x32_bf16 v[54:57], v[148:151], v[178:181], v[54:57]
	v_mfma_f32_16x16x32_bf16 v[46:49], v[162:165], v[178:181], v[46:49]
	v_mfma_f32_16x16x32_bf16 v[30:33], v[148:151], v[186:189], v[30:33]
	v_mfma_f32_16x16x32_bf16 v[26:29], v[162:165], v[186:189], v[26:29]
	v_mfma_f32_16x16x32_bf16 v[22:25], v[148:151], v[194:197], v[22:25]
	v_mfma_f32_16x16x32_bf16 v[14:17], v[162:165], v[194:197], v[14:17]
	v_mfma_f32_16x16x32_bf16 v[62:65], v[158:161], v[174:177], v[62:65]
	v_mfma_f32_16x16x32_bf16 v[58:61], v[166:169], v[174:177], v[58:61]
	v_mfma_f32_16x16x32_bf16 v[54:57], v[158:161], v[182:185], v[54:57]
	v_mfma_f32_16x16x32_bf16 v[46:49], v[166:169], v[182:185], v[46:49]
	v_mfma_f32_16x16x32_bf16 v[30:33], v[158:161], v[190:193], v[30:33]
	v_mfma_f32_16x16x32_bf16 v[26:29], v[166:169], v[190:193], v[26:29]
	v_mfma_f32_16x16x32_bf16 v[22:25], v[158:161], v[222:225], v[22:25]
	v_mfma_f32_16x16x32_bf16 v[14:17], v[166:169], v[222:225], v[14:17]
	s_barrier
	s_add_u32 s50, s50, 0x40080
	s_addc_u32 s51, s51, 0
	s_add_i32 s52, s52, s34
	v_lshl_add_u64 v[148:149], s[50:51], 0, v[0:1]
	s_mov_b32 m0, s52
	s_nop 0
	global_load_lds_dwordx4 v[148:149], off
	v_lshl_add_u64 v[148:149], s[50:51], 0, v[130:131]
	s_add_i32 m0, s52, 0x2000
	s_nop 0
	global_load_lds_dwordx4 v[148:149], off
	s_waitcnt vmcnt(6)
	s_barrier
	v_mfma_f32_16x16x32_bf16 v[50:53], v[226:229], v[170:173], v[50:53]
	v_mfma_f32_16x16x32_bf16 v[42:45], v[234:237], v[170:173], v[42:45]
	v_mfma_f32_16x16x32_bf16 v[38:41], v[226:229], v[178:181], v[38:41]
	v_mfma_f32_16x16x32_bf16 v[34:37], v[234:237], v[178:181], v[34:37]
	v_mfma_f32_16x16x32_bf16 v[18:21], v[226:229], v[186:189], v[18:21]
	v_mfma_f32_16x16x32_bf16 v[10:13], v[234:237], v[186:189], v[10:13]
	v_mfma_f32_16x16x32_bf16 v[6:9], v[226:229], v[194:197], v[6:9]
	v_mfma_f32_16x16x32_bf16 v[2:5], v[234:237], v[194:197], v[2:5]
	v_mfma_f32_16x16x32_bf16 v[50:53], v[230:233], v[174:177], v[50:53]
	v_mfma_f32_16x16x32_bf16 v[42:45], v[238:241], v[174:177], v[42:45]
	v_mfma_f32_16x16x32_bf16 v[38:41], v[230:233], v[182:185], v[38:41]
	v_mfma_f32_16x16x32_bf16 v[34:37], v[238:241], v[182:185], v[34:37]
	v_mfma_f32_16x16x32_bf16 v[18:21], v[230:233], v[190:193], v[18:21]
	v_mfma_f32_16x16x32_bf16 v[10:13], v[238:241], v[190:193], v[10:13]
	v_mfma_f32_16x16x32_bf16 v[6:9], v[230:233], v[222:225], v[6:9]
	v_mfma_f32_16x16x32_bf16 v[2:5], v[238:241], v[222:225], v[2:5]
	s_add_i32 s67, s67, 2
	s_add_u32 s48, s48, 0x100
	s_addc_u32 s49, s49, 0
	s_add_u32 s65, s65, 0x100
	s_addc_u32 s66, s66, 0
	s_cmp_gt_u32 s67, 13
	s_barrier
	s_cbranch_scc0 .LBB0_1197
